# up/gemm_in k-steps: last two sub-steps (8 MFMAs) after the stage barrier, alternating with the 8 LDS-DMA pieces; sub-step fragments in their own registers
# speedup vs baseline: 1.0040x; 1.0040x over previous
; #define WAIT_V0() asm volatile("s_waitcnt vmcnt(0)" ::: "memory")
; DI int glds_row(int i) { const int tid = ltid(); return ((tid >> 6) * 4 + i) * 8 + ((tid & 63) >> 3); }
; DI int glds_chunk(int row) { return (ltid() & 7) ^ ((row >> 1) & 7); }
; DI void gemm_core(char* smem, int nk, const char* Ab, const char* Bb, const unsigned (&aoff)[4], const unsigned (&boff)[4],
;                   f32x16 (&acc)[2][2]) {
;     ...
;   auto stage = [&](int buf, int kt) __attribute__((always_inline)) {
;     const char* ak = Ab + kt * 128;
;     const char* bk = Bb + kt * 128;
;     char* sa = smem + buf * STAGE_B + w * 4096;
; #pragma unroll
;     for (int i = 0; i < 4; ++i) {
;       __builtin_amdgcn_global_load_lds((const unsigned*)(ak + aoff[i]), (unsigned*)(sa + i * 1024), 16, 0, 0);
;       __builtin_amdgcn_global_load_lds((const unsigned*)(bk + boff[i]), (unsigned*)(sa + 16384 + i * 1024), 16, 0, 0);
;     }
;   };
;   stage(0, 0);
;   WAIT_V0();
;   __syncthreads();
; DI void phase_up(const Params& P, int layer, char* smem) {
;     ...
;   for (int t0 = blockIdx.x; t0 < MT * NT; t0 += gridDim.x) {
;     const int tl = xcd_tile(t0, MT * NT) - (t0 & 7) * ((MT * NT) >> 3);
;     const int mt = (t0 & 1) * 131 + tl / 11, nt = ((t0 & 7) >> 1) * 11 + tl % 11;
;     const int b = mt / 131, i = mt % 131;
;     const int tb0 = i * 126 - 2;
;     unsigned aoff[4], boff[4];
;     const char* Abase = (const char*)(hn + (size_t)b * S_ * 1024);
;     const unsigned zoff = (unsigned)((P.ws + OFF_ZPAGE) - Abase);
; #pragma unroll
;     for (int q = 0; q < 4; ++q) {
;       const int r = glds_row(q), ch = glds_chunk(r);
;       const int tb = tb0 + r;
;       const bool ok = (tb >= 0) && (tb < S_);
;       aoff[q] = ok ? (unsigned)((tb * 1024 + ch * 8) * 2) : zoff;
;       const int wr = (r < 64) ? (nt * 64 + r) : (DFF + nt * 64 + r - 64);
;       boff[q] = (unsigned)((wr * 1024 + ch * 8) * 2);
;     }
.LBB0_25:
	s_ashr_i32 s18, s2, 3
	s_and_b32 s19, s18, 0xffffffc0
	s_lshl_b32 s20, s18, 1
	s_bfe_u32 s21, s18, 0x10005
	s_and_b32 s20, s20, 62
	s_or_b32 s19, s21, s19
	s_or_b32 s19, s19, s20
	s_or_b32 s20, s18, 63
	s_cmpk_lt_i32 s20, 0x5a1
	s_cselect_b32 s18, s19, s18
	s_bitcmp1_b32 s2, 0
	s_mul_hi_i32 s20, s18, 0x2e8ba2e9
	s_cselect_b32 s19, 0x83, 0
	s_lshr_b32 s21, s20, 31
	s_ashr_i32 s20, s20, 1
	s_add_i32 s21, s20, s21
	s_add_i32 s20, s21, s19
	s_bfe_u32 s19, s2, 0x20001
	s_mul_i32 s21, s21, 11
	s_mul_i32 s19, s19, 11
	s_sub_i32 s18, s18, s21
	s_add_i32 s21, s18, s19
	s_mul_hi_i32 s18, s20, 0x3e88cb3d
	s_lshr_b32 s19, s18, 31
	s_ashr_i32 s18, s18, 5
	v_mov_b32_e32 v0, v161
	s_add_i32 s68, s18, s19
	s_mul_i32 s18, s68, 0x83
	v_ashrrev_i32_e32 v1, 1, v0
	v_lshrrev_b32_e32 v2, 3, v0
	v_bfe_u32 v0, v0, 3, 3
	s_movk_i32 s3, 0xffe0
	s_sub_i32 s28, s20, s18
	v_and_or_b32 v0, v1, s3, v0
	v_mov_b32_e32 v1, v161
	s_mulk_i32 s28, 0x7e
	s_ashr_i32 s69, s68, 31
	v_bfe_u32 v2, v2, 1, 2
	s_add_i32 s29, s28, -2
	s_lshl_b64 s[22:23], s[68:69], 25
	v_xor_b32_e32 v1, v2, v1
	s_add_u32 s18, s84, s22
	v_lshlrev_b32_e32 v1, 4, v1
	s_addc_u32 s19, s85, s23
	s_sub_i32 s22, 0x1b508000, s22
	s_lshl_b32 s21, s21, 6
	v_add_u32_e32 v2, s29, v0
	v_and_b32_e32 v1, 0x70, v1
	s_movk_i32 s3, 0x4000
	s_add_i32 s23, s21, 0xac0
	v_lshl_or_b32 v3, v2, 11, v1
	v_mov_b32_e32 v4, s22
	v_cmp_gt_u32_e32 vcc, s3, v2
	v_mov_b32_e32 v5, s21
	v_mov_b32_e32 v12, v161
	v_cndmask_b32_e32 v136, v4, v3, vcc
	v_mov_b32_e32 v3, s23
	v_cmp_gt_i32_e32 vcc, 64, v0
	v_lshl_add_u64 v[64:65], s[18:19], 0, v[136:137]
	s_mov_b64 s[4:5], 0x100
	v_cndmask_b32_e32 v2, v3, v5, vcc
	v_add_u32_e32 v0, v2, v0
	v_lshl_or_b32 v76, v0, 11, v1
	v_mov_b32_e32 v0, v161
	s_mov_b64 s[6:7], 0x780
	v_ashrrev_i32_e32 v1, 1, v0
	v_and_b32_e32 v1, 0xffffffe0, v1
	v_bfe_u32 v0, v0, 3, 3
	v_or3_b32 v1, v1, v0, 8
	v_mov_b32_e32 v0, v161
	v_lshrrev_b32_e32 v2, 1, v1
	v_xor_b32_e32 v0, v2, v0
	v_lshlrev_b32_e32 v0, 4, v0
	v_add_u32_e32 v2, s29, v1
	v_and_b32_e32 v6, 0x70, v0
	v_lshl_or_b32 v0, v2, 11, v6
	v_cmp_gt_u32_e32 vcc, s3, v2
	s_nop 1
	v_cndmask_b32_e32 v0, v4, v0, vcc
	v_cmp_gt_i32_e32 vcc, 64, v1
	s_nop 1
	v_cndmask_b32_e32 v2, v3, v5, vcc
	v_add_u32_e32 v1, v2, v1
	v_lshl_or_b32 v77, v1, 11, v6
	v_mov_b32_e32 v1, v161
	s_nop 0
	v_ashrrev_i32_e32 v2, 1, v1
	v_and_b32_e32 v2, 0xffffffe0, v2
	v_lshrrev_b32_e32 v6, 3, v1
	v_bfe_u32 v1, v1, 3, 3
	v_or3_b32 v1, v2, v1, 16
	v_mov_b32_e32 v2, v161
	v_bfe_u32 v6, v6, 1, 2
	v_xor_b32_e32 v2, v6, v2
	v_lshlrev_b32_e32 v2, 4, v2
	v_add_u32_e32 v6, s29, v1
	v_and_b32_e32 v7, 0x70, v2
	v_lshl_or_b32 v2, v6, 11, v7
	v_cmp_gt_u32_e32 vcc, s3, v6
	s_nop 1
	v_cndmask_b32_e32 v2, v4, v2, vcc
	v_cmp_gt_i32_e32 vcc, 64, v1
	s_nop 1
	v_cndmask_b32_e32 v6, v3, v5, vcc
	v_add_u32_e32 v1, v6, v1
	v_lshl_or_b32 v78, v1, 11, v7
	v_mov_b32_e32 v1, v161
	s_nop 0
	v_ashrrev_i32_e32 v6, 1, v1
	v_and_b32_e32 v6, 0xffffffe0, v6
	v_bfe_u32 v1, v1, 3, 3
	v_or3_b32 v1, v6, v1, 24
	v_mov_b32_e32 v6, v161
	v_lshrrev_b32_e32 v7, 1, v1
	v_xor_b32_e32 v6, v7, v6
	v_lshlrev_b32_e32 v6, 4, v6
	v_add_u32_e32 v7, s29, v1
	v_and_b32_e32 v6, 0x70, v6
	v_lshl_or_b32 v8, v7, 11, v6
	v_cmp_gt_u32_e32 vcc, s3, v7
	s_mov_b32 s3, 0x1ffffc0
	v_bfe_u32 v86, v12, 1, 3
	v_cndmask_b32_e32 v4, v4, v8, vcc
	v_cmp_gt_i32_e32 vcc, 64, v1
	v_bfe_u32 v117, v12, 5, 1
	s_nop 0
	v_cndmask_b32_e32 v3, v3, v5, vcc
	v_add_u32_e32 v1, v3, v1
	v_lshl_or_b32 v84, v1, 11, v6
	v_and_b32_e32 v1, 31, v12
	v_lshrrev_b32_e32 v5, 1, v12
	v_and_or_b32 v1, v5, s3, v1
	v_lshlrev_b32_e32 v87, 7, v1
	v_lshlrev_b32_e32 v1, 6, v12
	v_and_b32_e32 v97, 0xfffff000, v1
	v_add_u32_e32 v96, 0x4000, v97
	v_readfirstlane_b32 s84, v97
	s_mov_b32 m0, s84
	v_readfirstlane_b32 s85, v96
	v_or_b32_e32 v98, 0x400, v97
	global_load_lds_dwordx4 v136, s[18:19]
	s_mov_b32 m0, s85
	v_readfirstlane_b32 s86, v98
	v_add_u32_e32 v99, 0x4400, v97
	global_load_lds_dwordx4 v76, s[0:1]
	s_mov_b32 m0, s86
	v_readfirstlane_b32 s87, v99
	v_or_b32_e32 v100, 0x800, v97
	global_load_lds_dwordx4 v0, s[18:19]
	s_mov_b32 m0, s87
	v_readfirstlane_b32 s88, v100
	v_add_u32_e32 v101, 0x4800, v97
	v_lshrrev_b32_e32 v3, 5, v12
	global_load_lds_dwordx4 v77, s[0:1]
	s_mov_b32 m0, s88
	v_readfirstlane_b32 s89, v101
	v_or_b32_e32 v102, 0xc00, v97
	v_bitop3_b32 v3, v3, v86, 1 bitop3:0x6c
	global_load_lds_dwordx4 v2, s[18:19]
	s_mov_b32 m0, s89
	v_readfirstlane_b32 s90, v102
	v_add_u32_e32 v103, 0x4c00, v97
	v_lshlrev_b32_e32 v6, 4, v3
	v_mov_b32_e32 v1, v137
	v_mov_b32_e32 v3, v137
	global_load_lds_dwordx4 v78, s[0:1]
	v_mov_b32_e32 v5, v137
	s_mov_b32 m0, s90
	v_readfirstlane_b32 s91, v103
	v_add_u32_e32 v89, 0x8000, v97
	v_lshl_add_u64 v[66:67], s[18:19], 0, v[0:1]
	v_lshl_add_u64 v[68:69], s[18:19], 0, v[2:3]
	v_lshl_add_u64 v[70:71], s[18:19], 0, v[4:5]
	global_load_lds_dwordx4 v4, s[18:19]
	s_mov_b32 m0, s91
	v_add_u32_e32 v88, 0xc000, v97
	v_readfirstlane_b32 s18, v89
	global_load_lds_dwordx4 v84, s[0:1]
	v_lshl_add_u64 v[0:1], v[64:65], 0, s[94:95]
	s_mov_b32 m0, s18
	v_readfirstlane_b32 s19, v88
	v_add_u32_e32 v90, 0x8400, v97
	global_load_lds_dwordx4 v[0:1], off
	s_mov_b32 m0, s19
	v_readfirstlane_b32 s22, v90
	v_add_u32_e32 v91, 0xc400, v97
	global_load_lds_dwordx4 v76, s[14:15]
	v_lshl_add_u64 v[0:1], v[66:67], 0, s[94:95]
	s_mov_b32 m0, s22
	v_readfirstlane_b32 s23, v91
	v_add_u32_e32 v92, 0x8800, v97
	global_load_lds_dwordx4 v[0:1], off
	s_mov_b32 m0, s23
	v_readfirstlane_b32 s29, v92
	v_add_u32_e32 v93, 0xc800, v97
	global_load_lds_dwordx4 v77, s[14:15]
	v_lshl_add_u64 v[0:1], v[68:69], 0, s[94:95]
	s_mov_b32 m0, s29
	v_readfirstlane_b32 s69, v93
	v_add_u32_e32 v94, 0x8c00, v97
	global_load_lds_dwordx4 v[0:1], off
	s_mov_b32 m0, s69
	v_readfirstlane_b32 s70, v94
	v_add_u32_e32 v95, 0xcc00, v97
	global_load_lds_dwordx4 v78, s[14:15]
	v_lshl_add_u64 v[0:1], v[70:71], 0, s[94:95]
	s_mov_b32 m0, s70
	v_readfirstlane_b32 s71, v95
	global_load_lds_dwordx4 v[0:1], off
	s_mov_b32 m0, s71
	v_or_b32_e32 v79, v87, v6
	global_load_lds_dwordx4 v84, s[14:15]
	s_waitcnt vmcnt(8)
	s_waitcnt vmcnt(8) lgkmcnt(0)
	s_barrier
; #define WAIT_V0() asm volatile("s_waitcnt vmcnt(0)" ::: "memory")
; DI void gemm_core(char* smem, int nk, const char* Ab, const char* Bb, const unsigned (&aoff)[4], const unsigned (&boff)[4],
;                   f32x16 (&acc)[2][2]) {
;     ...
;   auto stage = [&](int buf, int kt) __attribute__((always_inline)) {
;     const char* ak = Ab + kt * 128;
;     const char* bk = Bb + kt * 128;
;     char* sa = smem + buf * STAGE_B + w * 4096;
; #pragma unroll
;     for (int i = 0; i < 4; ++i) {
;       __builtin_amdgcn_global_load_lds((const unsigned*)(ak + aoff[i]), (unsigned*)(sa + i * 1024), 16, 0, 0);
;       __builtin_amdgcn_global_load_lds((const unsigned*)(bk + boff[i]), (unsigned*)(sa + 16384 + i * 1024), 16, 0, 0);
;     }
;   };
;   stage(0, 0);
;   WAIT_V0();
;   __syncthreads();
;   for (int kt = 0; kt < nk; ++kt) {
;     const int cur = kt & 1;
;     if (kt + 1 < nk) stage(cur ^ 1, kt + 1);
;     const char* sb = smem + cur * STAGE_B;
; #pragma unroll
;     for (int ks = 0; ks < 4; ++ks) {
;       bf16x8 af[2], bfr[2];
; #pragma unroll
;       for (int mb = 0; mb < 2; ++mb) af[mb] = *(const bf16x8*)(sb + a_base + mb * 4096 + xo[ks]);
; #pragma unroll
;       for (int nb = 0; nb < 2; ++nb) bfr[nb] = *(const bf16x8*)(sb + b_base + nb * 4096 + xo[ks]);
; #pragma unroll
;       for (int mb = 0; mb < 2; ++mb)
; #pragma unroll
;         for (int nb = 0; nb < 2; ++nb)
;           acc[mb][nb] = __builtin_amdgcn_mfma_f32_32x32x16_bf16(af[mb], bfr[nb], acc[mb][nb], 0, 0, 0);
;     }
;     WAIT_V0();
;     __syncthreads();
;   }
	ds_read_b128 v[0:3], v79
	v_lshlrev_b32_e32 v4, 7, v12
	v_and_b32_e32 v116, 0x2f80, v4
	v_or_b32_e32 v81, v116, v6
	ds_read_b128 v[4:7], v81 offset:16384
	ds_read_b128 v[8:11], v81 offset:20480
	s_waitcnt lgkmcnt(0)
	v_mfma_f32_32x32x16_bf16 v[48:63], v[0:3], v[4:7], 0
	s_mov_b32 m0, s84
	s_mov_b32 s3, 0xfffffc0
	v_mfma_f32_32x32x16_bf16 v[32:47], v[0:3], v[8:11], 0
	ds_read_b128 v[0:3], v79 offset:4096
	s_waitcnt lgkmcnt(0)
	v_mfma_f32_32x32x16_bf16 v[16:31], v[0:3], v[4:7], 0
	v_bitop3_b32 v4, v117, v86, 2 bitop3:0x36
	v_lshlrev_b32_e32 v82, 4, v4
	v_or_b32_e32 v80, v87, v82
	ds_read_b128 v[104:107], v80
	v_or_b32_e32 v83, v116, v82
	ds_read_b128 v[108:111], v83 offset:16384
	ds_read_b128 v[112:115], v83 offset:20480
	s_waitcnt lgkmcnt(0)
	v_mfma_f32_32x32x16_bf16 v[48:63], v[104:107], v[108:111], v[48:63]
	v_bitop3_b32 v82, v117, v86, 4 bitop3:0x36
	v_lshlrev_b32_e32 v85, 4, v82
	v_or_b32_e32 v82, v87, v85
	v_or_b32_e32 v85, v116, v85
	v_bitop3_b32 v86, v117, v86, 6 bitop3:0x36
	v_mfma_f32_32x32x16_bf16 v[32:47], v[104:107], v[112:115], v[32:47]
	ds_read_b128 v[104:107], v80 offset:4096
	v_mfma_f32_32x32x16_bf16 v[0:15], v[0:3], v[8:11], 0
	s_waitcnt lgkmcnt(0)
	v_mfma_f32_32x32x16_bf16 v[16:31], v[104:107], v[108:111], v[16:31]
	ds_read_b128 v[108:111], v85 offset:16384
	v_mfma_f32_32x32x16_bf16 v[0:15], v[104:107], v[112:115], v[0:15]
	ds_read_b128 v[104:107], v82
	ds_read_b128 v[112:115], v85 offset:20480
	s_waitcnt lgkmcnt(0)
	v_mfma_f32_32x32x16_bf16 v[48:63], v[104:107], v[108:111], v[48:63]
	v_mfma_f32_32x32x16_bf16 v[32:47], v[104:107], v[112:115], v[32:47]
	ds_read_b128 v[104:107], v82 offset:4096
	s_waitcnt lgkmcnt(0)
	v_mfma_f32_32x32x16_bf16 v[16:31], v[104:107], v[108:111], v[16:31]
	v_lshlrev_b32_e32 v108, 4, v86
	v_or_b32_e32 v86, v87, v108
	v_or_b32_e32 v87, v116, v108
	ds_read_b128 v[108:111], v87 offset:16384
	v_mfma_f32_32x32x16_bf16 v[0:15], v[104:107], v[112:115], v[0:15]
	ds_read_b128 v[104:107], v86
	ds_read_b128 v[112:115], v87 offset:20480
	ds_read_b128 v[144:147], v86 offset:4096
	s_waitcnt vmcnt(0)
	s_waitcnt vmcnt(0) lgkmcnt(0)
	s_barrier
	v_mfma_f32_32x32x16_bf16 v[48:63], v[104:107], v[108:111], v[48:63]
	v_mfma_f32_32x32x16_bf16 v[32:47], v[104:107], v[112:115], v[32:47]
	v_mfma_f32_32x32x16_bf16 v[16:31], v[144:147], v[108:111], v[16:31]
	v_mfma_f32_32x32x16_bf16 v[0:15], v[144:147], v[112:115], v[0:15]
	ds_read_b128 v[104:107], v79 offset:32768
	ds_read_b128 v[108:111], v81 offset:49152
	ds_read_b128 v[112:115], v81 offset:53248
	v_lshl_add_u64 v[140:141], v[64:65], 0, s[4:5]
	global_load_lds_dwordx4 v[140:141], off
	s_mov_b32 m0, s85
	v_lshl_add_u64 v[142:143], v[66:67], 0, s[4:5]
	global_load_lds_dwordx4 v76, s[16:17]
	s_mov_b32 m0, s86
	s_nop 0
	global_load_lds_dwordx4 v[142:143], off
	s_mov_b32 m0, s87
	v_lshl_add_u64 v[140:141], v[68:69], 0, s[4:5]
	global_load_lds_dwordx4 v77, s[16:17]
	s_mov_b32 m0, s88
	s_nop 0
	global_load_lds_dwordx4 v[140:141], off
	s_mov_b32 m0, s89
	v_lshl_add_u64 v[142:143], v[70:71], 0, s[4:5]
	global_load_lds_dwordx4 v78, s[16:17]
	s_mov_b32 m0, s90
	s_mov_b64 s[4:5], 0x180
	global_load_lds_dwordx4 v[142:143], off
	s_mov_b32 m0, s91
	s_nop 0
	global_load_lds_dwordx4 v84, s[16:17]
	s_waitcnt lgkmcnt(0)
	v_mfma_f32_32x32x16_bf16 v[48:63], v[104:107], v[108:111], v[48:63]
	s_mov_b32 m0, s18
	v_mfma_f32_32x32x16_bf16 v[32:47], v[104:107], v[112:115], v[32:47]
	ds_read_b128 v[104:107], v79 offset:36864
	s_waitcnt lgkmcnt(0)
	v_mfma_f32_32x32x16_bf16 v[16:31], v[104:107], v[108:111], v[16:31]
	v_mfma_f32_32x32x16_bf16 v[0:15], v[104:107], v[112:115], v[0:15]
	ds_read_b128 v[104:107], v80 offset:32768
	ds_read_b128 v[108:111], v83 offset:49152
	ds_read_b128 v[112:115], v83 offset:53248
	s_waitcnt lgkmcnt(0)
	v_mfma_f32_32x32x16_bf16 v[48:63], v[104:107], v[108:111], v[48:63]
	v_mfma_f32_32x32x16_bf16 v[32:47], v[104:107], v[112:115], v[32:47]
	ds_read_b128 v[104:107], v80 offset:36864
	s_waitcnt lgkmcnt(0)
	v_mfma_f32_32x32x16_bf16 v[16:31], v[104:107], v[108:111], v[16:31]
	v_mfma_f32_32x32x16_bf16 v[0:15], v[104:107], v[112:115], v[0:15]
	ds_read_b128 v[148:151], v82 offset:32768
	ds_read_b128 v[156:159], v85 offset:49152
	ds_read_b128 v[208:211], v85 offset:53248
	ds_read_b128 v[152:155], v82 offset:36864
	ds_read_b128 v[104:107], v86 offset:32768
	ds_read_b128 v[108:111], v87 offset:49152
	ds_read_b128 v[112:115], v87 offset:53248
	ds_read_b128 v[144:147], v86 offset:36864
	s_waitcnt vmcnt(0)
	s_waitcnt vmcnt(0) lgkmcnt(0)
	s_barrier
; #define WAIT_V0() asm volatile("s_waitcnt vmcnt(0)" ::: "memory")
; DI void gemm_core(char* smem, int nk, const char* Ab, const char* Bb, const unsigned (&aoff)[4], const unsigned (&boff)[4],
;                   f32x16 (&acc)[2][2]) {
;     ...
;   auto stage = [&](int buf, int kt) __attribute__((always_inline)) {
;     const char* ak = Ab + kt * 128;
;     const char* bk = Bb + kt * 128;
;     char* sa = smem + buf * STAGE_B + w * 4096;
; #pragma unroll
;     for (int i = 0; i < 4; ++i) {
;       __builtin_amdgcn_global_load_lds((const unsigned*)(ak + aoff[i]), (unsigned*)(sa + i * 1024), 16, 0, 0);
;       __builtin_amdgcn_global_load_lds((const unsigned*)(bk + boff[i]), (unsigned*)(sa + 16384 + i * 1024), 16, 0, 0);
;     }
;   };
;   stage(0, 0);
;   WAIT_V0();
;   __syncthreads();
;   for (int kt = 0; kt < nk; ++kt) {
;     const int cur = kt & 1;
;     if (kt + 1 < nk) stage(cur ^ 1, kt + 1);
;     const char* sb = smem + cur * STAGE_B;
; #pragma unroll
;     for (int ks = 0; ks < 4; ++ks) {
;       bf16x8 af[2], bfr[2];
; #pragma unroll
;       for (int mb = 0; mb < 2; ++mb) af[mb] = *(const bf16x8*)(sb + a_base + mb * 4096 + xo[ks]);
; #pragma unroll
;       for (int nb = 0; nb < 2; ++nb) bfr[nb] = *(const bf16x8*)(sb + b_base + nb * 4096 + xo[ks]);
; #pragma unroll
;       for (int mb = 0; mb < 2; ++mb)
; #pragma unroll
;         for (int nb = 0; nb < 2; ++nb)
;           acc[mb][nb] = __builtin_amdgcn_mfma_f32_32x32x16_bf16(af[mb], bfr[nb], acc[mb][nb], 0, 0, 0);
;     }
;     WAIT_V0();
;     __syncthreads();
;   }
	v_mfma_f32_32x32x16_bf16 v[48:63], v[148:151], v[156:159], v[48:63]
	v_lshl_add_u64 v[140:141], v[64:65], 0, s[4:5]
	global_load_lds_dwordx4 v[140:141], off
	v_mfma_f32_32x32x16_bf16 v[32:47], v[148:151], v[208:211], v[32:47]
	s_mov_b32 m0, s19
	v_lshl_add_u64 v[142:143], v[66:67], 0, s[4:5]
	global_load_lds_dwordx4 v76, s[42:43]
	v_mfma_f32_32x32x16_bf16 v[16:31], v[152:155], v[156:159], v[16:31]
	s_mov_b32 m0, s22
	s_nop 0
	global_load_lds_dwordx4 v[142:143], off
	v_mfma_f32_32x32x16_bf16 v[0:15], v[152:155], v[208:211], v[0:15]
	s_mov_b32 m0, s23
	v_lshl_add_u64 v[140:141], v[68:69], 0, s[4:5]
	global_load_lds_dwordx4 v77, s[42:43]
	v_mfma_f32_32x32x16_bf16 v[48:63], v[104:107], v[108:111], v[48:63]
	s_mov_b32 m0, s29
	s_nop 0
	global_load_lds_dwordx4 v[140:141], off
	v_mfma_f32_32x32x16_bf16 v[32:47], v[104:107], v[112:115], v[32:47]
	s_mov_b32 m0, s69
	v_lshl_add_u64 v[142:143], v[70:71], 0, s[4:5]
	global_load_lds_dwordx4 v78, s[42:43]
	v_mfma_f32_32x32x16_bf16 v[16:31], v[144:147], v[108:111], v[16:31]
	s_mov_b32 m0, s70
	s_mov_b64 s[4:5], 0x280
	global_load_lds_dwordx4 v[142:143], off
	v_mfma_f32_32x32x16_bf16 v[0:15], v[144:147], v[112:115], v[0:15]
	s_mov_b32 m0, s71
	s_nop 0
	global_load_lds_dwordx4 v84, s[42:43]
	ds_read_b128 v[104:107], v79
	ds_read_b128 v[108:111], v81 offset:16384
	ds_read_b128 v[112:115], v81 offset:20480
	s_waitcnt lgkmcnt(0)
	v_mfma_f32_32x32x16_bf16 v[48:63], v[104:107], v[108:111], v[48:63]
	s_mov_b32 m0, s84
	v_mfma_f32_32x32x16_bf16 v[32:47], v[104:107], v[112:115], v[32:47]
	ds_read_b128 v[104:107], v79 offset:4096
	s_waitcnt lgkmcnt(0)
	v_mfma_f32_32x32x16_bf16 v[16:31], v[104:107], v[108:111], v[16:31]
	v_mfma_f32_32x32x16_bf16 v[0:15], v[104:107], v[112:115], v[0:15]
	ds_read_b128 v[104:107], v80
	ds_read_b128 v[108:111], v83 offset:16384
	ds_read_b128 v[112:115], v83 offset:20480
	s_waitcnt lgkmcnt(0)
	v_mfma_f32_32x32x16_bf16 v[48:63], v[104:107], v[108:111], v[48:63]
	v_mfma_f32_32x32x16_bf16 v[32:47], v[104:107], v[112:115], v[32:47]
	ds_read_b128 v[104:107], v80 offset:4096
	s_waitcnt lgkmcnt(0)
	v_mfma_f32_32x32x16_bf16 v[16:31], v[104:107], v[108:111], v[16:31]
	v_mfma_f32_32x32x16_bf16 v[0:15], v[104:107], v[112:115], v[0:15]
	ds_read_b128 v[148:151], v82
	ds_read_b128 v[156:159], v85 offset:16384
	ds_read_b128 v[208:211], v85 offset:20480
	ds_read_b128 v[152:155], v82 offset:4096
	ds_read_b128 v[104:107], v86
	ds_read_b128 v[108:111], v87 offset:16384
	ds_read_b128 v[112:115], v87 offset:20480
	ds_read_b128 v[144:147], v86 offset:4096
	s_waitcnt vmcnt(0)
	s_waitcnt vmcnt(0) lgkmcnt(0)
	s_barrier
	v_mfma_f32_32x32x16_bf16 v[48:63], v[148:151], v[156:159], v[48:63]
	v_lshl_add_u64 v[140:141], v[64:65], 0, s[30:31]
	global_load_lds_dwordx4 v[140:141], off
	v_mfma_f32_32x32x16_bf16 v[32:47], v[148:151], v[208:211], v[32:47]
	s_mov_b32 m0, s85
	v_lshl_add_u64 v[142:143], v[66:67], 0, s[30:31]
	global_load_lds_dwordx4 v76, s[44:45]
	v_mfma_f32_32x32x16_bf16 v[16:31], v[152:155], v[156:159], v[16:31]
	s_mov_b32 m0, s86
	s_nop 0
	global_load_lds_dwordx4 v[142:143], off
	v_mfma_f32_32x32x16_bf16 v[0:15], v[152:155], v[208:211], v[0:15]
	s_mov_b32 m0, s87
	v_lshl_add_u64 v[140:141], v[68:69], 0, s[30:31]
	global_load_lds_dwordx4 v77, s[44:45]
	v_mfma_f32_32x32x16_bf16 v[48:63], v[104:107], v[108:111], v[48:63]
	s_mov_b32 m0, s88
	s_nop 0
	global_load_lds_dwordx4 v[140:141], off
	v_mfma_f32_32x32x16_bf16 v[32:47], v[104:107], v[112:115], v[32:47]
	s_mov_b32 m0, s89
	v_lshl_add_u64 v[142:143], v[70:71], 0, s[30:31]
	global_load_lds_dwordx4 v78, s[44:45]
	v_mfma_f32_32x32x16_bf16 v[16:31], v[144:147], v[108:111], v[16:31]
	s_mov_b32 m0, s90
	s_nop 0
	global_load_lds_dwordx4 v[142:143], off
	v_mfma_f32_32x32x16_bf16 v[0:15], v[144:147], v[112:115], v[0:15]
	s_mov_b32 m0, s91
	s_nop 0
	global_load_lds_dwordx4 v84, s[44:45]
	ds_read_b128 v[104:107], v79 offset:32768
	ds_read_b128 v[108:111], v81 offset:49152
	ds_read_b128 v[112:115], v81 offset:53248
	s_waitcnt lgkmcnt(0)
	v_mfma_f32_32x32x16_bf16 v[48:63], v[104:107], v[108:111], v[48:63]
	s_mov_b32 m0, s18
	v_mfma_f32_32x32x16_bf16 v[32:47], v[104:107], v[112:115], v[32:47]
	ds_read_b128 v[104:107], v79 offset:36864
	s_waitcnt lgkmcnt(0)
	v_mfma_f32_32x32x16_bf16 v[16:31], v[104:107], v[108:111], v[16:31]
	v_mfma_f32_32x32x16_bf16 v[0:15], v[104:107], v[112:115], v[0:15]
	ds_read_b128 v[104:107], v80 offset:32768
	ds_read_b128 v[108:111], v83 offset:49152
	ds_read_b128 v[112:115], v83 offset:53248
	s_waitcnt lgkmcnt(0)
	v_mfma_f32_32x32x16_bf16 v[48:63], v[104:107], v[108:111], v[48:63]
	v_mfma_f32_32x32x16_bf16 v[32:47], v[104:107], v[112:115], v[32:47]
	ds_read_b128 v[104:107], v80 offset:36864
	s_waitcnt lgkmcnt(0)
	v_mfma_f32_32x32x16_bf16 v[16:31], v[104:107], v[108:111], v[16:31]
	v_mfma_f32_32x32x16_bf16 v[0:15], v[104:107], v[112:115], v[0:15]
	ds_read_b128 v[148:151], v82 offset:32768
	ds_read_b128 v[156:159], v85 offset:49152
	ds_read_b128 v[208:211], v85 offset:53248
	ds_read_b128 v[152:155], v82 offset:36864
	ds_read_b128 v[104:107], v86 offset:32768
	ds_read_b128 v[108:111], v87 offset:49152
	ds_read_b128 v[112:115], v87 offset:53248
	ds_read_b128 v[144:147], v86 offset:36864
	s_waitcnt vmcnt(0)
	s_waitcnt vmcnt(0) lgkmcnt(0)
	s_barrier
; #define WAIT_V0() asm volatile("s_waitcnt vmcnt(0)" ::: "memory")
; DI void gemm_core(char* smem, int nk, const char* Ab, const char* Bb, const unsigned (&aoff)[4], const unsigned (&boff)[4],
;                   f32x16 (&acc)[2][2]) {
;     ...
;   auto stage = [&](int buf, int kt) __attribute__((always_inline)) {
;     const char* ak = Ab + kt * 128;
;     const char* bk = Bb + kt * 128;
;     char* sa = smem + buf * STAGE_B + w * 4096;
; #pragma unroll
;     for (int i = 0; i < 4; ++i) {
;       __builtin_amdgcn_global_load_lds((const unsigned*)(ak + aoff[i]), (unsigned*)(sa + i * 1024), 16, 0, 0);
;       __builtin_amdgcn_global_load_lds((const unsigned*)(bk + boff[i]), (unsigned*)(sa + 16384 + i * 1024), 16, 0, 0);
;     }
;   };
;   stage(0, 0);
;   WAIT_V0();
;   __syncthreads();
;   for (int kt = 0; kt < nk; ++kt) {
;     const int cur = kt & 1;
;     if (kt + 1 < nk) stage(cur ^ 1, kt + 1);
;     const char* sb = smem + cur * STAGE_B;
; #pragma unroll
;     for (int ks = 0; ks < 4; ++ks) {
;       bf16x8 af[2], bfr[2];
; #pragma unroll
;       for (int mb = 0; mb < 2; ++mb) af[mb] = *(const bf16x8*)(sb + a_base + mb * 4096 + xo[ks]);
; #pragma unroll
;       for (int nb = 0; nb < 2; ++nb) bfr[nb] = *(const bf16x8*)(sb + b_base + nb * 4096 + xo[ks]);
; #pragma unroll
;       for (int mb = 0; mb < 2; ++mb)
; #pragma unroll
;         for (int nb = 0; nb < 2; ++nb)
;           acc[mb][nb] = __builtin_amdgcn_mfma_f32_32x32x16_bf16(af[mb], bfr[nb], acc[mb][nb], 0, 0, 0);
;     }
;     WAIT_V0();
;     __syncthreads();
;   }
	v_mfma_f32_32x32x16_bf16 v[48:63], v[148:151], v[156:159], v[48:63]
	v_lshl_add_u64 v[140:141], v[64:65], 0, s[4:5]
	global_load_lds_dwordx4 v[140:141], off
	v_mfma_f32_32x32x16_bf16 v[32:47], v[148:151], v[208:211], v[32:47]
	s_mov_b32 m0, s19
	v_lshl_add_u64 v[142:143], v[66:67], 0, s[4:5]
	global_load_lds_dwordx4 v76, s[46:47]
	v_mfma_f32_32x32x16_bf16 v[16:31], v[152:155], v[156:159], v[16:31]
	s_mov_b32 m0, s22
	s_nop 0
	global_load_lds_dwordx4 v[142:143], off
	v_mfma_f32_32x32x16_bf16 v[0:15], v[152:155], v[208:211], v[0:15]
	s_mov_b32 m0, s23
	v_lshl_add_u64 v[140:141], v[68:69], 0, s[4:5]
	global_load_lds_dwordx4 v77, s[46:47]
	v_mfma_f32_32x32x16_bf16 v[48:63], v[104:107], v[108:111], v[48:63]
	s_mov_b32 m0, s29
	s_nop 0
	global_load_lds_dwordx4 v[140:141], off
	v_mfma_f32_32x32x16_bf16 v[32:47], v[104:107], v[112:115], v[32:47]
	s_mov_b32 m0, s69
	v_lshl_add_u64 v[142:143], v[70:71], 0, s[4:5]
	global_load_lds_dwordx4 v78, s[46:47]
	v_mfma_f32_32x32x16_bf16 v[16:31], v[144:147], v[108:111], v[16:31]
	s_mov_b32 m0, s70
	s_mov_b64 s[4:5], 0x300
	global_load_lds_dwordx4 v[142:143], off
	v_mfma_f32_32x32x16_bf16 v[0:15], v[144:147], v[112:115], v[0:15]
	s_mov_b32 m0, s71
	s_nop 0
	global_load_lds_dwordx4 v84, s[46:47]
	ds_read_b128 v[104:107], v79
	ds_read_b128 v[108:111], v81 offset:16384
	ds_read_b128 v[112:115], v81 offset:20480
	s_waitcnt lgkmcnt(0)
	v_mfma_f32_32x32x16_bf16 v[48:63], v[104:107], v[108:111], v[48:63]
	s_mov_b32 m0, s84
	v_mfma_f32_32x32x16_bf16 v[32:47], v[104:107], v[112:115], v[32:47]
	ds_read_b128 v[104:107], v79 offset:4096
	s_waitcnt lgkmcnt(0)
	v_mfma_f32_32x32x16_bf16 v[16:31], v[104:107], v[108:111], v[16:31]
	v_mfma_f32_32x32x16_bf16 v[0:15], v[104:107], v[112:115], v[0:15]
	ds_read_b128 v[104:107], v80
	ds_read_b128 v[108:111], v83 offset:16384
	ds_read_b128 v[112:115], v83 offset:20480
	s_waitcnt lgkmcnt(0)
	v_mfma_f32_32x32x16_bf16 v[48:63], v[104:107], v[108:111], v[48:63]
	v_mfma_f32_32x32x16_bf16 v[32:47], v[104:107], v[112:115], v[32:47]
	ds_read_b128 v[104:107], v80 offset:4096
	s_waitcnt lgkmcnt(0)
	v_mfma_f32_32x32x16_bf16 v[16:31], v[104:107], v[108:111], v[16:31]
	v_mfma_f32_32x32x16_bf16 v[0:15], v[104:107], v[112:115], v[0:15]
	ds_read_b128 v[148:151], v82
	ds_read_b128 v[156:159], v85 offset:16384
	ds_read_b128 v[208:211], v85 offset:20480
	ds_read_b128 v[152:155], v82 offset:4096
	ds_read_b128 v[104:107], v86
	ds_read_b128 v[108:111], v87 offset:16384
	ds_read_b128 v[112:115], v87 offset:20480
	ds_read_b128 v[144:147], v86 offset:4096
	s_waitcnt vmcnt(0)
	s_waitcnt vmcnt(0) lgkmcnt(0)
	s_barrier
	v_mfma_f32_32x32x16_bf16 v[48:63], v[148:151], v[156:159], v[48:63]
	v_lshl_add_u64 v[140:141], v[64:65], 0, s[4:5]
	global_load_lds_dwordx4 v[140:141], off
	v_mfma_f32_32x32x16_bf16 v[32:47], v[148:151], v[208:211], v[32:47]
	s_mov_b32 m0, s85
	v_lshl_add_u64 v[142:143], v[66:67], 0, s[4:5]
	global_load_lds_dwordx4 v76, s[48:49]
	v_mfma_f32_32x32x16_bf16 v[16:31], v[152:155], v[156:159], v[16:31]
	s_mov_b32 m0, s86
	s_nop 0
	global_load_lds_dwordx4 v[142:143], off
	v_mfma_f32_32x32x16_bf16 v[0:15], v[152:155], v[208:211], v[0:15]
	s_mov_b32 m0, s87
	v_lshl_add_u64 v[140:141], v[68:69], 0, s[4:5]
	global_load_lds_dwordx4 v77, s[48:49]
	v_mfma_f32_32x32x16_bf16 v[48:63], v[104:107], v[108:111], v[48:63]
	s_mov_b32 m0, s88
	s_nop 0
	global_load_lds_dwordx4 v[140:141], off
	v_mfma_f32_32x32x16_bf16 v[32:47], v[104:107], v[112:115], v[32:47]
	s_mov_b32 m0, s89
	v_lshl_add_u64 v[142:143], v[70:71], 0, s[4:5]
	global_load_lds_dwordx4 v78, s[48:49]
	v_mfma_f32_32x32x16_bf16 v[16:31], v[144:147], v[108:111], v[16:31]
	s_mov_b32 m0, s90
	s_mov_b64 s[4:5], 0x380
	global_load_lds_dwordx4 v[142:143], off
	v_mfma_f32_32x32x16_bf16 v[0:15], v[144:147], v[112:115], v[0:15]
	s_mov_b32 m0, s91
	s_nop 0
	global_load_lds_dwordx4 v84, s[48:49]
	ds_read_b128 v[104:107], v79 offset:32768
	ds_read_b128 v[108:111], v81 offset:49152
	ds_read_b128 v[112:115], v81 offset:53248
	s_waitcnt lgkmcnt(0)
	v_mfma_f32_32x32x16_bf16 v[48:63], v[104:107], v[108:111], v[48:63]
	s_mov_b32 m0, s18
	v_mfma_f32_32x32x16_bf16 v[32:47], v[104:107], v[112:115], v[32:47]
	ds_read_b128 v[104:107], v79 offset:36864
	s_waitcnt lgkmcnt(0)
	v_mfma_f32_32x32x16_bf16 v[16:31], v[104:107], v[108:111], v[16:31]
	v_mfma_f32_32x32x16_bf16 v[0:15], v[104:107], v[112:115], v[0:15]
	ds_read_b128 v[104:107], v80 offset:32768
	ds_read_b128 v[108:111], v83 offset:49152
	ds_read_b128 v[112:115], v83 offset:53248
	s_waitcnt lgkmcnt(0)
	v_mfma_f32_32x32x16_bf16 v[48:63], v[104:107], v[108:111], v[48:63]
	v_mfma_f32_32x32x16_bf16 v[32:47], v[104:107], v[112:115], v[32:47]
	ds_read_b128 v[104:107], v80 offset:36864
	s_waitcnt lgkmcnt(0)
	v_mfma_f32_32x32x16_bf16 v[16:31], v[104:107], v[108:111], v[16:31]
	v_mfma_f32_32x32x16_bf16 v[0:15], v[104:107], v[112:115], v[0:15]
	ds_read_b128 v[148:151], v82 offset:32768
	ds_read_b128 v[156:159], v85 offset:49152
	ds_read_b128 v[208:211], v85 offset:53248
	ds_read_b128 v[152:155], v82 offset:36864
	ds_read_b128 v[104:107], v86 offset:32768
	ds_read_b128 v[108:111], v87 offset:49152
	ds_read_b128 v[112:115], v87 offset:53248
	ds_read_b128 v[144:147], v86 offset:36864
	s_waitcnt vmcnt(0)
	s_waitcnt vmcnt(0) lgkmcnt(0)
	s_barrier
; #define WAIT_V0() asm volatile("s_waitcnt vmcnt(0)" ::: "memory")
; DI void gemm_core(char* smem, int nk, const char* Ab, const char* Bb, const unsigned (&aoff)[4], const unsigned (&boff)[4],
;                   f32x16 (&acc)[2][2]) {
;     ...
;   auto stage = [&](int buf, int kt) __attribute__((always_inline)) {
;     const char* ak = Ab + kt * 128;
;     const char* bk = Bb + kt * 128;
;     char* sa = smem + buf * STAGE_B + w * 4096;
; #pragma unroll
;     for (int i = 0; i < 4; ++i) {
;       __builtin_amdgcn_global_load_lds((const unsigned*)(ak + aoff[i]), (unsigned*)(sa + i * 1024), 16, 0, 0);
;       __builtin_amdgcn_global_load_lds((const unsigned*)(bk + boff[i]), (unsigned*)(sa + 16384 + i * 1024), 16, 0, 0);
;     }
;   };
;   stage(0, 0);
;   WAIT_V0();
;   __syncthreads();
;   for (int kt = 0; kt < nk; ++kt) {
;     const int cur = kt & 1;
;     if (kt + 1 < nk) stage(cur ^ 1, kt + 1);
;     const char* sb = smem + cur * STAGE_B;
; #pragma unroll
;     for (int ks = 0; ks < 4; ++ks) {
;       bf16x8 af[2], bfr[2];
; #pragma unroll
;       for (int mb = 0; mb < 2; ++mb) af[mb] = *(const bf16x8*)(sb + a_base + mb * 4096 + xo[ks]);
; #pragma unroll
;       for (int nb = 0; nb < 2; ++nb) bfr[nb] = *(const bf16x8*)(sb + b_base + nb * 4096 + xo[ks]);
; #pragma unroll
;       for (int mb = 0; mb < 2; ++mb)
; #pragma unroll
;         for (int nb = 0; nb < 2; ++nb)
;           acc[mb][nb] = __builtin_amdgcn_mfma_f32_32x32x16_bf16(af[mb], bfr[nb], acc[mb][nb], 0, 0, 0);
;     }
;     WAIT_V0();
;     __syncthreads();
;   }
	v_mfma_f32_32x32x16_bf16 v[48:63], v[148:151], v[156:159], v[48:63]
	v_lshl_add_u64 v[140:141], v[64:65], 0, s[4:5]
	global_load_lds_dwordx4 v[140:141], off
	v_mfma_f32_32x32x16_bf16 v[32:47], v[148:151], v[208:211], v[32:47]
	s_mov_b32 m0, s19
	v_lshl_add_u64 v[142:143], v[66:67], 0, s[4:5]
	global_load_lds_dwordx4 v76, s[50:51]
	v_mfma_f32_32x32x16_bf16 v[16:31], v[152:155], v[156:159], v[16:31]
	s_mov_b32 m0, s22
	s_nop 0
	global_load_lds_dwordx4 v[142:143], off
	v_mfma_f32_32x32x16_bf16 v[0:15], v[152:155], v[208:211], v[0:15]
	s_mov_b32 m0, s23
	v_lshl_add_u64 v[140:141], v[68:69], 0, s[4:5]
	global_load_lds_dwordx4 v77, s[50:51]
	v_mfma_f32_32x32x16_bf16 v[48:63], v[104:107], v[108:111], v[48:63]
	s_mov_b32 m0, s29
	s_nop 0
	global_load_lds_dwordx4 v[140:141], off
	v_mfma_f32_32x32x16_bf16 v[32:47], v[104:107], v[112:115], v[32:47]
	s_mov_b32 m0, s69
	v_lshl_add_u64 v[142:143], v[70:71], 0, s[4:5]
	global_load_lds_dwordx4 v78, s[50:51]
	v_mfma_f32_32x32x16_bf16 v[16:31], v[144:147], v[108:111], v[16:31]
	s_mov_b32 m0, s70
	s_mov_b64 s[4:5], 0x400
	global_load_lds_dwordx4 v[142:143], off
	v_mfma_f32_32x32x16_bf16 v[0:15], v[144:147], v[112:115], v[0:15]
	s_mov_b32 m0, s71
	s_nop 0
	global_load_lds_dwordx4 v84, s[50:51]
	ds_read_b128 v[104:107], v79
	ds_read_b128 v[108:111], v81 offset:16384
	ds_read_b128 v[112:115], v81 offset:20480
	s_waitcnt lgkmcnt(0)
	v_mfma_f32_32x32x16_bf16 v[48:63], v[104:107], v[108:111], v[48:63]
	s_mov_b32 m0, s84
	v_readfirstlane_b32 s84, v89
	v_mfma_f32_32x32x16_bf16 v[32:47], v[104:107], v[112:115], v[32:47]
	ds_read_b128 v[104:107], v79 offset:4096
	s_waitcnt lgkmcnt(0)
	v_mfma_f32_32x32x16_bf16 v[16:31], v[104:107], v[108:111], v[16:31]
	v_mfma_f32_32x32x16_bf16 v[0:15], v[104:107], v[112:115], v[0:15]
	ds_read_b128 v[104:107], v80
	ds_read_b128 v[108:111], v83 offset:16384
	ds_read_b128 v[112:115], v83 offset:20480
	s_waitcnt lgkmcnt(0)
	v_mfma_f32_32x32x16_bf16 v[48:63], v[104:107], v[108:111], v[48:63]
	v_mfma_f32_32x32x16_bf16 v[32:47], v[104:107], v[112:115], v[32:47]
	ds_read_b128 v[104:107], v80 offset:4096
	s_waitcnt lgkmcnt(0)
	v_mfma_f32_32x32x16_bf16 v[16:31], v[104:107], v[108:111], v[16:31]
	v_mfma_f32_32x32x16_bf16 v[0:15], v[104:107], v[112:115], v[0:15]
	ds_read_b128 v[148:151], v82
	ds_read_b128 v[156:159], v85 offset:16384
	ds_read_b128 v[208:211], v85 offset:20480
	ds_read_b128 v[152:155], v82 offset:4096
	ds_read_b128 v[104:107], v86
	ds_read_b128 v[108:111], v87 offset:16384
	ds_read_b128 v[112:115], v87 offset:20480
	ds_read_b128 v[144:147], v86 offset:4096
	s_waitcnt vmcnt(0)
	s_waitcnt vmcnt(0) lgkmcnt(0)
	s_barrier
	v_mfma_f32_32x32x16_bf16 v[48:63], v[148:151], v[156:159], v[48:63]
	v_lshl_add_u64 v[140:141], v[64:65], 0, s[4:5]
	global_load_lds_dwordx4 v[140:141], off
	v_mfma_f32_32x32x16_bf16 v[32:47], v[148:151], v[208:211], v[32:47]
	s_mov_b32 m0, s85
	v_lshl_add_u64 v[142:143], v[66:67], 0, s[4:5]
	global_load_lds_dwordx4 v76, s[52:53]
	v_mfma_f32_32x32x16_bf16 v[16:31], v[152:155], v[156:159], v[16:31]
	s_mov_b32 m0, s86
	v_readfirstlane_b32 s85, v88
	global_load_lds_dwordx4 v[142:143], off
	v_mfma_f32_32x32x16_bf16 v[0:15], v[152:155], v[208:211], v[0:15]
	s_mov_b32 m0, s87
	v_lshl_add_u64 v[140:141], v[68:69], 0, s[4:5]
	global_load_lds_dwordx4 v77, s[52:53]
	v_mfma_f32_32x32x16_bf16 v[48:63], v[104:107], v[108:111], v[48:63]
	s_mov_b32 m0, s88
	v_readfirstlane_b32 s86, v90
	global_load_lds_dwordx4 v[140:141], off
	v_mfma_f32_32x32x16_bf16 v[32:47], v[104:107], v[112:115], v[32:47]
	s_mov_b32 m0, s89
	v_lshl_add_u64 v[142:143], v[70:71], 0, s[4:5]
	global_load_lds_dwordx4 v78, s[52:53]
	v_mfma_f32_32x32x16_bf16 v[16:31], v[144:147], v[108:111], v[16:31]
	s_mov_b32 m0, s90
	s_mov_b64 s[4:5], 0x480
	global_load_lds_dwordx4 v[142:143], off
	v_mfma_f32_32x32x16_bf16 v[0:15], v[144:147], v[112:115], v[0:15]
	s_mov_b32 m0, s91
	v_readfirstlane_b32 s87, v91
	global_load_lds_dwordx4 v84, s[52:53]
	ds_read_b128 v[104:107], v79 offset:32768
	ds_read_b128 v[108:111], v81 offset:49152
	ds_read_b128 v[112:115], v81 offset:53248
	s_waitcnt lgkmcnt(0)
	v_mfma_f32_32x32x16_bf16 v[48:63], v[104:107], v[108:111], v[48:63]
	s_mov_b32 m0, s18
	v_readfirstlane_b32 s18, v97
	v_readfirstlane_b32 s88, v92
	v_readfirstlane_b32 s89, v93
	v_readfirstlane_b32 s90, v94
	v_readfirstlane_b32 s91, v95
	v_mfma_f32_32x32x16_bf16 v[32:47], v[104:107], v[112:115], v[32:47]
	ds_read_b128 v[104:107], v79 offset:36864
	s_waitcnt lgkmcnt(0)
	v_mfma_f32_32x32x16_bf16 v[16:31], v[104:107], v[108:111], v[16:31]
	v_mfma_f32_32x32x16_bf16 v[0:15], v[104:107], v[112:115], v[0:15]
	ds_read_b128 v[104:107], v80 offset:32768
	ds_read_b128 v[108:111], v83 offset:49152
	ds_read_b128 v[112:115], v83 offset:53248
	s_waitcnt lgkmcnt(0)
	v_mfma_f32_32x32x16_bf16 v[48:63], v[104:107], v[108:111], v[48:63]
	v_mfma_f32_32x32x16_bf16 v[32:47], v[104:107], v[112:115], v[32:47]
	ds_read_b128 v[104:107], v80 offset:36864
	s_waitcnt lgkmcnt(0)
	v_mfma_f32_32x32x16_bf16 v[16:31], v[104:107], v[108:111], v[16:31]
	v_mfma_f32_32x32x16_bf16 v[0:15], v[104:107], v[112:115], v[0:15]
	ds_read_b128 v[148:151], v82 offset:32768
	ds_read_b128 v[156:159], v85 offset:49152
	ds_read_b128 v[208:211], v85 offset:53248
	ds_read_b128 v[152:155], v82 offset:36864
	ds_read_b128 v[104:107], v86 offset:32768
	ds_read_b128 v[108:111], v87 offset:49152
	ds_read_b128 v[112:115], v87 offset:53248
	ds_read_b128 v[144:147], v86 offset:36864
	s_waitcnt vmcnt(0)
	s_waitcnt vmcnt(0) lgkmcnt(0)
	s_barrier
; #define WAIT_V0() asm volatile("s_waitcnt vmcnt(0)" ::: "memory")
; DI void gemm_core(char* smem, int nk, const char* Ab, const char* Bb, const unsigned (&aoff)[4], const unsigned (&boff)[4],
;                   f32x16 (&acc)[2][2]) {
;     ...
;   auto stage = [&](int buf, int kt) __attribute__((always_inline)) {
;     const char* ak = Ab + kt * 128;
;     const char* bk = Bb + kt * 128;
;     char* sa = smem + buf * STAGE_B + w * 4096;
; #pragma unroll
;     for (int i = 0; i < 4; ++i) {
;       __builtin_amdgcn_global_load_lds((const unsigned*)(ak + aoff[i]), (unsigned*)(sa + i * 1024), 16, 0, 0);
;       __builtin_amdgcn_global_load_lds((const unsigned*)(bk + boff[i]), (unsigned*)(sa + 16384 + i * 1024), 16, 0, 0);
;     }
;   };
;   stage(0, 0);
;   WAIT_V0();
;   __syncthreads();
;   for (int kt = 0; kt < nk; ++kt) {
;     const int cur = kt & 1;
;     if (kt + 1 < nk) stage(cur ^ 1, kt + 1);
;     const char* sb = smem + cur * STAGE_B;
; #pragma unroll
;     for (int ks = 0; ks < 4; ++ks) {
;       bf16x8 af[2], bfr[2];
; #pragma unroll
;       for (int mb = 0; mb < 2; ++mb) af[mb] = *(const bf16x8*)(sb + a_base + mb * 4096 + xo[ks]);
; #pragma unroll
;       for (int nb = 0; nb < 2; ++nb) bfr[nb] = *(const bf16x8*)(sb + b_base + nb * 4096 + xo[ks]);
; #pragma unroll
;       for (int mb = 0; mb < 2; ++mb)
; #pragma unroll
;         for (int nb = 0; nb < 2; ++nb)
;           acc[mb][nb] = __builtin_amdgcn_mfma_f32_32x32x16_bf16(af[mb], bfr[nb], acc[mb][nb], 0, 0, 0);
;     }
;     WAIT_V0();
;     __syncthreads();
;   }
	v_mfma_f32_32x32x16_bf16 v[48:63], v[148:151], v[156:159], v[48:63]
	v_mfma_f32_32x32x16_bf16 v[32:47], v[148:151], v[208:211], v[32:47]
	v_mfma_f32_32x32x16_bf16 v[16:31], v[152:155], v[156:159], v[16:31]
	v_mfma_f32_32x32x16_bf16 v[0:15], v[152:155], v[208:211], v[0:15]
	v_mfma_f32_32x32x16_bf16 v[48:63], v[104:107], v[108:111], v[48:63]
	v_mfma_f32_32x32x16_bf16 v[32:47], v[104:107], v[112:115], v[32:47]
	v_mfma_f32_32x32x16_bf16 v[16:31], v[144:147], v[108:111], v[16:31]
	v_mfma_f32_32x32x16_bf16 v[0:15], v[144:147], v[112:115], v[0:15]
	v_lshl_add_u64 v[104:105], v[64:65], 0, s[4:5]
	global_load_lds_dwordx4 v[104:105], off
	s_mov_b32 m0, s19
	v_lshl_add_u64 v[104:105], v[66:67], 0, s[4:5]
	global_load_lds_dwordx4 v76, s[54:55]
	s_mov_b32 m0, s22
	v_readfirstlane_b32 s19, v96
	global_load_lds_dwordx4 v[104:105], off
	s_mov_b32 m0, s23
	v_lshl_add_u64 v[104:105], v[68:69], 0, s[4:5]
	global_load_lds_dwordx4 v77, s[54:55]
	s_mov_b32 m0, s29
	v_readfirstlane_b32 s22, v98
	global_load_lds_dwordx4 v[104:105], off
	s_mov_b32 m0, s69
	v_lshl_add_u64 v[104:105], v[70:71], 0, s[4:5]
	global_load_lds_dwordx4 v78, s[54:55]
	s_mov_b32 m0, s70
	s_mov_b64 s[4:5], 0x500
	global_load_lds_dwordx4 v[104:105], off
	s_mov_b32 m0, s71
	v_lshl_add_u64 v[96:97], v[66:67], 0, s[4:5]
	global_load_lds_dwordx4 v84, s[54:55]
	ds_read_b128 v[104:107], v79
	ds_read_b128 v[108:111], v81 offset:16384
	ds_read_b128 v[112:115], v81 offset:20480
	s_waitcnt lgkmcnt(0)
	v_mfma_f32_32x32x16_bf16 v[48:63], v[104:107], v[108:111], v[48:63]
	s_mov_b32 m0, s18
	v_readfirstlane_b32 s23, v99
	v_readfirstlane_b32 s29, v100
	v_readfirstlane_b32 s69, v101
	v_readfirstlane_b32 s70, v102
	v_readfirstlane_b32 s71, v103
	v_mfma_f32_32x32x16_bf16 v[32:47], v[104:107], v[112:115], v[32:47]
	ds_read_b128 v[104:107], v79 offset:4096
	s_waitcnt lgkmcnt(0)
	v_mfma_f32_32x32x16_bf16 v[16:31], v[104:107], v[108:111], v[16:31]
	v_mfma_f32_32x32x16_bf16 v[0:15], v[104:107], v[112:115], v[0:15]
	ds_read_b128 v[104:107], v80
	ds_read_b128 v[108:111], v83 offset:16384
	ds_read_b128 v[112:115], v83 offset:20480
	s_waitcnt lgkmcnt(0)
	v_mfma_f32_32x32x16_bf16 v[48:63], v[104:107], v[108:111], v[48:63]
	v_mfma_f32_32x32x16_bf16 v[32:47], v[104:107], v[112:115], v[32:47]
	ds_read_b128 v[104:107], v80 offset:4096
	s_waitcnt lgkmcnt(0)
	v_mfma_f32_32x32x16_bf16 v[16:31], v[104:107], v[108:111], v[16:31]
	v_mfma_f32_32x32x16_bf16 v[0:15], v[104:107], v[112:115], v[0:15]
	ds_read_b128 v[148:151], v82
	ds_read_b128 v[156:159], v85 offset:16384
	ds_read_b128 v[208:211], v85 offset:20480
	ds_read_b128 v[152:155], v82 offset:4096
	ds_read_b128 v[104:107], v86
	ds_read_b128 v[108:111], v87 offset:16384
	ds_read_b128 v[112:115], v87 offset:20480
	ds_read_b128 v[144:147], v86 offset:4096
	s_waitcnt vmcnt(0)
	s_waitcnt vmcnt(0) lgkmcnt(0)
	s_barrier
	v_mfma_f32_32x32x16_bf16 v[48:63], v[148:151], v[156:159], v[48:63]
	v_mfma_f32_32x32x16_bf16 v[32:47], v[148:151], v[208:211], v[32:47]
	v_mfma_f32_32x32x16_bf16 v[16:31], v[152:155], v[156:159], v[16:31]
	v_mfma_f32_32x32x16_bf16 v[0:15], v[152:155], v[208:211], v[0:15]
	v_mfma_f32_32x32x16_bf16 v[48:63], v[104:107], v[108:111], v[48:63]
	v_mfma_f32_32x32x16_bf16 v[32:47], v[104:107], v[112:115], v[32:47]
	v_mfma_f32_32x32x16_bf16 v[16:31], v[144:147], v[108:111], v[16:31]
	v_mfma_f32_32x32x16_bf16 v[0:15], v[144:147], v[112:115], v[0:15]
	v_lshl_add_u64 v[104:105], v[64:65], 0, s[4:5]
	global_load_lds_dwordx4 v[104:105], off
	s_mov_b32 m0, s19
	s_nop 0
	global_load_lds_dwordx4 v76, s[56:57]
	s_mov_b32 m0, s22
	s_nop 0
	global_load_lds_dwordx4 v[96:97], off
	s_mov_b32 m0, s23
	v_lshl_add_u64 v[96:97], v[68:69], 0, s[4:5]
	global_load_lds_dwordx4 v77, s[56:57]
	s_mov_b32 m0, s29
	s_nop 0
	global_load_lds_dwordx4 v[96:97], off
	s_mov_b32 m0, s69
	v_lshl_add_u64 v[96:97], v[70:71], 0, s[4:5]
	global_load_lds_dwordx4 v78, s[56:57]
	s_mov_b32 m0, s70
	s_mov_b64 s[4:5], 0x580
	global_load_lds_dwordx4 v[96:97], off
	s_mov_b32 m0, s71
	v_lshl_add_u64 v[88:89], v[66:67], 0, s[4:5]
	global_load_lds_dwordx4 v84, s[56:57]
	ds_read_b128 v[96:99], v79 offset:32768
	ds_read_b128 v[100:103], v81 offset:49152
	ds_read_b128 v[104:107], v81 offset:53248
	s_waitcnt lgkmcnt(0)
	v_mfma_f32_32x32x16_bf16 v[48:63], v[96:99], v[100:103], v[48:63]
	s_mov_b32 m0, s84
	v_mfma_f32_32x32x16_bf16 v[32:47], v[96:99], v[104:107], v[32:47]
	ds_read_b128 v[96:99], v79 offset:36864
	s_waitcnt lgkmcnt(0)
	v_mfma_f32_32x32x16_bf16 v[16:31], v[96:99], v[100:103], v[16:31]
	v_mfma_f32_32x32x16_bf16 v[0:15], v[96:99], v[104:107], v[0:15]
	ds_read_b128 v[96:99], v80 offset:32768
	ds_read_b128 v[100:103], v83 offset:49152
	ds_read_b128 v[104:107], v83 offset:53248
	s_waitcnt lgkmcnt(0)
	v_mfma_f32_32x32x16_bf16 v[48:63], v[96:99], v[100:103], v[48:63]
	v_mfma_f32_32x32x16_bf16 v[32:47], v[96:99], v[104:107], v[32:47]
	ds_read_b128 v[96:99], v80 offset:36864
	s_waitcnt lgkmcnt(0)
	v_mfma_f32_32x32x16_bf16 v[16:31], v[96:99], v[100:103], v[16:31]
	v_mfma_f32_32x32x16_bf16 v[0:15], v[96:99], v[104:107], v[0:15]
	ds_read_b128 v[148:151], v82 offset:32768
	ds_read_b128 v[156:159], v85 offset:49152
	ds_read_b128 v[208:211], v85 offset:53248
	ds_read_b128 v[152:155], v82 offset:36864
	ds_read_b128 v[96:99], v86 offset:32768
	ds_read_b128 v[100:103], v87 offset:49152
	ds_read_b128 v[104:107], v87 offset:53248
	ds_read_b128 v[144:147], v86 offset:36864
	s_waitcnt vmcnt(0)
	s_waitcnt vmcnt(0) lgkmcnt(0)
	s_barrier
; #define WAIT_V0() asm volatile("s_waitcnt vmcnt(0)" ::: "memory")
; DI void gemm_core(char* smem, int nk, const char* Ab, const char* Bb, const unsigned (&aoff)[4], const unsigned (&boff)[4],
;                   f32x16 (&acc)[2][2]) {
;     ...
;   auto stage = [&](int buf, int kt) __attribute__((always_inline)) {
;     const char* ak = Ab + kt * 128;
;     const char* bk = Bb + kt * 128;
;     char* sa = smem + buf * STAGE_B + w * 4096;
; #pragma unroll
;     for (int i = 0; i < 4; ++i) {
;       __builtin_amdgcn_global_load_lds((const unsigned*)(ak + aoff[i]), (unsigned*)(sa + i * 1024), 16, 0, 0);
;       __builtin_amdgcn_global_load_lds((const unsigned*)(bk + boff[i]), (unsigned*)(sa + 16384 + i * 1024), 16, 0, 0);
;     }
;   };
;   stage(0, 0);
;   WAIT_V0();
;   __syncthreads();
;   for (int kt = 0; kt < nk; ++kt) {
;     const int cur = kt & 1;
;     if (kt + 1 < nk) stage(cur ^ 1, kt + 1);
;     const char* sb = smem + cur * STAGE_B;
; #pragma unroll
;     for (int ks = 0; ks < 4; ++ks) {
;       bf16x8 af[2], bfr[2];
; #pragma unroll
;       for (int mb = 0; mb < 2; ++mb) af[mb] = *(const bf16x8*)(sb + a_base + mb * 4096 + xo[ks]);
; #pragma unroll
;       for (int nb = 0; nb < 2; ++nb) bfr[nb] = *(const bf16x8*)(sb + b_base + nb * 4096 + xo[ks]);
; #pragma unroll
;       for (int mb = 0; mb < 2; ++mb)
; #pragma unroll
;         for (int nb = 0; nb < 2; ++nb)
;           acc[mb][nb] = __builtin_amdgcn_mfma_f32_32x32x16_bf16(af[mb], bfr[nb], acc[mb][nb], 0, 0, 0);
;     }
;     WAIT_V0();
;     __syncthreads();
;   }
	v_mfma_f32_32x32x16_bf16 v[48:63], v[148:151], v[156:159], v[48:63]
	v_mfma_f32_32x32x16_bf16 v[32:47], v[148:151], v[208:211], v[32:47]
	v_mfma_f32_32x32x16_bf16 v[16:31], v[152:155], v[156:159], v[16:31]
	v_mfma_f32_32x32x16_bf16 v[0:15], v[152:155], v[208:211], v[0:15]
	v_mfma_f32_32x32x16_bf16 v[48:63], v[96:99], v[100:103], v[48:63]
	v_mfma_f32_32x32x16_bf16 v[32:47], v[96:99], v[104:107], v[32:47]
	v_mfma_f32_32x32x16_bf16 v[16:31], v[144:147], v[100:103], v[16:31]
	v_mfma_f32_32x32x16_bf16 v[0:15], v[144:147], v[104:107], v[0:15]
	v_lshl_add_u64 v[96:97], v[64:65], 0, s[4:5]
	global_load_lds_dwordx4 v[96:97], off
	s_mov_b32 m0, s85
	s_nop 0
	global_load_lds_dwordx4 v76, s[58:59]
	s_mov_b32 m0, s86
	s_nop 0
	global_load_lds_dwordx4 v[88:89], off
	s_mov_b32 m0, s87
	v_lshl_add_u64 v[88:89], v[68:69], 0, s[4:5]
	global_load_lds_dwordx4 v77, s[58:59]
	s_mov_b32 m0, s88
	s_nop 0
	global_load_lds_dwordx4 v[88:89], off
	s_mov_b32 m0, s89
	v_lshl_add_u64 v[88:89], v[70:71], 0, s[4:5]
	global_load_lds_dwordx4 v78, s[58:59]
	s_mov_b32 m0, s90
	s_mov_b64 s[4:5], 0x600
	global_load_lds_dwordx4 v[88:89], off
	s_mov_b32 m0, s91
	s_nop 0
	global_load_lds_dwordx4 v84, s[58:59]
	ds_read_b128 v[88:91], v79
	ds_read_b128 v[92:95], v81 offset:16384
	ds_read_b128 v[96:99], v81 offset:20480
	s_waitcnt lgkmcnt(0)
	v_mfma_f32_32x32x16_bf16 v[48:63], v[88:91], v[92:95], v[48:63]
	s_mov_b32 m0, s18
	v_mfma_f32_32x32x16_bf16 v[32:47], v[88:91], v[96:99], v[32:47]
	ds_read_b128 v[88:91], v79 offset:4096
	s_waitcnt lgkmcnt(0)
	v_mfma_f32_32x32x16_bf16 v[16:31], v[88:91], v[92:95], v[16:31]
	v_mfma_f32_32x32x16_bf16 v[0:15], v[88:91], v[96:99], v[0:15]
	ds_read_b128 v[88:91], v80
	ds_read_b128 v[92:95], v83 offset:16384
	ds_read_b128 v[96:99], v83 offset:20480
	s_waitcnt lgkmcnt(0)
	v_mfma_f32_32x32x16_bf16 v[48:63], v[88:91], v[92:95], v[48:63]
	v_mfma_f32_32x32x16_bf16 v[32:47], v[88:91], v[96:99], v[32:47]
	ds_read_b128 v[88:91], v80 offset:4096
	s_waitcnt lgkmcnt(0)
	v_mfma_f32_32x32x16_bf16 v[16:31], v[88:91], v[92:95], v[16:31]
	v_mfma_f32_32x32x16_bf16 v[0:15], v[88:91], v[96:99], v[0:15]
	ds_read_b128 v[148:151], v82
	ds_read_b128 v[156:159], v85 offset:16384
	ds_read_b128 v[208:211], v85 offset:20480
	ds_read_b128 v[152:155], v82 offset:4096
	ds_read_b128 v[88:91], v86
	ds_read_b128 v[92:95], v87 offset:16384
	ds_read_b128 v[96:99], v87 offset:20480
	ds_read_b128 v[144:147], v86 offset:4096
	s_waitcnt vmcnt(0)
	s_waitcnt vmcnt(0) lgkmcnt(0)
	s_barrier
	v_mfma_f32_32x32x16_bf16 v[48:63], v[148:151], v[156:159], v[48:63]
	v_lshl_add_u64 v[140:141], v[64:65], 0, s[4:5]
	global_load_lds_dwordx4 v[140:141], off
	v_mfma_f32_32x32x16_bf16 v[32:47], v[148:151], v[208:211], v[32:47]
	s_mov_b32 m0, s19
	v_lshl_add_u64 v[142:143], v[66:67], 0, s[4:5]
	global_load_lds_dwordx4 v76, s[60:61]
	v_mfma_f32_32x32x16_bf16 v[16:31], v[152:155], v[156:159], v[16:31]
	s_mov_b32 m0, s22
	s_nop 0
	global_load_lds_dwordx4 v[142:143], off
	v_mfma_f32_32x32x16_bf16 v[0:15], v[152:155], v[208:211], v[0:15]
	s_mov_b32 m0, s23
	v_lshl_add_u64 v[140:141], v[68:69], 0, s[4:5]
	global_load_lds_dwordx4 v77, s[60:61]
	v_mfma_f32_32x32x16_bf16 v[48:63], v[88:91], v[92:95], v[48:63]
	s_mov_b32 m0, s29
	s_nop 0
	global_load_lds_dwordx4 v[140:141], off
	v_mfma_f32_32x32x16_bf16 v[32:47], v[88:91], v[96:99], v[32:47]
	s_mov_b32 m0, s69
	v_lshl_add_u64 v[142:143], v[70:71], 0, s[4:5]
	global_load_lds_dwordx4 v78, s[60:61]
	v_mfma_f32_32x32x16_bf16 v[16:31], v[144:147], v[92:95], v[16:31]
	s_mov_b32 m0, s70
	s_mov_b64 s[4:5], 0x680
	global_load_lds_dwordx4 v[142:143], off
	v_mfma_f32_32x32x16_bf16 v[0:15], v[144:147], v[96:99], v[0:15]
	s_mov_b32 m0, s71
	s_nop 0
	global_load_lds_dwordx4 v84, s[60:61]
	ds_read_b128 v[88:91], v79 offset:32768
	ds_read_b128 v[92:95], v81 offset:49152
	ds_read_b128 v[96:99], v81 offset:53248
	s_waitcnt lgkmcnt(0)
	v_mfma_f32_32x32x16_bf16 v[48:63], v[88:91], v[92:95], v[48:63]
	s_mov_b32 m0, s84
	v_mfma_f32_32x32x16_bf16 v[32:47], v[88:91], v[96:99], v[32:47]
	ds_read_b128 v[88:91], v79 offset:36864
	s_waitcnt lgkmcnt(0)
	v_mfma_f32_32x32x16_bf16 v[16:31], v[88:91], v[92:95], v[16:31]
	v_mfma_f32_32x32x16_bf16 v[0:15], v[88:91], v[96:99], v[0:15]
	ds_read_b128 v[88:91], v80 offset:32768
	ds_read_b128 v[92:95], v83 offset:49152
	ds_read_b128 v[96:99], v83 offset:53248
	s_waitcnt lgkmcnt(0)
	v_mfma_f32_32x32x16_bf16 v[48:63], v[88:91], v[92:95], v[48:63]
	v_mfma_f32_32x32x16_bf16 v[32:47], v[88:91], v[96:99], v[32:47]
	ds_read_b128 v[88:91], v80 offset:36864
	s_waitcnt lgkmcnt(0)
	v_mfma_f32_32x32x16_bf16 v[16:31], v[88:91], v[92:95], v[16:31]
	v_mfma_f32_32x32x16_bf16 v[0:15], v[88:91], v[96:99], v[0:15]
	ds_read_b128 v[148:151], v82 offset:32768
	ds_read_b128 v[156:159], v85 offset:49152
	ds_read_b128 v[208:211], v85 offset:53248
	ds_read_b128 v[152:155], v82 offset:36864
	ds_read_b128 v[88:91], v86 offset:32768
	ds_read_b128 v[92:95], v87 offset:49152
	ds_read_b128 v[96:99], v87 offset:53248
	ds_read_b128 v[144:147], v86 offset:36864
	s_waitcnt vmcnt(0)
	s_waitcnt vmcnt(0) lgkmcnt(0)
	s_barrier
; #define WAIT_V0() asm volatile("s_waitcnt vmcnt(0)" ::: "memory")
; DI void gemm_core(char* smem, int nk, const char* Ab, const char* Bb, const unsigned (&aoff)[4], const unsigned (&boff)[4],
;                   f32x16 (&acc)[2][2]) {
;     ...
;   auto stage = [&](int buf, int kt) __attribute__((always_inline)) {
;     const char* ak = Ab + kt * 128;
;     const char* bk = Bb + kt * 128;
;     char* sa = smem + buf * STAGE_B + w * 4096;
; #pragma unroll
;     for (int i = 0; i < 4; ++i) {
;       __builtin_amdgcn_global_load_lds((const unsigned*)(ak + aoff[i]), (unsigned*)(sa + i * 1024), 16, 0, 0);
;       __builtin_amdgcn_global_load_lds((const unsigned*)(bk + boff[i]), (unsigned*)(sa + 16384 + i * 1024), 16, 0, 0);
;     }
;   };
;   stage(0, 0);
;   WAIT_V0();
;   __syncthreads();
;   for (int kt = 0; kt < nk; ++kt) {
;     const int cur = kt & 1;
;     if (kt + 1 < nk) stage(cur ^ 1, kt + 1);
;     const char* sb = smem + cur * STAGE_B;
; #pragma unroll
;     for (int ks = 0; ks < 4; ++ks) {
;       bf16x8 af[2], bfr[2];
; #pragma unroll
;       for (int mb = 0; mb < 2; ++mb) af[mb] = *(const bf16x8*)(sb + a_base + mb * 4096 + xo[ks]);
; #pragma unroll
;       for (int nb = 0; nb < 2; ++nb) bfr[nb] = *(const bf16x8*)(sb + b_base + nb * 4096 + xo[ks]);
; #pragma unroll
;       for (int mb = 0; mb < 2; ++mb)
; #pragma unroll
;         for (int nb = 0; nb < 2; ++nb)
;           acc[mb][nb] = __builtin_amdgcn_mfma_f32_32x32x16_bf16(af[mb], bfr[nb], acc[mb][nb], 0, 0, 0);
;     }
;     WAIT_V0();
;     __syncthreads();
;   }
	v_mfma_f32_32x32x16_bf16 v[48:63], v[148:151], v[156:159], v[48:63]
	v_lshl_add_u64 v[140:141], v[64:65], 0, s[4:5]
	global_load_lds_dwordx4 v[140:141], off
	v_mfma_f32_32x32x16_bf16 v[32:47], v[148:151], v[208:211], v[32:47]
	s_mov_b32 m0, s85
	v_lshl_add_u64 v[142:143], v[66:67], 0, s[4:5]
	global_load_lds_dwordx4 v76, s[62:63]
	v_mfma_f32_32x32x16_bf16 v[16:31], v[152:155], v[156:159], v[16:31]
	s_mov_b32 m0, s86
	s_nop 0
	global_load_lds_dwordx4 v[142:143], off
	v_mfma_f32_32x32x16_bf16 v[0:15], v[152:155], v[208:211], v[0:15]
	s_mov_b32 m0, s87
	v_lshl_add_u64 v[140:141], v[68:69], 0, s[4:5]
	global_load_lds_dwordx4 v77, s[62:63]
	v_mfma_f32_32x32x16_bf16 v[48:63], v[88:91], v[92:95], v[48:63]
	s_mov_b32 m0, s88
	s_nop 0
	global_load_lds_dwordx4 v[140:141], off
	v_mfma_f32_32x32x16_bf16 v[32:47], v[88:91], v[96:99], v[32:47]
	s_mov_b32 m0, s89
	v_lshl_add_u64 v[142:143], v[70:71], 0, s[4:5]
	global_load_lds_dwordx4 v78, s[62:63]
	v_mfma_f32_32x32x16_bf16 v[16:31], v[144:147], v[92:95], v[16:31]
	s_mov_b32 m0, s90
	s_mov_b64 s[4:5], 0x700
	global_load_lds_dwordx4 v[142:143], off
	v_mfma_f32_32x32x16_bf16 v[0:15], v[144:147], v[96:99], v[0:15]
	s_mov_b32 m0, s91
	s_nop 0
	global_load_lds_dwordx4 v84, s[62:63]
	ds_read_b128 v[88:91], v79
	ds_read_b128 v[92:95], v81 offset:16384
	ds_read_b128 v[96:99], v81 offset:20480
	s_waitcnt lgkmcnt(0)
	v_mfma_f32_32x32x16_bf16 v[48:63], v[88:91], v[92:95], v[48:63]
	s_mov_b32 m0, s18
	v_mfma_f32_32x32x16_bf16 v[32:47], v[88:91], v[96:99], v[32:47]
	ds_read_b128 v[88:91], v79 offset:4096
	s_waitcnt lgkmcnt(0)
	v_mfma_f32_32x32x16_bf16 v[16:31], v[88:91], v[92:95], v[16:31]
	v_mfma_f32_32x32x16_bf16 v[0:15], v[88:91], v[96:99], v[0:15]
	ds_read_b128 v[88:91], v80
	ds_read_b128 v[92:95], v83 offset:16384
	ds_read_b128 v[96:99], v83 offset:20480
	s_waitcnt lgkmcnt(0)
	v_mfma_f32_32x32x16_bf16 v[48:63], v[88:91], v[92:95], v[48:63]
	v_mfma_f32_32x32x16_bf16 v[32:47], v[88:91], v[96:99], v[32:47]
	ds_read_b128 v[88:91], v80 offset:4096
	s_waitcnt lgkmcnt(0)
	v_mfma_f32_32x32x16_bf16 v[16:31], v[88:91], v[92:95], v[16:31]
	v_mfma_f32_32x32x16_bf16 v[0:15], v[88:91], v[96:99], v[0:15]
	ds_read_b128 v[148:151], v82
	ds_read_b128 v[156:159], v85 offset:16384
	ds_read_b128 v[208:211], v85 offset:20480
	ds_read_b128 v[152:155], v82 offset:4096
	ds_read_b128 v[88:91], v86
	ds_read_b128 v[92:95], v87 offset:16384
	ds_read_b128 v[96:99], v87 offset:20480
	ds_read_b128 v[144:147], v86 offset:4096
	s_waitcnt vmcnt(0)
	s_waitcnt vmcnt(0) lgkmcnt(0)
	s_barrier
	v_mfma_f32_32x32x16_bf16 v[48:63], v[148:151], v[156:159], v[48:63]
	v_mfma_f32_32x32x16_bf16 v[32:47], v[148:151], v[208:211], v[32:47]
	v_mfma_f32_32x32x16_bf16 v[16:31], v[152:155], v[156:159], v[16:31]
	v_mfma_f32_32x32x16_bf16 v[0:15], v[152:155], v[208:211], v[0:15]
	v_mfma_f32_32x32x16_bf16 v[48:63], v[88:91], v[92:95], v[48:63]
	v_mfma_f32_32x32x16_bf16 v[32:47], v[88:91], v[96:99], v[32:47]
	v_mfma_f32_32x32x16_bf16 v[16:31], v[144:147], v[92:95], v[16:31]
	v_mfma_f32_32x32x16_bf16 v[0:15], v[144:147], v[96:99], v[0:15]
	v_lshl_add_u64 v[88:89], v[64:65], 0, s[4:5]
	global_load_lds_dwordx4 v[88:89], off
	s_mov_b32 m0, s19
	v_lshl_add_u64 v[88:89], v[66:67], 0, s[4:5]
	global_load_lds_dwordx4 v76, s[64:65]
	s_mov_b32 m0, s22
	s_nop 0
	global_load_lds_dwordx4 v[88:89], off
	s_mov_b32 m0, s23
	v_lshl_add_u64 v[88:89], v[68:69], 0, s[4:5]
	global_load_lds_dwordx4 v77, s[64:65]
	s_mov_b32 m0, s29
	s_nop 0
	global_load_lds_dwordx4 v[88:89], off
	s_mov_b32 m0, s69
	v_lshl_add_u64 v[88:89], v[70:71], 0, s[4:5]
	global_load_lds_dwordx4 v78, s[64:65]
	s_mov_b32 m0, s70
	s_mov_b64 s[4:5], 0x780
	global_load_lds_dwordx4 v[88:89], off
	s_mov_b32 m0, s71
	v_lshl_add_u64 v[64:65], v[64:65], 0, s[4:5]
	global_load_lds_dwordx4 v84, s[64:65]
	ds_read_b128 v[88:91], v79 offset:32768
	ds_read_b128 v[92:95], v81 offset:49152
	ds_read_b128 v[96:99], v81 offset:53248
	s_waitcnt lgkmcnt(0)
	v_mfma_f32_32x32x16_bf16 v[48:63], v[88:91], v[92:95], v[48:63]
	s_mov_b32 m0, s84
	s_movk_i32 s4, 0x4000
	v_mfma_f32_32x32x16_bf16 v[32:47], v[88:91], v[96:99], v[32:47]
	ds_read_b128 v[88:91], v79 offset:36864
	s_waitcnt lgkmcnt(0)
	v_mfma_f32_32x32x16_bf16 v[16:31], v[88:91], v[92:95], v[16:31]
	v_mfma_f32_32x32x16_bf16 v[0:15], v[88:91], v[96:99], v[0:15]
	ds_read_b128 v[88:91], v80 offset:32768
	ds_read_b128 v[92:95], v83 offset:49152
	ds_read_b128 v[96:99], v83 offset:53248
	s_waitcnt lgkmcnt(0)
	v_mfma_f32_32x32x16_bf16 v[48:63], v[88:91], v[92:95], v[48:63]
	v_mfma_f32_32x32x16_bf16 v[32:47], v[88:91], v[96:99], v[32:47]
	ds_read_b128 v[88:91], v80 offset:36864
	s_waitcnt lgkmcnt(0)
	v_mfma_f32_32x32x16_bf16 v[16:31], v[88:91], v[92:95], v[16:31]
	v_mfma_f32_32x32x16_bf16 v[0:15], v[88:91], v[96:99], v[0:15]
	ds_read_b128 v[88:91], v82 offset:32768
	ds_read_b128 v[92:95], v85 offset:49152
	ds_read_b128 v[96:99], v85 offset:53248
	s_waitcnt lgkmcnt(0)
	v_mfma_f32_32x32x16_bf16 v[48:63], v[88:91], v[92:95], v[48:63]
	v_mfma_f32_32x32x16_bf16 v[32:47], v[88:91], v[96:99], v[32:47]
	ds_read_b128 v[88:91], v82 offset:36864
	s_waitcnt lgkmcnt(0)
	v_mfma_f32_32x32x16_bf16 v[16:31], v[88:91], v[92:95], v[16:31]
	v_mfma_f32_32x32x16_bf16 v[0:15], v[88:91], v[96:99], v[0:15]
	ds_read_b128 v[88:91], v86 offset:32768
	ds_read_b128 v[92:95], v87 offset:49152
	ds_read_b128 v[96:99], v87 offset:53248
	s_waitcnt lgkmcnt(0)
	v_mfma_f32_32x32x16_bf16 v[48:63], v[88:91], v[92:95], v[48:63]
	v_mfma_f32_32x32x16_bf16 v[32:47], v[88:91], v[96:99], v[32:47]
	ds_read_b128 v[88:91], v86 offset:36864
	s_waitcnt vmcnt(0)
	s_waitcnt vmcnt(0) lgkmcnt(0)
	s_barrier
; #define WAIT_V0() asm volatile("s_waitcnt vmcnt(0)" ::: "memory")
; DI void gemm_core(char* smem, int nk, const char* Ab, const char* Bb, const unsigned (&aoff)[4], const unsigned (&boff)[4],
;                   f32x16 (&acc)[2][2]) {
;     ...
;   auto stage = [&](int buf, int kt) __attribute__((always_inline)) {
;     const char* ak = Ab + kt * 128;
;     const char* bk = Bb + kt * 128;
;     char* sa = smem + buf * STAGE_B + w * 4096;
; #pragma unroll
;     for (int i = 0; i < 4; ++i) {
;       __builtin_amdgcn_global_load_lds((const unsigned*)(ak + aoff[i]), (unsigned*)(sa + i * 1024), 16, 0, 0);
;       __builtin_amdgcn_global_load_lds((const unsigned*)(bk + boff[i]), (unsigned*)(sa + 16384 + i * 1024), 16, 0, 0);
;     }
;   };
;   stage(0, 0);
;   WAIT_V0();
;   __syncthreads();
;   for (int kt = 0; kt < nk; ++kt) {
;     const int cur = kt & 1;
;     if (kt + 1 < nk) stage(cur ^ 1, kt + 1);
;     const char* sb = smem + cur * STAGE_B;
; #pragma unroll
;     for (int ks = 0; ks < 4; ++ks) {
;       bf16x8 af[2], bfr[2];
; #pragma unroll
;       for (int mb = 0; mb < 2; ++mb) af[mb] = *(const bf16x8*)(sb + a_base + mb * 4096 + xo[ks]);
; #pragma unroll
;       for (int nb = 0; nb < 2; ++nb) bfr[nb] = *(const bf16x8*)(sb + b_base + nb * 4096 + xo[ks]);
; #pragma unroll
;       for (int mb = 0; mb < 2; ++mb)
; #pragma unroll
;         for (int nb = 0; nb < 2; ++nb)
;           acc[mb][nb] = __builtin_amdgcn_mfma_f32_32x32x16_bf16(af[mb], bfr[nb], acc[mb][nb], 0, 0, 0);
;     }
;     WAIT_V0();
;     __syncthreads();
;   }
	global_load_lds_dwordx4 v[64:65], off
	s_mov_b32 m0, s85
	v_lshl_add_u64 v[64:65], v[66:67], 0, s[6:7]
	global_load_lds_dwordx4 v76, s[66:67]
	s_mov_b32 m0, s86
	v_mfma_f32_32x32x16_bf16 v[16:31], v[88:91], v[92:95], v[16:31]
	global_load_lds_dwordx4 v[64:65], off
	s_mov_b32 m0, s87
	v_lshl_add_u64 v[64:65], v[68:69], 0, s[6:7]
	global_load_lds_dwordx4 v77, s[66:67]
	s_mov_b32 m0, s88
	v_mfma_f32_32x32x16_bf16 v[0:15], v[88:91], v[96:99], v[0:15]
	global_load_lds_dwordx4 v[64:65], off
	s_mov_b32 m0, s89
	v_lshl_add_u64 v[64:65], v[70:71], 0, s[6:7]
	global_load_lds_dwordx4 v78, s[66:67]
	s_mov_b32 m0, s90
	v_readlane_b32 s86, v254, 58
	global_load_lds_dwordx4 v[64:65], off
	s_mov_b32 m0, s91
	v_readlane_b32 s87, v254, 59
	global_load_lds_dwordx4 v84, s[66:67]
	ds_read_b128 v[64:67], v79
	ds_read_b128 v[68:71], v81 offset:16384
	ds_read_b128 v[88:91], v81 offset:20480
	s_waitcnt lgkmcnt(0)
	v_mfma_f32_32x32x16_bf16 v[48:63], v[64:67], v[68:71], v[48:63]
	v_mfma_f32_32x32x16_bf16 v[32:47], v[64:67], v[88:91], v[32:47]
	ds_read_b128 v[64:67], v79 offset:4096
	s_waitcnt lgkmcnt(0)
	v_mfma_f32_32x32x16_bf16 v[16:31], v[64:67], v[68:71], v[16:31]
	v_mfma_f32_32x32x16_bf16 v[0:15], v[64:67], v[88:91], v[0:15]
	ds_read_b128 v[64:67], v80
	ds_read_b128 v[68:71], v83 offset:16384
	ds_read_b128 v[88:91], v83 offset:20480
	s_waitcnt lgkmcnt(0)
	v_mfma_f32_32x32x16_bf16 v[48:63], v[64:67], v[68:71], v[48:63]
	v_mfma_f32_32x32x16_bf16 v[32:47], v[64:67], v[88:91], v[32:47]
	ds_read_b128 v[64:67], v80 offset:4096
	s_waitcnt lgkmcnt(0)
	v_mfma_f32_32x32x16_bf16 v[16:31], v[64:67], v[68:71], v[16:31]
	v_mfma_f32_32x32x16_bf16 v[0:15], v[64:67], v[88:91], v[0:15]
	ds_read_b128 v[148:151], v82
	ds_read_b128 v[156:159], v85 offset:16384
	ds_read_b128 v[208:211], v85 offset:20480
	ds_read_b128 v[152:155], v82 offset:4096
	ds_read_b128 v[64:67], v86
	ds_read_b128 v[68:71], v87 offset:16384
	ds_read_b128 v[88:91], v87 offset:20480
	ds_read_b128 v[144:147], v86 offset:4096
	s_waitcnt vmcnt(0)
	s_waitcnt vmcnt(0) lgkmcnt(0)
	s_barrier
	v_mfma_f32_32x32x16_bf16 v[48:63], v[148:151], v[156:159], v[48:63]
	v_mfma_f32_32x32x16_bf16 v[32:47], v[148:151], v[208:211], v[32:47]
	v_mfma_f32_32x32x16_bf16 v[16:31], v[152:155], v[156:159], v[16:31]
	v_mfma_f32_32x32x16_bf16 v[0:15], v[152:155], v[208:211], v[0:15]
	v_mfma_f32_32x32x16_bf16 v[48:63], v[64:67], v[68:71], v[48:63]
	v_mfma_f32_32x32x16_bf16 v[32:47], v[64:67], v[88:91], v[32:47]
	v_mfma_f32_32x32x16_bf16 v[16:31], v[144:147], v[68:71], v[16:31]
	v_mfma_f32_32x32x16_bf16 v[0:15], v[144:147], v[88:91], v[0:15]
	ds_read_b128 v[64:67], v79 offset:32768
	ds_read_b128 v[68:71], v81 offset:49152
	ds_read_b128 v[88:91], v81 offset:53248
	s_waitcnt lgkmcnt(1)
	v_mfma_f32_32x32x16_bf16 v[48:63], v[64:67], v[68:71], v[48:63]
	s_waitcnt lgkmcnt(0)
	v_mfma_f32_32x32x16_bf16 v[32:47], v[64:67], v[88:91], v[32:47]
	ds_read_b128 v[64:67], v79 offset:36864
	s_waitcnt lgkmcnt(0)
	v_mfma_f32_32x32x16_bf16 v[16:31], v[64:67], v[68:71], v[16:31]
	v_mfma_f32_32x32x16_bf16 v[0:15], v[64:67], v[88:91], v[0:15]
	ds_read_b128 v[64:67], v80 offset:32768
	ds_read_b128 v[68:71], v83 offset:49152
	ds_read_b128 v[76:79], v83 offset:53248
	s_waitcnt lgkmcnt(1)
	v_mfma_f32_32x32x16_bf16 v[48:63], v[64:67], v[68:71], v[48:63]
	s_waitcnt lgkmcnt(0)
	v_mfma_f32_32x32x16_bf16 v[32:47], v[64:67], v[76:79], v[32:47]
	ds_read_b128 v[64:67], v80 offset:36864
	s_waitcnt lgkmcnt(0)
	v_mfma_f32_32x32x16_bf16 v[16:31], v[64:67], v[68:71], v[16:31]
	v_mfma_f32_32x32x16_bf16 v[0:15], v[64:67], v[76:79], v[0:15]
	ds_read_b128 v[64:67], v82 offset:32768
	ds_read_b128 v[68:71], v85 offset:49152
	ds_read_b128 v[76:79], v85 offset:53248
	s_waitcnt lgkmcnt(1)
	v_mfma_f32_32x32x16_bf16 v[48:63], v[64:67], v[68:71], v[48:63]
	s_waitcnt lgkmcnt(0)
	v_mfma_f32_32x32x16_bf16 v[32:47], v[64:67], v[76:79], v[32:47]
	ds_read_b128 v[64:67], v82 offset:36864
	s_waitcnt lgkmcnt(0)
	v_mfma_f32_32x32x16_bf16 v[16:31], v[64:67], v[68:71], v[16:31]
	ds_read_b128 v[68:71], v87 offset:53248
	ds_read_b128 v[80:83], v87 offset:49152
	ds_read_b128 v[88:91], v86 offset:36864
	ds_read_b128 v[84:87], v86 offset:32768
	s_waitcnt vmcnt(0)
	s_waitcnt lgkmcnt(0)
	s_barrier
; DI void phase_up(const Params& P, int layer, char* smem) {
;     ...
;     epi_foreach(acc, [&](int row, int col, float v) __attribute__((always_inline)) { Cs[row * 136 + col] = f2bf(v); });
;     __syncthreads();
;     {
;       const int col = tid & 63, rb = tid >> 6;
;       const int cv = nt * 64 + col, cg_ = DFF + nt * 64 + col;
;       const float w0v = cw[cv], w1v = cw[5632 + cv], w2v = cw[2 * 5632 + cv], bv = cb[cv];
;       const float w0g = cw[cg_], w1g = cw[5632 + cg_], w2g = cw[2 * 5632 + cg_], bgt = cb[cg_];
;       for (int r = 2 + rb; r < 128; r += 4) {
	v_mfma_f32_32x32x16_bf16 v[48:63], v[84:87], v[80:83], v[48:63]
	v_mfma_f32_32x32x16_bf16 v[0:15], v[64:67], v[76:79], v[0:15]
	v_mov_b32_e32 v64, v161
	v_mov_b32_e32 v65, v161
	v_lshrrev_b32_e32 v67, 3, v64
	v_and_b32_e32 v67, 4, v67
	v_lshrrev_b32_e32 v66, 1, v65
	v_and_b32_e32 v64, 31, v64
	v_and_or_b32 v64, v65, 64, v64
	v_and_or_b32 v65, v66, s3, v67
	v_mul_lo_u32 v65, v65, s97
	s_nop 1
	v_cvt_pk_bf16_f32 v48, v48, s0
	v_lshl_add_u32 v64, v64, 1, v65
	ds_write_b16 v64, v48
	v_cvt_pk_bf16_f32 v48, v49, s0
	ds_write_b16 v64, v48 offset:272
	v_cvt_pk_bf16_f32 v48, v50, s0
	ds_write_b16 v64, v48 offset:544
	v_cvt_pk_bf16_f32 v48, v51, s0
	ds_write_b16 v64, v48 offset:816
	v_cvt_pk_bf16_f32 v48, v52, s0
	ds_write_b16 v64, v48 offset:2176
	v_cvt_pk_bf16_f32 v48, v53, s0
	ds_write_b16 v64, v48 offset:2448
	v_cvt_pk_bf16_f32 v48, v54, s0
	ds_write_b16 v64, v48 offset:2720
	v_cvt_pk_bf16_f32 v48, v55, s0
	v_mfma_f32_32x32x16_bf16 v[32:47], v[84:87], v[68:71], v[32:47]
	ds_write_b16 v64, v48 offset:2992
	v_mfma_f32_32x32x16_bf16 v[16:31], v[88:91], v[80:83], v[16:31]
	v_mfma_f32_32x32x16_bf16 v[0:15], v[88:91], v[68:71], v[0:15]
	v_cvt_pk_bf16_f32 v48, v56, s0
	ds_write_b16 v64, v48 offset:4352
	v_cvt_pk_bf16_f32 v48, v57, s0
	ds_write_b16 v64, v48 offset:4624
	v_cvt_pk_bf16_f32 v48, v58, s0
	ds_write_b16 v64, v48 offset:4896
	v_cvt_pk_bf16_f32 v48, v59, s0
	ds_write_b16 v64, v48 offset:5168
	v_cvt_pk_bf16_f32 v48, v60, s0
	ds_write_b16 v64, v48 offset:6528
	v_cvt_pk_bf16_f32 v48, v61, s0
	ds_write_b16 v64, v48 offset:6800
	v_cvt_pk_bf16_f32 v48, v62, s0
	ds_write_b16 v64, v48 offset:7072
	v_cvt_pk_bf16_f32 v48, v63, s0
	ds_write_b16 v64, v48 offset:7344
	v_cvt_pk_bf16_f32 v32, v32, s0
	ds_write_b16 v64, v32 offset:64
	v_cvt_pk_bf16_f32 v32, v33, s0
	ds_write_b16 v64, v32 offset:336
	v_cvt_pk_bf16_f32 v32, v34, s0
	ds_write_b16 v64, v32 offset:608
	v_cvt_pk_bf16_f32 v32, v35, s0
	ds_write_b16 v64, v32 offset:880
	v_cvt_pk_bf16_f32 v32, v36, s0
	ds_write_b16 v64, v32 offset:2240
	v_cvt_pk_bf16_f32 v32, v37, s0
	ds_write_b16 v64, v32 offset:2512
	v_cvt_pk_bf16_f32 v32, v38, s0
	ds_write_b16 v64, v32 offset:2784
	v_cvt_pk_bf16_f32 v32, v39, s0
	ds_write_b16 v64, v32 offset:3056
	v_cvt_pk_bf16_f32 v32, v40, s0
	ds_write_b16 v64, v32 offset:4416
	v_cvt_pk_bf16_f32 v32, v41, s0
	ds_write_b16 v64, v32 offset:4688
	v_cvt_pk_bf16_f32 v32, v42, s0
	ds_write_b16 v64, v32 offset:4960
	v_cvt_pk_bf16_f32 v32, v43, s0
	ds_write_b16 v64, v32 offset:5232
	v_cvt_pk_bf16_f32 v32, v44, s0
	ds_write_b16 v64, v32 offset:6592
	v_cvt_pk_bf16_f32 v32, v45, s0
	ds_write_b16 v64, v32 offset:6864
	v_cvt_pk_bf16_f32 v32, v46, s0
	ds_write_b16 v64, v32 offset:7136
	v_cvt_pk_bf16_f32 v32, v47, s0
	ds_write_b16 v64, v32 offset:7408
	v_cvt_pk_bf16_f32 v16, v16, s0
	ds_write_b16 v64, v16 offset:8704
	v_cvt_pk_bf16_f32 v16, v17, s0
	ds_write_b16 v64, v16 offset:8976
	v_cvt_pk_bf16_f32 v16, v18, s0
	ds_write_b16 v64, v16 offset:9248
	v_cvt_pk_bf16_f32 v16, v19, s0
	ds_write_b16 v64, v16 offset:9520
	v_cvt_pk_bf16_f32 v16, v20, s0
	ds_write_b16 v64, v16 offset:10880
	v_cvt_pk_bf16_f32 v16, v21, s0
	ds_write_b16 v64, v16 offset:11152
	v_cvt_pk_bf16_f32 v16, v22, s0
	ds_write_b16 v64, v16 offset:11424
	v_cvt_pk_bf16_f32 v16, v23, s0
	ds_write_b16 v64, v16 offset:11696
	v_cvt_pk_bf16_f32 v16, v24, s0
	ds_write_b16 v64, v16 offset:13056
	v_cvt_pk_bf16_f32 v16, v25, s0
	ds_write_b16 v64, v16 offset:13328
	v_cvt_pk_bf16_f32 v16, v26, s0
	ds_write_b16 v64, v16 offset:13600
	v_cvt_pk_bf16_f32 v16, v27, s0
	ds_write_b16 v64, v16 offset:13872
	v_cvt_pk_bf16_f32 v16, v28, s0
	ds_write_b16 v64, v16 offset:15232
	v_cvt_pk_bf16_f32 v16, v29, s0
	ds_write_b16 v64, v16 offset:15504
	v_cvt_pk_bf16_f32 v16, v30, s0
	ds_write_b16 v64, v16 offset:15776
	v_cvt_pk_bf16_f32 v16, v31, s0
	ds_write_b16 v64, v16 offset:16048
	v_cvt_pk_bf16_f32 v0, v0, s0
	ds_write_b16 v64, v0 offset:8768
	v_cvt_pk_bf16_f32 v0, v1, s0
	ds_write_b16 v64, v0 offset:9040
	v_cvt_pk_bf16_f32 v0, v2, s0
	ds_write_b16 v64, v0 offset:9312
	v_cvt_pk_bf16_f32 v0, v3, s0
	ds_write_b16 v64, v0 offset:9584
	v_cvt_pk_bf16_f32 v0, v4, s0
	ds_write_b16 v64, v0 offset:10944
	v_cvt_pk_bf16_f32 v0, v5, s0
	ds_write_b16 v64, v0 offset:11216
	v_cvt_pk_bf16_f32 v0, v6, s0
	ds_write_b16 v64, v0 offset:11488
	v_cvt_pk_bf16_f32 v0, v7, s0
	ds_write_b16 v64, v0 offset:11760
	v_cvt_pk_bf16_f32 v0, v8, s0
	ds_write_b16 v64, v0 offset:13120
	v_cvt_pk_bf16_f32 v0, v9, s0
	ds_write_b16 v64, v0 offset:13392
	v_cvt_pk_bf16_f32 v0, v10, s0
	ds_write_b16 v64, v0 offset:13664
	v_cvt_pk_bf16_f32 v0, v11, s0
	ds_write_b16 v64, v0 offset:13936
	v_cvt_pk_bf16_f32 v0, v12, s0
	ds_write_b16 v64, v0 offset:15296
	v_cvt_pk_bf16_f32 v0, v13, s0
	ds_write_b16 v64, v0 offset:15568
	v_cvt_pk_bf16_f32 v0, v14, s0
	ds_write_b16 v64, v0 offset:15840
	v_cvt_pk_bf16_f32 v0, v15, s0
	ds_write_b16 v64, v0 offset:16112
	s_waitcnt lgkmcnt(0)
	s_barrier
	s_and_saveexec_b64 s[18:19], s[40:41]
	s_mov_b32 s3, 0xb000
	s_cbranch_execz .LBB0_24
	v_add_u32_e32 v136, s21, v74
	v_lshlrev_b64 v[4:5], 2, v[136:137]
	v_lshl_add_u64 v[8:9], s[10:11], 0, v[4:5]
	v_or_b32_e32 v10, s21, v72
	v_lshlrev_b32_e32 v126, 1, v10
	v_lshl_add_u64 v[2:3], s[12:13], 0, v[4:5]
	v_add_co_u32_e32 v4, vcc, 0xb000, v8
	v_ashrrev_i32_e32 v11, 31, v10
	s_nop 0
	v_addc_co_u32_e32 v5, vcc, 0, v9, vcc
	v_lshl_add_u64 v[0:1], v[10:11], 1, s[86:87]
	v_add_co_u32_e32 v6, vcc, 0x5000, v8
	v_lshlrev_b64 v[10:11], 2, v[10:11]
	s_nop 0
	v_addc_co_u32_e32 v7, vcc, 0, v9, vcc
	v_lshl_add_u64 v[12:13], s[12:13], 0, v[10:11]
	v_lshl_add_u64 v[10:11], s[10:11], 0, v[10:11]
	global_load_dword v3, v[2:3], off
	s_mulk_i32 s20, 0x7e
	global_load_dword v5, v[4:5], off
	s_nop 0
	global_load_dword v7, v[6:7], off offset:2048
	s_nop 0
	global_load_dword v9, v[8:9], off
	s_mul_i32 s21, s68, 0x7a
	global_load_dword v2, v[12:13], off
	v_add_co_u32_e32 v12, vcc, s3, v10
	s_sub_i32 s29, s20, s21
	s_nop 0
	v_addc_co_u32_e32 v13, vcc, 0, v11, vcc
	global_load_dword v4, v[12:13], off
	v_add_co_u32_e32 v12, vcc, 0x5000, v10
	s_mov_b64 s[20:21], 0
	s_nop 0
	v_addc_co_u32_e32 v13, vcc, 0, v11, vcc
	global_load_dword v6, v[12:13], off offset:2048
	global_load_dword v8, v[10:11], off
	v_mov_b32_e32 v11, v73
	v_mul_u32_u24_e32 v10, 0x110, v73
	v_mov_b32_e32 v128, 0
	v_mov_b32_e32 v129, 0
	v_mov_b32_e32 v130, 0
	v_mov_b32_e32 v131, 0
	v_mov_b32_e32 v132, 0
	v_mov_b32_e32 v133, 0
	v_mov_b32_e32 v134, 0
	v_mov_b32_e32 v135, 0
	s_waitcnt vmcnt(0)
	v_readfirstlane_b32 s22, v73
	v_add_u32_e32 v10, v75, v10
	v_add_u32_e32 v127, 0x1600, v126
	s_lshl_b32 s22, s22, 1
	s_add_i32 s23, s29, s22
	s_mul_hi_i32 s21, s23, 0x1600
	s_mul_i32 s20, s23, 0x1600
	s_add_u32 s20, s20, s86
	s_addc_u32 s21, s21, s87
	s_branch .LBB0_28

; DI int glds_row(int i) { const int tid = ltid(); return ((tid >> 6) * 4 + i) * 8 + ((tid & 63) >> 3); }
; DI int glds_chunk(int row) { return (ltid() & 7) ^ ((row >> 1) & 7); }
; DI void gemm_tile(char* smem, int nk, const bf16* A, int lda, int m0, const bf16* Bt, int ldb, int n0, f32x16 (&acc)[2][2]) {
;   unsigned aoff[4], boff[4];
; #pragma unroll
;   for (int i = 0; i < 4; ++i) {
;     const int row = glds_row(i), ch = glds_chunk(row);
;     aoff[i] = (unsigned)((row * lda + ch * 8) * 2);
;     boff[i] = (unsigned)((row * ldb + ch * 8) * 2);
;   }
;   gemm_core(smem, nk, (const char*)(A + (size_t)m0 * lda), (const char*)(Bt + (size_t)n0 * ldb), aoff, boff, acc);
; DI void phase_gemm_in(const Params& P, int layer, char* smem) {
;     ...
;   for (int t0 = blockIdx.x; t0 < NT * MT; t0 += gridDim.x) {
;     const int tl = xcd_tile(t0, NT * MT) - (t0 & 7) * ((NT * MT) >> 3);
;     const int m0 = ((t0 & 3) * 64 + tl / 11) * 128, n0 = (((t0 & 7) >> 2) * 11 + tl % 11) * 128;
;     f32x16 acc[2][2];
;     gemm_tile(smem, 16, hn, 1024, m0, wt, 1024, n0, acc);
.LBB0_436:
	v_mov_b32_e32 v0, v161
	s_ashr_i32 s0, s14, 3
	v_lshrrev_b32_e32 v1, 1, v0
	v_lshrrev_b32_e32 v2, 3, v0
	v_bfe_u32 v0, v0, 3, 3
	v_and_or_b32 v0, v1, s9, v0
	v_mov_b32_e32 v1, v161
	v_bfe_u32 v2, v2, 1, 2
	v_xor_b32_e32 v1, v2, v1
	v_lshlrev_b32_e32 v0, 11, v0
	v_lshlrev_b32_e32 v1, 4, v1
	v_and_or_b32 v136, v1, s92, v0
	v_mov_b32_e32 v0, v161
	s_and_b32 s1, s0, 0xffffffc0
	v_ashrrev_i32_e32 v1, 1, v0
	v_and_b32_e32 v1, 0xffffffe0, v1
	v_bfe_u32 v0, v0, 3, 3
	v_or3_b32 v0, v0, v1, 8
	v_mov_b32_e32 v1, v161
	v_lshrrev_b32_e32 v2, 1, v0
	v_xor_b32_e32 v1, v2, v1
	v_lshlrev_b32_e32 v0, 11, v0
	v_lshlrev_b32_e32 v1, 4, v1
	v_and_or_b32 v0, v1, s92, v0
	v_mov_b32_e32 v1, v161
	s_lshl_b32 s10, s0, 1
	v_lshrrev_b32_e32 v2, 1, v1
	v_lshrrev_b32_e32 v3, 3, v1
	v_bfe_u32 v1, v1, 3, 3
	v_and_or_b32 v1, v2, s9, v1
	v_mov_b32_e32 v2, v161
	s_bfe_u32 s11, s0, 0x10005
	v_bfe_u32 v3, v3, 1, 2
	s_and_b32 s10, s10, 62
	s_or_b32 s1, s11, s1
	v_xor_b32_e32 v2, v3, v2
	s_or_b32 s1, s1, s10
	s_or_b32 s10, s0, 63
	v_lshlrev_b32_e32 v2, 4, v2
	s_cmpk_lt_i32 s10, 0x2c0
	v_lshlrev_b32_e32 v1, 11, v1
	v_and_b32_e32 v2, 0x70, v2
	s_cselect_b32 s1, s1, s0
	v_or3_b32 v2, v1, v2, s8
	v_mov_b32_e32 v1, v161
	s_mul_hi_i32 s10, s1, 0x2e8ba2e9
	s_lshr_b32 s11, s10, 31
	v_ashrrev_i32_e32 v3, 1, v1
	s_ashr_i32 s10, s10, 1
	v_and_b32_e32 v3, 0xffffffe0, v3
	v_bfe_u32 v1, v1, 3, 3
	s_and_b32 s0, s13, 0xc0
	s_add_i32 s10, s10, s11
	v_or3_b32 v1, v1, v3, 24
	v_mov_b32_e32 v3, v161
	s_add_i32 s15, s10, s0
	s_bfe_i32 s11, s14, 0x10002
	s_mul_i32 s10, s10, 11
	v_lshrrev_b32_e32 v4, 1, v1
	s_and_b32 s11, s11, 11
	s_sub_i32 s1, s1, s10
	v_xor_b32_e32 v3, v4, v3
	s_lshl_b32 s0, s15, 7
	s_add_i32 s1, s1, s11
	v_lshlrev_b32_e32 v1, 11, v1
	v_lshlrev_b32_e32 v3, 4, v3
	v_mov_b32_e32 v12, v161
	s_lshl_b32 s10, s1, 7
	v_and_or_b32 v4, v3, s92, v1
	s_ashr_i32 s1, s0, 31
	s_lshl_b64 s[16:17], s[0:1], 11
	v_and_b32_e32 v1, 31, v12
	v_lshrrev_b32_e32 v5, 1, v12
	v_and_or_b32 v1, v5, s6, v1
	s_add_u32 s16, s84, s16
	v_lshlrev_b32_e32 v112, 7, v1
	v_lshlrev_b32_e32 v1, 6, v12
	s_addc_u32 s17, s85, s17
	s_ashr_i32 s11, s10, 31
	v_and_b32_e32 v89, 0xfffff000, v1
	s_lshl_b64 s[18:19], s[10:11], 11
	v_add_u32_e32 v88, 0x4000, v89
	v_readfirstlane_b32 s20, v89
	s_add_u32 s18, s2, s18
	s_mov_b32 m0, s20
	v_readfirstlane_b32 s21, v88
	v_or_b32_e32 v90, 0x400, v89
	s_addc_u32 s19, s12, s19
	global_load_lds_dwordx4 v136, s[16:17]
	s_mov_b32 m0, s21
	v_readfirstlane_b32 s22, v90
	v_add_u32_e32 v91, 0x4400, v89
	global_load_lds_dwordx4 v136, s[18:19]
	s_mov_b32 m0, s22
	v_readfirstlane_b32 s23, v91
	v_or_b32_e32 v92, 0x800, v89
	global_load_lds_dwordx4 v0, s[16:17]
	s_mov_b32 m0, s23
	v_readfirstlane_b32 s28, v92
	v_add_u32_e32 v93, 0x4800, v89
	global_load_lds_dwordx4 v0, s[18:19]
	s_mov_b32 m0, s28
	v_readfirstlane_b32 s29, v93
	v_or_b32_e32 v94, 0xc00, v89
	global_load_lds_dwordx4 v2, s[16:17]
	s_mov_b32 m0, s29
	v_readfirstlane_b32 s40, v94
	v_add_u32_e32 v95, 0x4c00, v89
	v_lshrrev_b32_e32 v3, 5, v12
	v_bfe_u32 v99, v12, 1, 3
	global_load_lds_dwordx4 v2, s[18:19]
	s_mov_b32 m0, s40
	v_readfirstlane_b32 s41, v95
	v_add_u32_e32 v97, 0x8000, v89
	v_bitop3_b32 v3, v3, v99, 1 bitop3:0x6c
	v_lshl_add_u64 v[64:65], s[16:17], 0, v[136:137]
	v_mov_b32_e32 v1, v137
	global_load_lds_dwordx4 v4, s[16:17]
	s_mov_b32 m0, s41
	v_add_u32_e32 v96, 0xc000, v89
	v_readfirstlane_b32 s42, v97
	v_lshlrev_b32_e32 v6, 4, v3
	v_lshl_add_u64 v[66:67], s[18:19], 0, v[136:137]
	v_lshl_add_u64 v[68:69], s[16:17], 0, v[0:1]
	v_lshl_add_u64 v[70:71], s[18:19], 0, v[0:1]
	v_mov_b32_e32 v3, v137
	global_load_lds_dwordx4 v4, s[18:19]
	v_lshl_add_u64 v[0:1], v[64:65], 0, s[94:95]
	s_mov_b32 m0, s42
	v_readfirstlane_b32 s43, v96
	v_add_u32_e32 v98, 0x8400, v89
	v_lshl_add_u64 v[72:73], s[16:17], 0, v[2:3]
	v_lshl_add_u64 v[74:75], s[18:19], 0, v[2:3]
	global_load_lds_dwordx4 v[0:1], off
	v_lshl_add_u64 v[0:1], v[66:67], 0, s[94:95]
	s_mov_b32 m0, s43
	v_readfirstlane_b32 s44, v98
	v_add_u32_e32 v2, 0xc400, v89
	v_mov_b32_e32 v5, v137
	global_load_lds_dwordx4 v[0:1], off
	v_lshl_add_u64 v[0:1], v[68:69], 0, s[94:95]
	s_mov_b32 m0, s44
	v_readfirstlane_b32 s1, v2
	v_add_u32_e32 v2, 0x8800, v89
	v_lshl_add_u64 v[76:77], s[16:17], 0, v[4:5]
	global_load_lds_dwordx4 v[0:1], off
	v_lshl_add_u64 v[0:1], v[70:71], 0, s[94:95]
	s_mov_b32 m0, s1
	v_readfirstlane_b32 s16, v2
	v_add_u32_e32 v2, 0xc800, v89
	global_load_lds_dwordx4 v[0:1], off
	v_lshl_add_u64 v[0:1], v[72:73], 0, s[94:95]
	s_mov_b32 m0, s16
	v_readfirstlane_b32 s17, v2
	v_add_u32_e32 v2, 0x8c00, v89
	v_lshl_add_u64 v[78:79], s[18:19], 0, v[4:5]
	global_load_lds_dwordx4 v[0:1], off
	v_lshl_add_u64 v[0:1], v[74:75], 0, s[94:95]
	s_mov_b32 m0, s17
	v_readfirstlane_b32 s18, v2
	v_add_u32_e32 v2, 0xcc00, v89
	global_load_lds_dwordx4 v[0:1], off
	v_lshl_add_u64 v[0:1], v[76:77], 0, s[94:95]
	s_mov_b32 m0, s18
	v_readfirstlane_b32 s19, v2
	global_load_lds_dwordx4 v[0:1], off
	v_lshl_add_u64 v[0:1], v[78:79], 0, s[94:95]
	s_mov_b32 m0, s19
	v_or_b32_e32 v80, v112, v6
	global_load_lds_dwordx4 v[0:1], off
	s_waitcnt vmcnt(8)
	s_waitcnt vmcnt(8) lgkmcnt(0)
	s_barrier
; #define WAIT_V0() asm volatile("s_waitcnt vmcnt(0)" ::: "memory")
; DI void gemm_core(char* smem, int nk, const char* Ab, const char* Bb, const unsigned (&aoff)[4], const unsigned (&boff)[4],
;                   f32x16 (&acc)[2][2]) {
;     ...
;   stage(0, 0);
;   WAIT_V0();
;   __syncthreads();
;   for (int kt = 0; kt < nk; ++kt) {
;     const int cur = kt & 1;
;     if (kt + 1 < nk) stage(cur ^ 1, kt + 1);
;     const char* sb = smem + cur * STAGE_B;
; #pragma unroll
;     for (int ks = 0; ks < 4; ++ks) {
;       bf16x8 af[2], bfr[2];
; #pragma unroll
;       for (int mb = 0; mb < 2; ++mb) af[mb] = *(const bf16x8*)(sb + a_base + mb * 4096 + xo[ks]);
; #pragma unroll
;       for (int nb = 0; nb < 2; ++nb) bfr[nb] = *(const bf16x8*)(sb + b_base + nb * 4096 + xo[ks]);
; #pragma unroll
;       for (int mb = 0; mb < 2; ++mb)
; #pragma unroll
;         for (int nb = 0; nb < 2; ++nb)
;           acc[mb][nb] = __builtin_amdgcn_mfma_f32_32x32x16_bf16(af[mb], bfr[nb], acc[mb][nb], 0, 0, 0);
;     }
;     WAIT_V0();
;     __syncthreads();
;   }
	ds_read_b128 v[0:3], v80
	v_lshlrev_b32_e32 v4, 7, v12
	v_and_b32_e32 v113, 0x2f80, v4
	v_or_b32_e32 v82, v113, v6
	ds_read_b128 v[4:7], v82 offset:16384
	ds_read_b128 v[8:11], v82 offset:20480
	s_waitcnt lgkmcnt(0)
	v_mfma_f32_32x32x16_bf16 v[48:63], v[0:3], v[4:7], 0
	v_bfe_u32 v114, v12, 5, 1
	s_mov_b32 m0, s20
	v_mfma_f32_32x32x16_bf16 v[32:47], v[0:3], v[8:11], 0
	ds_read_b128 v[0:3], v80 offset:4096
	s_waitcnt lgkmcnt(0)
	v_mfma_f32_32x32x16_bf16 v[16:31], v[0:3], v[4:7], 0
	v_bitop3_b32 v4, v114, v99, 2 bitop3:0x36
	v_lshlrev_b32_e32 v83, 4, v4
	v_or_b32_e32 v81, v112, v83
	ds_read_b128 v[84:87], v81
	v_or_b32_e32 v83, v113, v83
	ds_read_b128 v[100:103], v83 offset:16384
	ds_read_b128 v[104:107], v83 offset:20480
	s_waitcnt lgkmcnt(0)
	v_mfma_f32_32x32x16_bf16 v[48:63], v[84:87], v[100:103], v[48:63]
	v_mfma_f32_32x32x16_bf16 v[32:47], v[84:87], v[104:107], v[32:47]
	ds_read_b128 v[84:87], v81 offset:4096
	v_mfma_f32_32x32x16_bf16 v[0:15], v[0:3], v[8:11], 0
	s_waitcnt lgkmcnt(0)
	v_mfma_f32_32x32x16_bf16 v[16:31], v[84:87], v[100:103], v[16:31]
	v_bitop3_b32 v100, v114, v99, 4 bitop3:0x36
	v_lshlrev_b32_e32 v108, 4, v100
	v_mfma_f32_32x32x16_bf16 v[0:15], v[84:87], v[104:107], v[0:15]
	v_or_b32_e32 v84, v112, v108
	ds_read_b128 v[100:103], v84
	v_or_b32_e32 v85, v113, v108
	ds_read_b128 v[104:107], v85 offset:16384
	ds_read_b128 v[108:111], v85 offset:20480
	v_bitop3_b32 v86, v114, v99, 6 bitop3:0x36
	v_lshlrev_b32_e32 v87, 4, v86
	s_waitcnt lgkmcnt(0)
	v_mfma_f32_32x32x16_bf16 v[48:63], v[100:103], v[104:107], v[48:63]
	v_or_b32_e32 v86, v112, v87
	v_or_b32_e32 v87, v113, v87
	v_mfma_f32_32x32x16_bf16 v[32:47], v[100:103], v[108:111], v[32:47]
	ds_read_b128 v[100:103], v84 offset:4096
	s_waitcnt lgkmcnt(0)
	v_mfma_f32_32x32x16_bf16 v[16:31], v[100:103], v[104:107], v[16:31]
	ds_read_b128 v[104:107], v87 offset:16384
	v_mfma_f32_32x32x16_bf16 v[0:15], v[100:103], v[108:111], v[0:15]
	ds_read_b128 v[100:103], v86
	ds_read_b128 v[108:111], v87 offset:20480
	ds_read_b128 v[120:123], v86 offset:4096
	s_waitcnt vmcnt(0)
	s_waitcnt vmcnt(0) lgkmcnt(0)
	s_barrier
	v_mfma_f32_32x32x16_bf16 v[48:63], v[100:103], v[104:107], v[48:63]
	v_mfma_f32_32x32x16_bf16 v[32:47], v[100:103], v[108:111], v[32:47]
	v_mfma_f32_32x32x16_bf16 v[16:31], v[120:123], v[104:107], v[16:31]
	v_mfma_f32_32x32x16_bf16 v[0:15], v[120:123], v[108:111], v[0:15]
	ds_read_b128 v[100:103], v80 offset:32768
	ds_read_b128 v[104:107], v82 offset:49152
	ds_read_b128 v[108:111], v82 offset:53248
	v_lshl_add_u64 v[116:117], v[64:65], 0, s[36:37]
	global_load_lds_dwordx4 v[116:117], off
	v_lshl_add_u64 v[118:119], v[66:67], 0, s[36:37]
	s_mov_b32 m0, s21
	s_nop 0
	global_load_lds_dwordx4 v[118:119], off
	v_lshl_add_u64 v[116:117], v[68:69], 0, s[36:37]
	s_mov_b32 m0, s22
	s_nop 0
	global_load_lds_dwordx4 v[116:117], off
	v_lshl_add_u64 v[118:119], v[70:71], 0, s[36:37]
	s_mov_b32 m0, s23
	s_nop 0
	global_load_lds_dwordx4 v[118:119], off
	v_lshl_add_u64 v[116:117], v[72:73], 0, s[36:37]
	s_mov_b32 m0, s28
	s_nop 0
	global_load_lds_dwordx4 v[116:117], off
	v_lshl_add_u64 v[118:119], v[74:75], 0, s[36:37]
	s_mov_b32 m0, s29
	s_nop 0
	global_load_lds_dwordx4 v[118:119], off
	v_lshl_add_u64 v[116:117], v[76:77], 0, s[36:37]
	s_mov_b32 m0, s40
	s_nop 0
	global_load_lds_dwordx4 v[116:117], off
	v_lshl_add_u64 v[118:119], v[78:79], 0, s[36:37]
	s_mov_b32 m0, s41
	s_nop 0
	global_load_lds_dwordx4 v[118:119], off
	s_waitcnt lgkmcnt(0)
	v_mfma_f32_32x32x16_bf16 v[48:63], v[100:103], v[104:107], v[48:63]
	s_mov_b32 m0, s42
	v_mfma_f32_32x32x16_bf16 v[32:47], v[100:103], v[108:111], v[32:47]
	ds_read_b128 v[100:103], v80 offset:36864
	s_waitcnt lgkmcnt(0)
	v_mfma_f32_32x32x16_bf16 v[16:31], v[100:103], v[104:107], v[16:31]
	v_mfma_f32_32x32x16_bf16 v[0:15], v[100:103], v[108:111], v[0:15]
	ds_read_b128 v[100:103], v81 offset:32768
	ds_read_b128 v[104:107], v83 offset:49152
	ds_read_b128 v[108:111], v83 offset:53248
	s_waitcnt lgkmcnt(0)
	v_mfma_f32_32x32x16_bf16 v[48:63], v[100:103], v[104:107], v[48:63]
	v_mfma_f32_32x32x16_bf16 v[32:47], v[100:103], v[108:111], v[32:47]
	ds_read_b128 v[100:103], v81 offset:36864
	s_waitcnt lgkmcnt(0)
	v_mfma_f32_32x32x16_bf16 v[16:31], v[100:103], v[104:107], v[16:31]
	v_mfma_f32_32x32x16_bf16 v[0:15], v[100:103], v[108:111], v[0:15]
	ds_read_b128 v[124:127], v84 offset:32768
	ds_read_b128 v[132:135], v85 offset:49152
	ds_read_b128 v[140:143], v85 offset:53248
	ds_read_b128 v[128:131], v84 offset:36864
	ds_read_b128 v[100:103], v86 offset:32768
	ds_read_b128 v[104:107], v87 offset:49152
	ds_read_b128 v[108:111], v87 offset:53248
	ds_read_b128 v[120:123], v86 offset:36864
	s_waitcnt vmcnt(0)
	s_waitcnt vmcnt(0) lgkmcnt(0)
	s_barrier
; #define WAIT_V0() asm volatile("s_waitcnt vmcnt(0)" ::: "memory")
; DI void gemm_core(char* smem, int nk, const char* Ab, const char* Bb, const unsigned (&aoff)[4], const unsigned (&boff)[4],
;                   f32x16 (&acc)[2][2]) {
;     ...
;   auto stage = [&](int buf, int kt) __attribute__((always_inline)) {
;     const char* ak = Ab + kt * 128;
;     const char* bk = Bb + kt * 128;
;     char* sa = smem + buf * STAGE_B + w * 4096;
; #pragma unroll
;     for (int i = 0; i < 4; ++i) {
;       __builtin_amdgcn_global_load_lds((const unsigned*)(ak + aoff[i]), (unsigned*)(sa + i * 1024), 16, 0, 0);
;       __builtin_amdgcn_global_load_lds((const unsigned*)(bk + boff[i]), (unsigned*)(sa + 16384 + i * 1024), 16, 0, 0);
;     }
;   };
;   stage(0, 0);
;   WAIT_V0();
;   __syncthreads();
;   for (int kt = 0; kt < nk; ++kt) {
;     const int cur = kt & 1;
;     if (kt + 1 < nk) stage(cur ^ 1, kt + 1);
;     const char* sb = smem + cur * STAGE_B;
; #pragma unroll
;     for (int ks = 0; ks < 4; ++ks) {
;       bf16x8 af[2], bfr[2];
; #pragma unroll
;       for (int mb = 0; mb < 2; ++mb) af[mb] = *(const bf16x8*)(sb + a_base + mb * 4096 + xo[ks]);
; #pragma unroll
;       for (int nb = 0; nb < 2; ++nb) bfr[nb] = *(const bf16x8*)(sb + b_base + nb * 4096 + xo[ks]);
; #pragma unroll
;       for (int mb = 0; mb < 2; ++mb)
; #pragma unroll
;         for (int nb = 0; nb < 2; ++nb)
;           acc[mb][nb] = __builtin_amdgcn_mfma_f32_32x32x16_bf16(af[mb], bfr[nb], acc[mb][nb], 0, 0, 0);
;     }
;     WAIT_V0();
;     __syncthreads();
;   }
	v_mfma_f32_32x32x16_bf16 v[48:63], v[124:127], v[132:135], v[48:63]
	v_lshl_add_u64 v[116:117], v[64:65], 0, s[38:39]
	global_load_lds_dwordx4 v[116:117], off
	v_mfma_f32_32x32x16_bf16 v[32:47], v[124:127], v[140:143], v[32:47]
	v_lshl_add_u64 v[118:119], v[66:67], 0, s[38:39]
	s_mov_b32 m0, s43
	s_nop 0
	global_load_lds_dwordx4 v[118:119], off
	v_mfma_f32_32x32x16_bf16 v[16:31], v[128:131], v[132:135], v[16:31]
	v_lshl_add_u64 v[116:117], v[68:69], 0, s[38:39]
	s_mov_b32 m0, s44
	s_nop 0
	global_load_lds_dwordx4 v[116:117], off
	v_mfma_f32_32x32x16_bf16 v[0:15], v[128:131], v[140:143], v[0:15]
	v_lshl_add_u64 v[118:119], v[70:71], 0, s[38:39]
	s_mov_b32 m0, s1
	s_nop 0
	global_load_lds_dwordx4 v[118:119], off
	v_mfma_f32_32x32x16_bf16 v[48:63], v[100:103], v[104:107], v[48:63]
	v_lshl_add_u64 v[116:117], v[72:73], 0, s[38:39]
	s_mov_b32 m0, s16
	s_nop 0
	global_load_lds_dwordx4 v[116:117], off
	v_mfma_f32_32x32x16_bf16 v[32:47], v[100:103], v[108:111], v[32:47]
	v_lshl_add_u64 v[118:119], v[74:75], 0, s[38:39]
	s_mov_b32 m0, s17
	s_nop 0
	global_load_lds_dwordx4 v[118:119], off
	v_mfma_f32_32x32x16_bf16 v[16:31], v[120:123], v[104:107], v[16:31]
	v_lshl_add_u64 v[116:117], v[76:77], 0, s[38:39]
	s_mov_b32 m0, s18
	s_nop 0
	global_load_lds_dwordx4 v[116:117], off
	v_mfma_f32_32x32x16_bf16 v[0:15], v[120:123], v[108:111], v[0:15]
	v_lshl_add_u64 v[118:119], v[78:79], 0, s[38:39]
	s_mov_b32 m0, s19
	s_nop 0
	global_load_lds_dwordx4 v[118:119], off
	ds_read_b128 v[100:103], v80
	ds_read_b128 v[104:107], v82 offset:16384
	ds_read_b128 v[108:111], v82 offset:20480
	s_waitcnt lgkmcnt(0)
	v_mfma_f32_32x32x16_bf16 v[48:63], v[100:103], v[104:107], v[48:63]
	s_mov_b32 m0, s20
	v_mfma_f32_32x32x16_bf16 v[32:47], v[100:103], v[108:111], v[32:47]
	ds_read_b128 v[100:103], v80 offset:4096
	s_waitcnt lgkmcnt(0)
	v_mfma_f32_32x32x16_bf16 v[16:31], v[100:103], v[104:107], v[16:31]
	v_mfma_f32_32x32x16_bf16 v[0:15], v[100:103], v[108:111], v[0:15]
	ds_read_b128 v[100:103], v81
	ds_read_b128 v[104:107], v83 offset:16384
	ds_read_b128 v[108:111], v83 offset:20480
	s_waitcnt lgkmcnt(0)
	v_mfma_f32_32x32x16_bf16 v[48:63], v[100:103], v[104:107], v[48:63]
	v_mfma_f32_32x32x16_bf16 v[32:47], v[100:103], v[108:111], v[32:47]
	ds_read_b128 v[100:103], v81 offset:4096
	s_waitcnt lgkmcnt(0)
	v_mfma_f32_32x32x16_bf16 v[16:31], v[100:103], v[104:107], v[16:31]
	v_mfma_f32_32x32x16_bf16 v[0:15], v[100:103], v[108:111], v[0:15]
	ds_read_b128 v[124:127], v84
	ds_read_b128 v[132:135], v85 offset:16384
	ds_read_b128 v[140:143], v85 offset:20480
	ds_read_b128 v[128:131], v84 offset:4096
	ds_read_b128 v[100:103], v86
	ds_read_b128 v[104:107], v87 offset:16384
	ds_read_b128 v[108:111], v87 offset:20480
	ds_read_b128 v[120:123], v86 offset:4096
	s_waitcnt vmcnt(0)
	s_waitcnt vmcnt(0) lgkmcnt(0)
	s_barrier
	v_mfma_f32_32x32x16_bf16 v[48:63], v[124:127], v[132:135], v[48:63]
	v_lshl_add_u64 v[116:117], v[64:65], 0, s[30:31]
	global_load_lds_dwordx4 v[116:117], off
	v_mfma_f32_32x32x16_bf16 v[32:47], v[124:127], v[140:143], v[32:47]
	v_lshl_add_u64 v[118:119], v[66:67], 0, s[30:31]
	s_mov_b32 m0, s21
	s_nop 0
	global_load_lds_dwordx4 v[118:119], off
	v_mfma_f32_32x32x16_bf16 v[16:31], v[128:131], v[132:135], v[16:31]
	v_lshl_add_u64 v[116:117], v[68:69], 0, s[30:31]
	s_mov_b32 m0, s22
	s_nop 0
	global_load_lds_dwordx4 v[116:117], off
	v_mfma_f32_32x32x16_bf16 v[0:15], v[128:131], v[140:143], v[0:15]
	v_lshl_add_u64 v[118:119], v[70:71], 0, s[30:31]
	s_mov_b32 m0, s23
	s_nop 0
	global_load_lds_dwordx4 v[118:119], off
	v_mfma_f32_32x32x16_bf16 v[48:63], v[100:103], v[104:107], v[48:63]
	v_lshl_add_u64 v[116:117], v[72:73], 0, s[30:31]
	s_mov_b32 m0, s28
	s_nop 0
	global_load_lds_dwordx4 v[116:117], off
	v_mfma_f32_32x32x16_bf16 v[32:47], v[100:103], v[108:111], v[32:47]
	v_lshl_add_u64 v[118:119], v[74:75], 0, s[30:31]
	s_mov_b32 m0, s29
	s_nop 0
	global_load_lds_dwordx4 v[118:119], off
	v_mfma_f32_32x32x16_bf16 v[16:31], v[120:123], v[104:107], v[16:31]
	v_lshl_add_u64 v[116:117], v[76:77], 0, s[30:31]
	s_mov_b32 m0, s40
	s_nop 0
	global_load_lds_dwordx4 v[116:117], off
	v_mfma_f32_32x32x16_bf16 v[0:15], v[120:123], v[108:111], v[0:15]
	v_lshl_add_u64 v[118:119], v[78:79], 0, s[30:31]
	s_mov_b32 m0, s41
	s_nop 0
	global_load_lds_dwordx4 v[118:119], off
	ds_read_b128 v[100:103], v80 offset:32768
	ds_read_b128 v[104:107], v82 offset:49152
	ds_read_b128 v[108:111], v82 offset:53248
	s_waitcnt lgkmcnt(0)
	v_mfma_f32_32x32x16_bf16 v[48:63], v[100:103], v[104:107], v[48:63]
	s_mov_b32 m0, s42
	v_mfma_f32_32x32x16_bf16 v[32:47], v[100:103], v[108:111], v[32:47]
	ds_read_b128 v[100:103], v80 offset:36864
	s_waitcnt lgkmcnt(0)
	v_mfma_f32_32x32x16_bf16 v[16:31], v[100:103], v[104:107], v[16:31]
	v_mfma_f32_32x32x16_bf16 v[0:15], v[100:103], v[108:111], v[0:15]
	ds_read_b128 v[100:103], v81 offset:32768
	ds_read_b128 v[104:107], v83 offset:49152
	ds_read_b128 v[108:111], v83 offset:53248
	s_waitcnt lgkmcnt(0)
	v_mfma_f32_32x32x16_bf16 v[48:63], v[100:103], v[104:107], v[48:63]
	v_mfma_f32_32x32x16_bf16 v[32:47], v[100:103], v[108:111], v[32:47]
	ds_read_b128 v[100:103], v81 offset:36864
	s_waitcnt lgkmcnt(0)
	v_mfma_f32_32x32x16_bf16 v[16:31], v[100:103], v[104:107], v[16:31]
	v_mfma_f32_32x32x16_bf16 v[0:15], v[100:103], v[108:111], v[0:15]
	ds_read_b128 v[124:127], v84 offset:32768
	ds_read_b128 v[132:135], v85 offset:49152
	ds_read_b128 v[140:143], v85 offset:53248
	ds_read_b128 v[128:131], v84 offset:36864
	ds_read_b128 v[100:103], v86 offset:32768
	ds_read_b128 v[104:107], v87 offset:49152
	ds_read_b128 v[108:111], v87 offset:53248
	ds_read_b128 v[120:123], v86 offset:36864
	s_waitcnt vmcnt(0)
	s_waitcnt vmcnt(0) lgkmcnt(0)
	s_barrier
; #define WAIT_V0() asm volatile("s_waitcnt vmcnt(0)" ::: "memory")
; DI void gemm_core(char* smem, int nk, const char* Ab, const char* Bb, const unsigned (&aoff)[4], const unsigned (&boff)[4],
;                   f32x16 (&acc)[2][2]) {
;     ...
;   auto stage = [&](int buf, int kt) __attribute__((always_inline)) {
;     const char* ak = Ab + kt * 128;
;     const char* bk = Bb + kt * 128;
;     char* sa = smem + buf * STAGE_B + w * 4096;
; #pragma unroll
;     for (int i = 0; i < 4; ++i) {
;       __builtin_amdgcn_global_load_lds((const unsigned*)(ak + aoff[i]), (unsigned*)(sa + i * 1024), 16, 0, 0);
;       __builtin_amdgcn_global_load_lds((const unsigned*)(bk + boff[i]), (unsigned*)(sa + 16384 + i * 1024), 16, 0, 0);
;     }
;   };
;   stage(0, 0);
;   WAIT_V0();
;   __syncthreads();
;   for (int kt = 0; kt < nk; ++kt) {
;     const int cur = kt & 1;
;     if (kt + 1 < nk) stage(cur ^ 1, kt + 1);
;     const char* sb = smem + cur * STAGE_B;
; #pragma unroll
;     for (int ks = 0; ks < 4; ++ks) {
;       bf16x8 af[2], bfr[2];
; #pragma unroll
;       for (int mb = 0; mb < 2; ++mb) af[mb] = *(const bf16x8*)(sb + a_base + mb * 4096 + xo[ks]);
; #pragma unroll
;       for (int nb = 0; nb < 2; ++nb) bfr[nb] = *(const bf16x8*)(sb + b_base + nb * 4096 + xo[ks]);
; #pragma unroll
;       for (int mb = 0; mb < 2; ++mb)
; #pragma unroll
;         for (int nb = 0; nb < 2; ++nb)
;           acc[mb][nb] = __builtin_amdgcn_mfma_f32_32x32x16_bf16(af[mb], bfr[nb], acc[mb][nb], 0, 0, 0);
;     }
;     WAIT_V0();
;     __syncthreads();
;   }
	v_mfma_f32_32x32x16_bf16 v[48:63], v[124:127], v[132:135], v[48:63]
	v_lshl_add_u64 v[116:117], v[64:65], 0, s[46:47]
	global_load_lds_dwordx4 v[116:117], off
	v_mfma_f32_32x32x16_bf16 v[32:47], v[124:127], v[140:143], v[32:47]
	v_lshl_add_u64 v[118:119], v[66:67], 0, s[46:47]
	s_mov_b32 m0, s43
	s_nop 0
	global_load_lds_dwordx4 v[118:119], off
	v_mfma_f32_32x32x16_bf16 v[16:31], v[128:131], v[132:135], v[16:31]
	v_lshl_add_u64 v[116:117], v[68:69], 0, s[46:47]
	s_mov_b32 m0, s44
	s_nop 0
	global_load_lds_dwordx4 v[116:117], off
	v_mfma_f32_32x32x16_bf16 v[0:15], v[128:131], v[140:143], v[0:15]
	v_lshl_add_u64 v[118:119], v[70:71], 0, s[46:47]
	s_mov_b32 m0, s1
	s_nop 0
	global_load_lds_dwordx4 v[118:119], off
	v_mfma_f32_32x32x16_bf16 v[48:63], v[100:103], v[104:107], v[48:63]
	v_lshl_add_u64 v[116:117], v[72:73], 0, s[46:47]
	s_mov_b32 m0, s16
	s_nop 0
	global_load_lds_dwordx4 v[116:117], off
	v_mfma_f32_32x32x16_bf16 v[32:47], v[100:103], v[108:111], v[32:47]
	v_lshl_add_u64 v[118:119], v[74:75], 0, s[46:47]
	s_mov_b32 m0, s17
	s_nop 0
	global_load_lds_dwordx4 v[118:119], off
	v_mfma_f32_32x32x16_bf16 v[16:31], v[120:123], v[104:107], v[16:31]
	v_lshl_add_u64 v[116:117], v[76:77], 0, s[46:47]
	s_mov_b32 m0, s18
	s_nop 0
	global_load_lds_dwordx4 v[116:117], off
	v_mfma_f32_32x32x16_bf16 v[0:15], v[120:123], v[108:111], v[0:15]
	v_lshl_add_u64 v[118:119], v[78:79], 0, s[46:47]
	s_mov_b32 m0, s19
	s_nop 0
	global_load_lds_dwordx4 v[118:119], off
	ds_read_b128 v[100:103], v80
	ds_read_b128 v[104:107], v82 offset:16384
	ds_read_b128 v[108:111], v82 offset:20480
	s_waitcnt lgkmcnt(0)
	v_mfma_f32_32x32x16_bf16 v[48:63], v[100:103], v[104:107], v[48:63]
	s_mov_b32 m0, s20
	v_mfma_f32_32x32x16_bf16 v[32:47], v[100:103], v[108:111], v[32:47]
	ds_read_b128 v[100:103], v80 offset:4096
	s_waitcnt lgkmcnt(0)
	v_mfma_f32_32x32x16_bf16 v[16:31], v[100:103], v[104:107], v[16:31]
	v_mfma_f32_32x32x16_bf16 v[0:15], v[100:103], v[108:111], v[0:15]
	ds_read_b128 v[100:103], v81
	ds_read_b128 v[104:107], v83 offset:16384
	ds_read_b128 v[108:111], v83 offset:20480
	s_waitcnt lgkmcnt(0)
	v_mfma_f32_32x32x16_bf16 v[48:63], v[100:103], v[104:107], v[48:63]
	v_mfma_f32_32x32x16_bf16 v[32:47], v[100:103], v[108:111], v[32:47]
	ds_read_b128 v[100:103], v81 offset:4096
	s_waitcnt lgkmcnt(0)
	v_mfma_f32_32x32x16_bf16 v[16:31], v[100:103], v[104:107], v[16:31]
	v_mfma_f32_32x32x16_bf16 v[0:15], v[100:103], v[108:111], v[0:15]
	ds_read_b128 v[124:127], v84
	ds_read_b128 v[132:135], v85 offset:16384
	ds_read_b128 v[140:143], v85 offset:20480
	ds_read_b128 v[128:131], v84 offset:4096
	ds_read_b128 v[100:103], v86
	ds_read_b128 v[104:107], v87 offset:16384
	ds_read_b128 v[108:111], v87 offset:20480
	ds_read_b128 v[120:123], v86 offset:4096
	s_waitcnt vmcnt(0)
	s_waitcnt vmcnt(0) lgkmcnt(0)
	s_barrier
	v_mfma_f32_32x32x16_bf16 v[48:63], v[124:127], v[132:135], v[48:63]
	v_lshl_add_u64 v[116:117], v[64:65], 0, s[48:49]
	global_load_lds_dwordx4 v[116:117], off
	v_mfma_f32_32x32x16_bf16 v[32:47], v[124:127], v[140:143], v[32:47]
	v_lshl_add_u64 v[118:119], v[66:67], 0, s[48:49]
	s_mov_b32 m0, s21
	s_nop 0
	global_load_lds_dwordx4 v[118:119], off
	v_mfma_f32_32x32x16_bf16 v[16:31], v[128:131], v[132:135], v[16:31]
	v_lshl_add_u64 v[116:117], v[68:69], 0, s[48:49]
	s_mov_b32 m0, s22
	s_nop 0
	global_load_lds_dwordx4 v[116:117], off
	v_mfma_f32_32x32x16_bf16 v[0:15], v[128:131], v[140:143], v[0:15]
	v_lshl_add_u64 v[118:119], v[70:71], 0, s[48:49]
	s_mov_b32 m0, s23
	s_nop 0
	global_load_lds_dwordx4 v[118:119], off
	v_mfma_f32_32x32x16_bf16 v[48:63], v[100:103], v[104:107], v[48:63]
	v_lshl_add_u64 v[116:117], v[72:73], 0, s[48:49]
	s_mov_b32 m0, s28
	s_nop 0
	global_load_lds_dwordx4 v[116:117], off
	v_mfma_f32_32x32x16_bf16 v[32:47], v[100:103], v[108:111], v[32:47]
	v_lshl_add_u64 v[118:119], v[74:75], 0, s[48:49]
	s_mov_b32 m0, s29
	s_nop 0
	global_load_lds_dwordx4 v[118:119], off
	v_mfma_f32_32x32x16_bf16 v[16:31], v[120:123], v[104:107], v[16:31]
	v_lshl_add_u64 v[116:117], v[76:77], 0, s[48:49]
	s_mov_b32 m0, s40
	s_nop 0
	global_load_lds_dwordx4 v[116:117], off
	v_mfma_f32_32x32x16_bf16 v[0:15], v[120:123], v[108:111], v[0:15]
	v_lshl_add_u64 v[118:119], v[78:79], 0, s[48:49]
	s_mov_b32 m0, s41
	s_nop 0
	global_load_lds_dwordx4 v[118:119], off
	ds_read_b128 v[100:103], v80 offset:32768
	ds_read_b128 v[104:107], v82 offset:49152
	ds_read_b128 v[108:111], v82 offset:53248
	s_waitcnt lgkmcnt(0)
	v_mfma_f32_32x32x16_bf16 v[48:63], v[100:103], v[104:107], v[48:63]
	s_mov_b32 m0, s42
	v_readfirstlane_b32 s42, v93
	v_mfma_f32_32x32x16_bf16 v[32:47], v[100:103], v[108:111], v[32:47]
	ds_read_b128 v[100:103], v80 offset:36864
	s_waitcnt lgkmcnt(0)
	v_mfma_f32_32x32x16_bf16 v[16:31], v[100:103], v[104:107], v[16:31]
	v_mfma_f32_32x32x16_bf16 v[0:15], v[100:103], v[108:111], v[0:15]
	ds_read_b128 v[100:103], v81 offset:32768
	ds_read_b128 v[104:107], v83 offset:49152
	ds_read_b128 v[108:111], v83 offset:53248
	s_waitcnt lgkmcnt(0)
	v_mfma_f32_32x32x16_bf16 v[48:63], v[100:103], v[104:107], v[48:63]
	v_mfma_f32_32x32x16_bf16 v[32:47], v[100:103], v[108:111], v[32:47]
	ds_read_b128 v[100:103], v81 offset:36864
	s_waitcnt lgkmcnt(0)
	v_mfma_f32_32x32x16_bf16 v[16:31], v[100:103], v[104:107], v[16:31]
	v_mfma_f32_32x32x16_bf16 v[0:15], v[100:103], v[108:111], v[0:15]
	ds_read_b128 v[124:127], v84 offset:32768
	ds_read_b128 v[132:135], v85 offset:49152
	ds_read_b128 v[140:143], v85 offset:53248
	ds_read_b128 v[128:131], v84 offset:36864
	ds_read_b128 v[100:103], v86 offset:32768
	ds_read_b128 v[104:107], v87 offset:49152
	ds_read_b128 v[108:111], v87 offset:53248
	ds_read_b128 v[120:123], v86 offset:36864
	s_waitcnt vmcnt(0)
	s_waitcnt vmcnt(0) lgkmcnt(0)
	s_barrier
; #define WAIT_V0() asm volatile("s_waitcnt vmcnt(0)" ::: "memory")
; DI void gemm_core(char* smem, int nk, const char* Ab, const char* Bb, const unsigned (&aoff)[4], const unsigned (&boff)[4],
;                   f32x16 (&acc)[2][2]) {
;     ...
;   auto stage = [&](int buf, int kt) __attribute__((always_inline)) {
;     const char* ak = Ab + kt * 128;
;     const char* bk = Bb + kt * 128;
;     char* sa = smem + buf * STAGE_B + w * 4096;
; #pragma unroll
;     for (int i = 0; i < 4; ++i) {
;       __builtin_amdgcn_global_load_lds((const unsigned*)(ak + aoff[i]), (unsigned*)(sa + i * 1024), 16, 0, 0);
;       __builtin_amdgcn_global_load_lds((const unsigned*)(bk + boff[i]), (unsigned*)(sa + 16384 + i * 1024), 16, 0, 0);
;     }
;   };
;   stage(0, 0);
;   WAIT_V0();
;   __syncthreads();
;   for (int kt = 0; kt < nk; ++kt) {
;     const int cur = kt & 1;
;     if (kt + 1 < nk) stage(cur ^ 1, kt + 1);
;     const char* sb = smem + cur * STAGE_B;
; #pragma unroll
;     for (int ks = 0; ks < 4; ++ks) {
;       bf16x8 af[2], bfr[2];
; #pragma unroll
;       for (int mb = 0; mb < 2; ++mb) af[mb] = *(const bf16x8*)(sb + a_base + mb * 4096 + xo[ks]);
; #pragma unroll
;       for (int nb = 0; nb < 2; ++nb) bfr[nb] = *(const bf16x8*)(sb + b_base + nb * 4096 + xo[ks]);
; #pragma unroll
;       for (int mb = 0; mb < 2; ++mb)
; #pragma unroll
;         for (int nb = 0; nb < 2; ++nb)
;           acc[mb][nb] = __builtin_amdgcn_mfma_f32_32x32x16_bf16(af[mb], bfr[nb], acc[mb][nb], 0, 0, 0);
;     }
;     WAIT_V0();
;     __syncthreads();
;   }
	v_mfma_f32_32x32x16_bf16 v[48:63], v[124:127], v[132:135], v[48:63]
	v_lshl_add_u64 v[116:117], v[64:65], 0, s[50:51]
	global_load_lds_dwordx4 v[116:117], off
	v_mfma_f32_32x32x16_bf16 v[32:47], v[124:127], v[140:143], v[32:47]
	v_lshl_add_u64 v[118:119], v[66:67], 0, s[50:51]
	s_mov_b32 m0, s43
	v_readfirstlane_b32 s43, v94
	global_load_lds_dwordx4 v[118:119], off
	v_mfma_f32_32x32x16_bf16 v[16:31], v[128:131], v[132:135], v[16:31]
	v_lshl_add_u64 v[116:117], v[68:69], 0, s[50:51]
	s_mov_b32 m0, s44
	v_readfirstlane_b32 s44, v95
	global_load_lds_dwordx4 v[116:117], off
	v_mfma_f32_32x32x16_bf16 v[0:15], v[128:131], v[140:143], v[0:15]
	v_lshl_add_u64 v[118:119], v[70:71], 0, s[50:51]
	s_mov_b32 m0, s1
	s_nop 0
	global_load_lds_dwordx4 v[118:119], off
	v_mfma_f32_32x32x16_bf16 v[48:63], v[100:103], v[104:107], v[48:63]
	v_lshl_add_u64 v[116:117], v[72:73], 0, s[50:51]
	s_mov_b32 m0, s16
	s_nop 0
	global_load_lds_dwordx4 v[116:117], off
	v_mfma_f32_32x32x16_bf16 v[32:47], v[100:103], v[108:111], v[32:47]
	v_lshl_add_u64 v[118:119], v[74:75], 0, s[50:51]
	s_mov_b32 m0, s17
	s_nop 0
	global_load_lds_dwordx4 v[118:119], off
	v_mfma_f32_32x32x16_bf16 v[16:31], v[120:123], v[104:107], v[16:31]
	v_lshl_add_u64 v[116:117], v[76:77], 0, s[50:51]
	s_mov_b32 m0, s18
	s_nop 0
	global_load_lds_dwordx4 v[116:117], off
	v_mfma_f32_32x32x16_bf16 v[0:15], v[120:123], v[108:111], v[0:15]
	v_lshl_add_u64 v[118:119], v[78:79], 0, s[50:51]
	s_mov_b32 m0, s19
	s_nop 0
	global_load_lds_dwordx4 v[118:119], off
	ds_read_b128 v[100:103], v80
	ds_read_b128 v[104:107], v82 offset:16384
	ds_read_b128 v[108:111], v82 offset:20480
	s_waitcnt lgkmcnt(0)
	v_mfma_f32_32x32x16_bf16 v[48:63], v[100:103], v[104:107], v[48:63]
	s_mov_b32 m0, s20
	v_readfirstlane_b32 s20, v97
	v_mfma_f32_32x32x16_bf16 v[32:47], v[100:103], v[108:111], v[32:47]
	ds_read_b128 v[100:103], v80 offset:4096
	s_waitcnt lgkmcnt(0)
	v_mfma_f32_32x32x16_bf16 v[16:31], v[100:103], v[104:107], v[16:31]
	v_mfma_f32_32x32x16_bf16 v[0:15], v[100:103], v[108:111], v[0:15]
	ds_read_b128 v[100:103], v81
	ds_read_b128 v[104:107], v83 offset:16384
	ds_read_b128 v[108:111], v83 offset:20480
	s_waitcnt lgkmcnt(0)
	v_mfma_f32_32x32x16_bf16 v[48:63], v[100:103], v[104:107], v[48:63]
	v_mfma_f32_32x32x16_bf16 v[32:47], v[100:103], v[108:111], v[32:47]
	ds_read_b128 v[100:103], v81 offset:4096
	s_waitcnt lgkmcnt(0)
	v_mfma_f32_32x32x16_bf16 v[16:31], v[100:103], v[104:107], v[16:31]
	v_mfma_f32_32x32x16_bf16 v[0:15], v[100:103], v[108:111], v[0:15]
	ds_read_b128 v[124:127], v84
	ds_read_b128 v[132:135], v85 offset:16384
	ds_read_b128 v[140:143], v85 offset:20480
	ds_read_b128 v[128:131], v84 offset:4096
	ds_read_b128 v[100:103], v86
	ds_read_b128 v[104:107], v87 offset:16384
	ds_read_b128 v[108:111], v87 offset:20480
	ds_read_b128 v[120:123], v86 offset:4096
	s_waitcnt vmcnt(0)
	s_waitcnt vmcnt(0) lgkmcnt(0)
	s_barrier
	v_mfma_f32_32x32x16_bf16 v[48:63], v[124:127], v[132:135], v[48:63]
	v_mfma_f32_32x32x16_bf16 v[32:47], v[124:127], v[140:143], v[32:47]
	v_mfma_f32_32x32x16_bf16 v[16:31], v[128:131], v[132:135], v[16:31]
	v_mfma_f32_32x32x16_bf16 v[0:15], v[128:131], v[140:143], v[0:15]
	v_mfma_f32_32x32x16_bf16 v[48:63], v[100:103], v[104:107], v[48:63]
	v_mfma_f32_32x32x16_bf16 v[32:47], v[100:103], v[108:111], v[32:47]
	v_mfma_f32_32x32x16_bf16 v[16:31], v[120:123], v[104:107], v[16:31]
	v_mfma_f32_32x32x16_bf16 v[0:15], v[120:123], v[108:111], v[0:15]
	v_lshl_add_u64 v[100:101], v[64:65], 0, s[52:53]
	global_load_lds_dwordx4 v[100:101], off
	v_lshl_add_u64 v[100:101], v[66:67], 0, s[52:53]
	s_mov_b32 m0, s21
	v_readfirstlane_b32 s21, v96
	global_load_lds_dwordx4 v[100:101], off
	v_lshl_add_u64 v[100:101], v[68:69], 0, s[52:53]
	s_mov_b32 m0, s22
	v_readfirstlane_b32 s22, v98
	global_load_lds_dwordx4 v[100:101], off
	v_lshl_add_u64 v[100:101], v[70:71], 0, s[52:53]
	s_mov_b32 m0, s23
	v_lshl_add_u64 v[96:97], v[68:69], 0, s[54:55]
	global_load_lds_dwordx4 v[100:101], off
	v_lshl_add_u64 v[100:101], v[72:73], 0, s[52:53]
	s_mov_b32 m0, s28
	v_readfirstlane_b32 s23, v89
	global_load_lds_dwordx4 v[100:101], off
	v_lshl_add_u64 v[100:101], v[74:75], 0, s[52:53]
	s_mov_b32 m0, s29
	v_readfirstlane_b32 s28, v88
	global_load_lds_dwordx4 v[100:101], off
	v_lshl_add_u64 v[100:101], v[76:77], 0, s[52:53]
	s_mov_b32 m0, s40
	v_readfirstlane_b32 s29, v90
	global_load_lds_dwordx4 v[100:101], off
	v_lshl_add_u64 v[100:101], v[78:79], 0, s[52:53]
	s_mov_b32 m0, s41
	v_lshl_add_u64 v[88:89], v[68:69], 0, s[56:57]
	global_load_lds_dwordx4 v[100:101], off
	ds_read_b128 v[100:103], v80 offset:32768
	ds_read_b128 v[104:107], v82 offset:49152
	ds_read_b128 v[108:111], v82 offset:53248
	s_waitcnt lgkmcnt(0)
	v_mfma_f32_32x32x16_bf16 v[48:63], v[100:103], v[104:107], v[48:63]
	s_mov_b32 m0, s20
	v_readfirstlane_b32 s40, v91
	v_readfirstlane_b32 s41, v92
	v_mfma_f32_32x32x16_bf16 v[32:47], v[100:103], v[108:111], v[32:47]
	ds_read_b128 v[100:103], v80 offset:36864
	s_waitcnt lgkmcnt(0)
	v_mfma_f32_32x32x16_bf16 v[16:31], v[100:103], v[104:107], v[16:31]
	v_mfma_f32_32x32x16_bf16 v[0:15], v[100:103], v[108:111], v[0:15]
	ds_read_b128 v[100:103], v81 offset:32768
	ds_read_b128 v[104:107], v83 offset:49152
	ds_read_b128 v[108:111], v83 offset:53248
	s_waitcnt lgkmcnt(0)
	v_mfma_f32_32x32x16_bf16 v[48:63], v[100:103], v[104:107], v[48:63]
	v_mfma_f32_32x32x16_bf16 v[32:47], v[100:103], v[108:111], v[32:47]
	ds_read_b128 v[100:103], v81 offset:36864
	s_waitcnt lgkmcnt(0)
	v_mfma_f32_32x32x16_bf16 v[16:31], v[100:103], v[104:107], v[16:31]
	v_mfma_f32_32x32x16_bf16 v[0:15], v[100:103], v[108:111], v[0:15]
	ds_read_b128 v[124:127], v84 offset:32768
	ds_read_b128 v[132:135], v85 offset:49152
	ds_read_b128 v[140:143], v85 offset:53248
	ds_read_b128 v[128:131], v84 offset:36864
	ds_read_b128 v[100:103], v86 offset:32768
	ds_read_b128 v[104:107], v87 offset:49152
	ds_read_b128 v[108:111], v87 offset:53248
	ds_read_b128 v[120:123], v86 offset:36864
	s_waitcnt vmcnt(0)
	s_waitcnt vmcnt(0) lgkmcnt(0)
	s_barrier
; #define WAIT_V0() asm volatile("s_waitcnt vmcnt(0)" ::: "memory")
; DI void gemm_core(char* smem, int nk, const char* Ab, const char* Bb, const unsigned (&aoff)[4], const unsigned (&boff)[4],
;                   f32x16 (&acc)[2][2]) {
;     ...
;   auto stage = [&](int buf, int kt) __attribute__((always_inline)) {
;     const char* ak = Ab + kt * 128;
;     const char* bk = Bb + kt * 128;
;     char* sa = smem + buf * STAGE_B + w * 4096;
; #pragma unroll
;     for (int i = 0; i < 4; ++i) {
;       __builtin_amdgcn_global_load_lds((const unsigned*)(ak + aoff[i]), (unsigned*)(sa + i * 1024), 16, 0, 0);
;       __builtin_amdgcn_global_load_lds((const unsigned*)(bk + boff[i]), (unsigned*)(sa + 16384 + i * 1024), 16, 0, 0);
;     }
;   };
;   stage(0, 0);
;   WAIT_V0();
;   __syncthreads();
;   for (int kt = 0; kt < nk; ++kt) {
;     const int cur = kt & 1;
;     if (kt + 1 < nk) stage(cur ^ 1, kt + 1);
;     const char* sb = smem + cur * STAGE_B;
; #pragma unroll
;     for (int ks = 0; ks < 4; ++ks) {
;       bf16x8 af[2], bfr[2];
; #pragma unroll
;       for (int mb = 0; mb < 2; ++mb) af[mb] = *(const bf16x8*)(sb + a_base + mb * 4096 + xo[ks]);
; #pragma unroll
;       for (int nb = 0; nb < 2; ++nb) bfr[nb] = *(const bf16x8*)(sb + b_base + nb * 4096 + xo[ks]);
; #pragma unroll
;       for (int mb = 0; mb < 2; ++mb)
; #pragma unroll
;         for (int nb = 0; nb < 2; ++nb)
;           acc[mb][nb] = __builtin_amdgcn_mfma_f32_32x32x16_bf16(af[mb], bfr[nb], acc[mb][nb], 0, 0, 0);
;     }
;     WAIT_V0();
;     __syncthreads();
;   }
	v_mfma_f32_32x32x16_bf16 v[48:63], v[124:127], v[132:135], v[48:63]
	v_mfma_f32_32x32x16_bf16 v[32:47], v[124:127], v[140:143], v[32:47]
	v_mfma_f32_32x32x16_bf16 v[16:31], v[128:131], v[132:135], v[16:31]
	v_mfma_f32_32x32x16_bf16 v[0:15], v[128:131], v[140:143], v[0:15]
	v_mfma_f32_32x32x16_bf16 v[48:63], v[100:103], v[104:107], v[48:63]
	v_mfma_f32_32x32x16_bf16 v[32:47], v[100:103], v[108:111], v[32:47]
	v_mfma_f32_32x32x16_bf16 v[16:31], v[120:123], v[104:107], v[16:31]
	v_mfma_f32_32x32x16_bf16 v[0:15], v[120:123], v[108:111], v[0:15]
	v_lshl_add_u64 v[100:101], v[64:65], 0, s[54:55]
	global_load_lds_dwordx4 v[100:101], off
	v_lshl_add_u64 v[100:101], v[66:67], 0, s[54:55]
	s_mov_b32 m0, s21
	s_nop 0
	global_load_lds_dwordx4 v[100:101], off
	s_mov_b32 m0, s22
	s_nop 0
	global_load_lds_dwordx4 v[96:97], off
	v_lshl_add_u64 v[96:97], v[70:71], 0, s[54:55]
	s_mov_b32 m0, s1
	s_nop 0
	global_load_lds_dwordx4 v[96:97], off
	v_lshl_add_u64 v[96:97], v[72:73], 0, s[54:55]
	s_mov_b32 m0, s16
	s_nop 0
	global_load_lds_dwordx4 v[96:97], off
	v_lshl_add_u64 v[96:97], v[74:75], 0, s[54:55]
	s_mov_b32 m0, s17
	s_nop 0
	global_load_lds_dwordx4 v[96:97], off
	v_lshl_add_u64 v[96:97], v[76:77], 0, s[54:55]
	s_mov_b32 m0, s18
	s_nop 0
	global_load_lds_dwordx4 v[96:97], off
	v_lshl_add_u64 v[96:97], v[78:79], 0, s[54:55]
	s_mov_b32 m0, s19
	s_nop 0
	global_load_lds_dwordx4 v[96:97], off
	ds_read_b128 v[96:99], v80
	ds_read_b128 v[100:103], v82 offset:16384
	ds_read_b128 v[104:107], v82 offset:20480
	s_waitcnt lgkmcnt(0)
	v_mfma_f32_32x32x16_bf16 v[48:63], v[96:99], v[100:103], v[48:63]
	s_mov_b32 m0, s23
	v_mfma_f32_32x32x16_bf16 v[32:47], v[96:99], v[104:107], v[32:47]
	ds_read_b128 v[96:99], v80 offset:4096
	s_waitcnt lgkmcnt(0)
	v_mfma_f32_32x32x16_bf16 v[16:31], v[96:99], v[100:103], v[16:31]
	v_mfma_f32_32x32x16_bf16 v[0:15], v[96:99], v[104:107], v[0:15]
	ds_read_b128 v[96:99], v81
	ds_read_b128 v[100:103], v83 offset:16384
	ds_read_b128 v[104:107], v83 offset:20480
	s_waitcnt lgkmcnt(0)
	v_mfma_f32_32x32x16_bf16 v[48:63], v[96:99], v[100:103], v[48:63]
	v_mfma_f32_32x32x16_bf16 v[32:47], v[96:99], v[104:107], v[32:47]
	ds_read_b128 v[96:99], v81 offset:4096
	s_waitcnt lgkmcnt(0)
	v_mfma_f32_32x32x16_bf16 v[16:31], v[96:99], v[100:103], v[16:31]
	v_mfma_f32_32x32x16_bf16 v[0:15], v[96:99], v[104:107], v[0:15]
	ds_read_b128 v[124:127], v84
	ds_read_b128 v[132:135], v85 offset:16384
	ds_read_b128 v[140:143], v85 offset:20480
	ds_read_b128 v[128:131], v84 offset:4096
	ds_read_b128 v[96:99], v86
	ds_read_b128 v[100:103], v87 offset:16384
	ds_read_b128 v[104:107], v87 offset:20480
	ds_read_b128 v[120:123], v86 offset:4096
	s_waitcnt vmcnt(0)
	s_waitcnt vmcnt(0) lgkmcnt(0)
	s_barrier
	v_mfma_f32_32x32x16_bf16 v[48:63], v[124:127], v[132:135], v[48:63]
	v_mfma_f32_32x32x16_bf16 v[32:47], v[124:127], v[140:143], v[32:47]
	v_mfma_f32_32x32x16_bf16 v[16:31], v[128:131], v[132:135], v[16:31]
	v_mfma_f32_32x32x16_bf16 v[0:15], v[128:131], v[140:143], v[0:15]
	v_mfma_f32_32x32x16_bf16 v[48:63], v[96:99], v[100:103], v[48:63]
	v_mfma_f32_32x32x16_bf16 v[32:47], v[96:99], v[104:107], v[32:47]
	v_mfma_f32_32x32x16_bf16 v[16:31], v[120:123], v[100:103], v[16:31]
	v_mfma_f32_32x32x16_bf16 v[0:15], v[120:123], v[104:107], v[0:15]
	v_lshl_add_u64 v[96:97], v[64:65], 0, s[56:57]
	global_load_lds_dwordx4 v[96:97], off
	v_lshl_add_u64 v[96:97], v[66:67], 0, s[56:57]
	s_mov_b32 m0, s28
	s_nop 0
	global_load_lds_dwordx4 v[96:97], off
	s_mov_b32 m0, s29
	s_nop 0
	global_load_lds_dwordx4 v[88:89], off
	v_lshl_add_u64 v[88:89], v[70:71], 0, s[56:57]
	s_mov_b32 m0, s40
	s_nop 0
	global_load_lds_dwordx4 v[88:89], off
	v_lshl_add_u64 v[88:89], v[72:73], 0, s[56:57]
	s_mov_b32 m0, s41
	s_nop 0
	global_load_lds_dwordx4 v[88:89], off
	v_lshl_add_u64 v[88:89], v[74:75], 0, s[56:57]
	s_mov_b32 m0, s42
	s_nop 0
	global_load_lds_dwordx4 v[88:89], off
	v_lshl_add_u64 v[88:89], v[76:77], 0, s[56:57]
	s_mov_b32 m0, s43
	s_nop 0
	global_load_lds_dwordx4 v[88:89], off
	v_lshl_add_u64 v[88:89], v[78:79], 0, s[56:57]
	s_mov_b32 m0, s44
	s_nop 0
	global_load_lds_dwordx4 v[88:89], off
	ds_read_b128 v[88:91], v80 offset:32768
	ds_read_b128 v[92:95], v82 offset:49152
	ds_read_b128 v[96:99], v82 offset:53248
	s_waitcnt lgkmcnt(0)
	v_mfma_f32_32x32x16_bf16 v[48:63], v[88:91], v[92:95], v[48:63]
	s_mov_b32 m0, s20
	v_mfma_f32_32x32x16_bf16 v[32:47], v[88:91], v[96:99], v[32:47]
	ds_read_b128 v[88:91], v80 offset:36864
	s_waitcnt lgkmcnt(0)
	v_mfma_f32_32x32x16_bf16 v[16:31], v[88:91], v[92:95], v[16:31]
	v_mfma_f32_32x32x16_bf16 v[0:15], v[88:91], v[96:99], v[0:15]
	ds_read_b128 v[88:91], v81 offset:32768
	ds_read_b128 v[92:95], v83 offset:49152
	ds_read_b128 v[96:99], v83 offset:53248
	s_waitcnt lgkmcnt(0)
	v_mfma_f32_32x32x16_bf16 v[48:63], v[88:91], v[92:95], v[48:63]
	v_mfma_f32_32x32x16_bf16 v[32:47], v[88:91], v[96:99], v[32:47]
	ds_read_b128 v[88:91], v81 offset:36864
	s_waitcnt lgkmcnt(0)
	v_mfma_f32_32x32x16_bf16 v[16:31], v[88:91], v[92:95], v[16:31]
	v_mfma_f32_32x32x16_bf16 v[0:15], v[88:91], v[96:99], v[0:15]
	ds_read_b128 v[124:127], v84 offset:32768
	ds_read_b128 v[132:135], v85 offset:49152
	ds_read_b128 v[140:143], v85 offset:53248
	ds_read_b128 v[128:131], v84 offset:36864
	ds_read_b128 v[88:91], v86 offset:32768
	ds_read_b128 v[92:95], v87 offset:49152
	ds_read_b128 v[96:99], v87 offset:53248
	ds_read_b128 v[120:123], v86 offset:36864
	s_waitcnt vmcnt(0)
	s_waitcnt vmcnt(0) lgkmcnt(0)
	s_barrier
; #define WAIT_V0() asm volatile("s_waitcnt vmcnt(0)" ::: "memory")
; DI void gemm_core(char* smem, int nk, const char* Ab, const char* Bb, const unsigned (&aoff)[4], const unsigned (&boff)[4],
;                   f32x16 (&acc)[2][2]) {
;     ...
;   auto stage = [&](int buf, int kt) __attribute__((always_inline)) {
;     const char* ak = Ab + kt * 128;
;     const char* bk = Bb + kt * 128;
;     char* sa = smem + buf * STAGE_B + w * 4096;
; #pragma unroll
;     for (int i = 0; i < 4; ++i) {
;       __builtin_amdgcn_global_load_lds((const unsigned*)(ak + aoff[i]), (unsigned*)(sa + i * 1024), 16, 0, 0);
;       __builtin_amdgcn_global_load_lds((const unsigned*)(bk + boff[i]), (unsigned*)(sa + 16384 + i * 1024), 16, 0, 0);
;     }
;   };
;   stage(0, 0);
;   WAIT_V0();
;   __syncthreads();
;   for (int kt = 0; kt < nk; ++kt) {
;     const int cur = kt & 1;
;     if (kt + 1 < nk) stage(cur ^ 1, kt + 1);
;     const char* sb = smem + cur * STAGE_B;
; #pragma unroll
;     for (int ks = 0; ks < 4; ++ks) {
;       bf16x8 af[2], bfr[2];
; #pragma unroll
;       for (int mb = 0; mb < 2; ++mb) af[mb] = *(const bf16x8*)(sb + a_base + mb * 4096 + xo[ks]);
; #pragma unroll
;       for (int nb = 0; nb < 2; ++nb) bfr[nb] = *(const bf16x8*)(sb + b_base + nb * 4096 + xo[ks]);
; #pragma unroll
;       for (int mb = 0; mb < 2; ++mb)
; #pragma unroll
;         for (int nb = 0; nb < 2; ++nb)
;           acc[mb][nb] = __builtin_amdgcn_mfma_f32_32x32x16_bf16(af[mb], bfr[nb], acc[mb][nb], 0, 0, 0);
;     }
;     WAIT_V0();
;     __syncthreads();
;   }
	v_mfma_f32_32x32x16_bf16 v[48:63], v[124:127], v[132:135], v[48:63]
	v_lshl_add_u64 v[116:117], v[64:65], 0, s[58:59]
	global_load_lds_dwordx4 v[116:117], off
	v_mfma_f32_32x32x16_bf16 v[32:47], v[124:127], v[140:143], v[32:47]
	v_lshl_add_u64 v[118:119], v[66:67], 0, s[58:59]
	s_mov_b32 m0, s21
	s_nop 0
	global_load_lds_dwordx4 v[118:119], off
	v_mfma_f32_32x32x16_bf16 v[16:31], v[128:131], v[132:135], v[16:31]
	v_lshl_add_u64 v[116:117], v[68:69], 0, s[58:59]
	s_mov_b32 m0, s22
	s_nop 0
	global_load_lds_dwordx4 v[116:117], off
	v_mfma_f32_32x32x16_bf16 v[0:15], v[128:131], v[140:143], v[0:15]
	v_lshl_add_u64 v[118:119], v[70:71], 0, s[58:59]
	s_mov_b32 m0, s1
	s_nop 0
	global_load_lds_dwordx4 v[118:119], off
	v_mfma_f32_32x32x16_bf16 v[48:63], v[88:91], v[92:95], v[48:63]
	v_lshl_add_u64 v[116:117], v[72:73], 0, s[58:59]
	s_mov_b32 m0, s16
	s_nop 0
	global_load_lds_dwordx4 v[116:117], off
	v_mfma_f32_32x32x16_bf16 v[32:47], v[88:91], v[96:99], v[32:47]
	v_lshl_add_u64 v[118:119], v[74:75], 0, s[58:59]
	s_mov_b32 m0, s17
	s_nop 0
	global_load_lds_dwordx4 v[118:119], off
	v_mfma_f32_32x32x16_bf16 v[16:31], v[120:123], v[92:95], v[16:31]
	v_lshl_add_u64 v[116:117], v[76:77], 0, s[58:59]
	s_mov_b32 m0, s18
	s_nop 0
	global_load_lds_dwordx4 v[116:117], off
	v_mfma_f32_32x32x16_bf16 v[0:15], v[120:123], v[96:99], v[0:15]
	v_lshl_add_u64 v[118:119], v[78:79], 0, s[58:59]
	s_mov_b32 m0, s19
	s_nop 0
	global_load_lds_dwordx4 v[118:119], off
	ds_read_b128 v[88:91], v80
	ds_read_b128 v[92:95], v82 offset:16384
	ds_read_b128 v[96:99], v82 offset:20480
	s_waitcnt lgkmcnt(0)
	v_mfma_f32_32x32x16_bf16 v[48:63], v[88:91], v[92:95], v[48:63]
	s_mov_b32 m0, s23
	v_mfma_f32_32x32x16_bf16 v[32:47], v[88:91], v[96:99], v[32:47]
	ds_read_b128 v[88:91], v80 offset:4096
	s_waitcnt lgkmcnt(0)
	v_mfma_f32_32x32x16_bf16 v[16:31], v[88:91], v[92:95], v[16:31]
	v_mfma_f32_32x32x16_bf16 v[0:15], v[88:91], v[96:99], v[0:15]
	ds_read_b128 v[88:91], v81
	ds_read_b128 v[92:95], v83 offset:16384
	ds_read_b128 v[96:99], v83 offset:20480
	s_waitcnt lgkmcnt(0)
	v_mfma_f32_32x32x16_bf16 v[48:63], v[88:91], v[92:95], v[48:63]
	v_mfma_f32_32x32x16_bf16 v[32:47], v[88:91], v[96:99], v[32:47]
	ds_read_b128 v[88:91], v81 offset:4096
	s_waitcnt lgkmcnt(0)
	v_mfma_f32_32x32x16_bf16 v[16:31], v[88:91], v[92:95], v[16:31]
	v_mfma_f32_32x32x16_bf16 v[0:15], v[88:91], v[96:99], v[0:15]
	ds_read_b128 v[124:127], v84
	ds_read_b128 v[132:135], v85 offset:16384
	ds_read_b128 v[140:143], v85 offset:20480
	ds_read_b128 v[128:131], v84 offset:4096
	ds_read_b128 v[88:91], v86
	ds_read_b128 v[92:95], v87 offset:16384
	ds_read_b128 v[96:99], v87 offset:20480
	ds_read_b128 v[120:123], v86 offset:4096
	s_waitcnt vmcnt(0)
	s_waitcnt vmcnt(0) lgkmcnt(0)
	s_barrier
	v_mfma_f32_32x32x16_bf16 v[48:63], v[124:127], v[132:135], v[48:63]
	v_lshl_add_u64 v[116:117], v[64:65], 0, s[60:61]
	global_load_lds_dwordx4 v[116:117], off
	v_mfma_f32_32x32x16_bf16 v[32:47], v[124:127], v[140:143], v[32:47]
	v_lshl_add_u64 v[118:119], v[66:67], 0, s[60:61]
	s_mov_b32 m0, s28
	s_nop 0
	global_load_lds_dwordx4 v[118:119], off
	v_mfma_f32_32x32x16_bf16 v[16:31], v[128:131], v[132:135], v[16:31]
	v_lshl_add_u64 v[116:117], v[68:69], 0, s[60:61]
	s_mov_b32 m0, s29
	s_nop 0
	global_load_lds_dwordx4 v[116:117], off
	v_mfma_f32_32x32x16_bf16 v[0:15], v[128:131], v[140:143], v[0:15]
	v_lshl_add_u64 v[118:119], v[70:71], 0, s[60:61]
	s_mov_b32 m0, s40
	s_nop 0
	global_load_lds_dwordx4 v[118:119], off
	v_mfma_f32_32x32x16_bf16 v[48:63], v[88:91], v[92:95], v[48:63]
	v_lshl_add_u64 v[116:117], v[72:73], 0, s[60:61]
	s_mov_b32 m0, s41
	s_nop 0
	global_load_lds_dwordx4 v[116:117], off
	v_mfma_f32_32x32x16_bf16 v[32:47], v[88:91], v[96:99], v[32:47]
	v_lshl_add_u64 v[118:119], v[74:75], 0, s[60:61]
	s_mov_b32 m0, s42
	s_nop 0
	global_load_lds_dwordx4 v[118:119], off
	v_mfma_f32_32x32x16_bf16 v[16:31], v[120:123], v[92:95], v[16:31]
	v_lshl_add_u64 v[116:117], v[76:77], 0, s[60:61]
	s_mov_b32 m0, s43
	s_nop 0
	global_load_lds_dwordx4 v[116:117], off
	v_mfma_f32_32x32x16_bf16 v[0:15], v[120:123], v[96:99], v[0:15]
	v_lshl_add_u64 v[118:119], v[78:79], 0, s[60:61]
	s_mov_b32 m0, s44
	s_nop 0
	global_load_lds_dwordx4 v[118:119], off
	ds_read_b128 v[88:91], v80 offset:32768
	ds_read_b128 v[92:95], v82 offset:49152
	ds_read_b128 v[96:99], v82 offset:53248
	s_waitcnt lgkmcnt(0)
	v_mfma_f32_32x32x16_bf16 v[48:63], v[88:91], v[92:95], v[48:63]
	s_mov_b32 m0, s20
	v_mfma_f32_32x32x16_bf16 v[32:47], v[88:91], v[96:99], v[32:47]
	ds_read_b128 v[88:91], v80 offset:36864
	s_waitcnt lgkmcnt(0)
	v_mfma_f32_32x32x16_bf16 v[16:31], v[88:91], v[92:95], v[16:31]
	v_mfma_f32_32x32x16_bf16 v[0:15], v[88:91], v[96:99], v[0:15]
	ds_read_b128 v[88:91], v81 offset:32768
	ds_read_b128 v[92:95], v83 offset:49152
	ds_read_b128 v[96:99], v83 offset:53248
	s_waitcnt lgkmcnt(0)
	v_mfma_f32_32x32x16_bf16 v[48:63], v[88:91], v[92:95], v[48:63]
	v_mfma_f32_32x32x16_bf16 v[32:47], v[88:91], v[96:99], v[32:47]
	ds_read_b128 v[88:91], v81 offset:36864
	s_waitcnt lgkmcnt(0)
	v_mfma_f32_32x32x16_bf16 v[16:31], v[88:91], v[92:95], v[16:31]
	v_mfma_f32_32x32x16_bf16 v[0:15], v[88:91], v[96:99], v[0:15]
	ds_read_b128 v[124:127], v84 offset:32768
	ds_read_b128 v[132:135], v85 offset:49152
	ds_read_b128 v[140:143], v85 offset:53248
	ds_read_b128 v[128:131], v84 offset:36864
	ds_read_b128 v[88:91], v86 offset:32768
	ds_read_b128 v[92:95], v87 offset:49152
	ds_read_b128 v[96:99], v87 offset:53248
	ds_read_b128 v[120:123], v86 offset:36864
	s_waitcnt vmcnt(0)
	s_waitcnt vmcnt(0) lgkmcnt(0)
	s_barrier
; #define WAIT_V0() asm volatile("s_waitcnt vmcnt(0)" ::: "memory")
; DI void gemm_core(char* smem, int nk, const char* Ab, const char* Bb, const unsigned (&aoff)[4], const unsigned (&boff)[4],
;                   f32x16 (&acc)[2][2]) {
;     ...
;   auto stage = [&](int buf, int kt) __attribute__((always_inline)) {
;     const char* ak = Ab + kt * 128;
;     const char* bk = Bb + kt * 128;
;     char* sa = smem + buf * STAGE_B + w * 4096;
; #pragma unroll
;     for (int i = 0; i < 4; ++i) {
;       __builtin_amdgcn_global_load_lds((const unsigned*)(ak + aoff[i]), (unsigned*)(sa + i * 1024), 16, 0, 0);
;       __builtin_amdgcn_global_load_lds((const unsigned*)(bk + boff[i]), (unsigned*)(sa + 16384 + i * 1024), 16, 0, 0);
;     }
;   };
;   stage(0, 0);
;   WAIT_V0();
;   __syncthreads();
;   for (int kt = 0; kt < nk; ++kt) {
;     const int cur = kt & 1;
;     if (kt + 1 < nk) stage(cur ^ 1, kt + 1);
;     const char* sb = smem + cur * STAGE_B;
; #pragma unroll
;     for (int ks = 0; ks < 4; ++ks) {
;       bf16x8 af[2], bfr[2];
; #pragma unroll
;       for (int mb = 0; mb < 2; ++mb) af[mb] = *(const bf16x8*)(sb + a_base + mb * 4096 + xo[ks]);
; #pragma unroll
;       for (int nb = 0; nb < 2; ++nb) bfr[nb] = *(const bf16x8*)(sb + b_base + nb * 4096 + xo[ks]);
; #pragma unroll
;       for (int mb = 0; mb < 2; ++mb)
; #pragma unroll
;         for (int nb = 0; nb < 2; ++nb)
;           acc[mb][nb] = __builtin_amdgcn_mfma_f32_32x32x16_bf16(af[mb], bfr[nb], acc[mb][nb], 0, 0, 0);
;     }
;     WAIT_V0();
;     __syncthreads();
;   }
	v_mfma_f32_32x32x16_bf16 v[48:63], v[124:127], v[132:135], v[48:63]
	v_lshl_add_u64 v[116:117], v[64:65], 0, s[62:63]
	global_load_lds_dwordx4 v[116:117], off
	v_mfma_f32_32x32x16_bf16 v[32:47], v[124:127], v[140:143], v[32:47]
	v_lshl_add_u64 v[118:119], v[66:67], 0, s[62:63]
	s_mov_b32 m0, s21
	s_nop 0
	global_load_lds_dwordx4 v[118:119], off
	v_mfma_f32_32x32x16_bf16 v[16:31], v[128:131], v[132:135], v[16:31]
	v_lshl_add_u64 v[116:117], v[68:69], 0, s[62:63]
	s_mov_b32 m0, s22
	s_nop 0
	global_load_lds_dwordx4 v[116:117], off
	v_mfma_f32_32x32x16_bf16 v[0:15], v[128:131], v[140:143], v[0:15]
	v_lshl_add_u64 v[118:119], v[70:71], 0, s[62:63]
	s_mov_b32 m0, s1
	s_nop 0
	global_load_lds_dwordx4 v[118:119], off
	v_mfma_f32_32x32x16_bf16 v[48:63], v[88:91], v[92:95], v[48:63]
	v_lshl_add_u64 v[116:117], v[72:73], 0, s[62:63]
	s_mov_b32 m0, s16
	s_nop 0
	global_load_lds_dwordx4 v[116:117], off
	v_mfma_f32_32x32x16_bf16 v[32:47], v[88:91], v[96:99], v[32:47]
	v_lshl_add_u64 v[118:119], v[74:75], 0, s[62:63]
	s_mov_b32 m0, s17
	s_nop 0
	global_load_lds_dwordx4 v[118:119], off
	v_mfma_f32_32x32x16_bf16 v[16:31], v[120:123], v[92:95], v[16:31]
	v_lshl_add_u64 v[116:117], v[76:77], 0, s[62:63]
	s_mov_b32 m0, s18
	s_nop 0
	global_load_lds_dwordx4 v[116:117], off
	v_mfma_f32_32x32x16_bf16 v[0:15], v[120:123], v[96:99], v[0:15]
	v_lshl_add_u64 v[118:119], v[78:79], 0, s[62:63]
	s_mov_b32 m0, s19
	s_nop 0
	global_load_lds_dwordx4 v[118:119], off
	ds_read_b128 v[88:91], v80
	ds_read_b128 v[92:95], v82 offset:16384
	ds_read_b128 v[96:99], v82 offset:20480
	s_waitcnt lgkmcnt(0)
	v_mfma_f32_32x32x16_bf16 v[48:63], v[88:91], v[92:95], v[48:63]
	s_mov_b32 m0, s23
	v_mfma_f32_32x32x16_bf16 v[32:47], v[88:91], v[96:99], v[32:47]
	ds_read_b128 v[88:91], v80 offset:4096
	s_waitcnt lgkmcnt(0)
	v_mfma_f32_32x32x16_bf16 v[16:31], v[88:91], v[92:95], v[16:31]
	v_mfma_f32_32x32x16_bf16 v[0:15], v[88:91], v[96:99], v[0:15]
	ds_read_b128 v[88:91], v81
	ds_read_b128 v[92:95], v83 offset:16384
	ds_read_b128 v[96:99], v83 offset:20480
	s_waitcnt lgkmcnt(0)
	v_mfma_f32_32x32x16_bf16 v[48:63], v[88:91], v[92:95], v[48:63]
	v_mfma_f32_32x32x16_bf16 v[32:47], v[88:91], v[96:99], v[32:47]
	ds_read_b128 v[88:91], v81 offset:4096
	s_waitcnt lgkmcnt(0)
	v_mfma_f32_32x32x16_bf16 v[16:31], v[88:91], v[92:95], v[16:31]
	v_mfma_f32_32x32x16_bf16 v[0:15], v[88:91], v[96:99], v[0:15]
	ds_read_b128 v[124:127], v84
	ds_read_b128 v[132:135], v85 offset:16384
	ds_read_b128 v[140:143], v85 offset:20480
	ds_read_b128 v[128:131], v84 offset:4096
	ds_read_b128 v[88:91], v86
	ds_read_b128 v[92:95], v87 offset:16384
	ds_read_b128 v[96:99], v87 offset:20480
	ds_read_b128 v[120:123], v86 offset:4096
	s_waitcnt vmcnt(0)
	s_waitcnt vmcnt(0) lgkmcnt(0)
	s_barrier
	v_mfma_f32_32x32x16_bf16 v[48:63], v[124:127], v[132:135], v[48:63]
	v_mfma_f32_32x32x16_bf16 v[32:47], v[124:127], v[140:143], v[32:47]
	v_mfma_f32_32x32x16_bf16 v[16:31], v[128:131], v[132:135], v[16:31]
	v_mfma_f32_32x32x16_bf16 v[0:15], v[128:131], v[140:143], v[0:15]
	v_mfma_f32_32x32x16_bf16 v[48:63], v[88:91], v[92:95], v[48:63]
	v_mfma_f32_32x32x16_bf16 v[32:47], v[88:91], v[96:99], v[32:47]
	v_mfma_f32_32x32x16_bf16 v[16:31], v[120:123], v[92:95], v[16:31]
	v_mfma_f32_32x32x16_bf16 v[0:15], v[120:123], v[96:99], v[0:15]
	v_lshl_add_u64 v[88:89], v[64:65], 0, s[64:65]
	global_load_lds_dwordx4 v[88:89], off
	v_lshl_add_u64 v[88:89], v[66:67], 0, s[64:65]
	s_mov_b32 m0, s28
	v_lshl_add_u64 v[64:65], v[64:65], 0, s[66:67]
	global_load_lds_dwordx4 v[88:89], off
	v_lshl_add_u64 v[88:89], v[68:69], 0, s[64:65]
	s_mov_b32 m0, s29
	s_nop 0
	global_load_lds_dwordx4 v[88:89], off
	v_lshl_add_u64 v[88:89], v[70:71], 0, s[64:65]
	s_mov_b32 m0, s40
	s_nop 0
	global_load_lds_dwordx4 v[88:89], off
	v_lshl_add_u64 v[88:89], v[72:73], 0, s[64:65]
	s_mov_b32 m0, s41
	s_nop 0
	global_load_lds_dwordx4 v[88:89], off
	v_lshl_add_u64 v[88:89], v[74:75], 0, s[64:65]
	s_mov_b32 m0, s42
	s_nop 0
	global_load_lds_dwordx4 v[88:89], off
	v_lshl_add_u64 v[88:89], v[76:77], 0, s[64:65]
	s_mov_b32 m0, s43
	s_nop 0
	global_load_lds_dwordx4 v[88:89], off
	v_lshl_add_u64 v[88:89], v[78:79], 0, s[64:65]
	s_mov_b32 m0, s44
	s_nop 0
	global_load_lds_dwordx4 v[88:89], off
	ds_read_b128 v[88:91], v80 offset:32768
	ds_read_b128 v[92:95], v82 offset:49152
	ds_read_b128 v[96:99], v82 offset:53248
	s_waitcnt lgkmcnt(0)
	v_mfma_f32_32x32x16_bf16 v[48:63], v[88:91], v[92:95], v[48:63]
	s_mov_b32 m0, s20
	v_mfma_f32_32x32x16_bf16 v[32:47], v[88:91], v[96:99], v[32:47]
	ds_read_b128 v[88:91], v80 offset:36864
	s_waitcnt lgkmcnt(0)
	v_mfma_f32_32x32x16_bf16 v[16:31], v[88:91], v[92:95], v[16:31]
	v_mfma_f32_32x32x16_bf16 v[0:15], v[88:91], v[96:99], v[0:15]
	ds_read_b128 v[88:91], v81 offset:32768
	ds_read_b128 v[92:95], v83 offset:49152
	ds_read_b128 v[96:99], v83 offset:53248
	s_waitcnt lgkmcnt(0)
	v_mfma_f32_32x32x16_bf16 v[48:63], v[88:91], v[92:95], v[48:63]
	v_mfma_f32_32x32x16_bf16 v[32:47], v[88:91], v[96:99], v[32:47]
	ds_read_b128 v[88:91], v81 offset:36864
	s_waitcnt lgkmcnt(0)
	v_mfma_f32_32x32x16_bf16 v[16:31], v[88:91], v[92:95], v[16:31]
	v_mfma_f32_32x32x16_bf16 v[0:15], v[88:91], v[96:99], v[0:15]
	ds_read_b128 v[88:91], v84 offset:32768
	ds_read_b128 v[92:95], v85 offset:49152
	ds_read_b128 v[96:99], v85 offset:53248
	s_waitcnt lgkmcnt(0)
	v_mfma_f32_32x32x16_bf16 v[48:63], v[88:91], v[92:95], v[48:63]
	v_mfma_f32_32x32x16_bf16 v[32:47], v[88:91], v[96:99], v[32:47]
	ds_read_b128 v[88:91], v84 offset:36864
	s_waitcnt lgkmcnt(0)
	v_mfma_f32_32x32x16_bf16 v[16:31], v[88:91], v[92:95], v[16:31]
	v_mfma_f32_32x32x16_bf16 v[0:15], v[88:91], v[96:99], v[0:15]
	ds_read_b128 v[88:91], v86 offset:32768
	ds_read_b128 v[92:95], v87 offset:49152
	ds_read_b128 v[96:99], v87 offset:53248
	s_waitcnt lgkmcnt(0)
	v_mfma_f32_32x32x16_bf16 v[48:63], v[88:91], v[92:95], v[48:63]
	v_mfma_f32_32x32x16_bf16 v[32:47], v[88:91], v[96:99], v[32:47]
	ds_read_b128 v[88:91], v86 offset:36864
	s_waitcnt vmcnt(0)
	s_waitcnt vmcnt(0) lgkmcnt(0)
	s_barrier
; DI void gemm_core(char* smem, int nk, const char* Ab, const char* Bb, const unsigned (&aoff)[4], const unsigned (&boff)[4],
;                   f32x16 (&acc)[2][2]) {
;     ...
;   auto stage = [&](int buf, int kt) __attribute__((always_inline)) {
;     const char* ak = Ab + kt * 128;
;     const char* bk = Bb + kt * 128;
;     char* sa = smem + buf * STAGE_B + w * 4096;
; #pragma unroll
;     for (int i = 0; i < 4; ++i) {
;       __builtin_amdgcn_global_load_lds((const unsigned*)(ak + aoff[i]), (unsigned*)(sa + i * 1024), 16, 0, 0);
;       __builtin_amdgcn_global_load_lds((const unsigned*)(bk + boff[i]), (unsigned*)(sa + 16384 + i * 1024), 16, 0, 0);
;     }
;   };
;   stage(0, 0);
;   WAIT_V0();
;   __syncthreads();
;   for (int kt = 0; kt < nk; ++kt) {
;     const int cur = kt & 1;
;     if (kt + 1 < nk) stage(cur ^ 1, kt + 1);
;     const char* sb = smem + cur * STAGE_B;
; #pragma unroll
;     for (int ks = 0; ks < 4; ++ks) {
;       bf16x8 af[2], bfr[2];
; #pragma unroll
;       for (int mb = 0; mb < 2; ++mb) af[mb] = *(const bf16x8*)(sb + a_base + mb * 4096 + xo[ks]);
; #pragma unroll
;       for (int nb = 0; nb < 2; ++nb) bfr[nb] = *(const bf16x8*)(sb + b_base + nb * 4096 + xo[ks]);
; #pragma unroll
;       for (int mb = 0; mb < 2; ++mb)
; #pragma unroll
;         for (int nb = 0; nb < 2; ++nb)
;           acc[mb][nb] = __builtin_amdgcn_mfma_f32_32x32x16_bf16(af[mb], bfr[nb], acc[mb][nb], 0, 0, 0);
;     }
;     WAIT_V0();
;     __syncthreads();
;   }
; template <class F>
; DI void epi_foreach(const f32x16 (&acc)[2][2], F f) {
;   const int lane = ltid() & 63, w = ltid() >> 6;
;   const int wm = w >> 1, wn = w & 1;
; #pragma unroll
;   for (int mb = 0; mb < 2; ++mb)
; #pragma unroll
;     for (int nb = 0; nb < 2; ++nb)
; #pragma unroll
;       for (int r = 0; r < 16; ++r) {
;         const int row = wm * 64 + mb * 32 + (r & 3) + 8 * (r >> 2) + 4 * (lane >> 5);
;         const int col = wn * 64 + nb * 32 + (lane & 31);
;         f(row, col, acc[mb][nb][r]);
;         if ((r & 7) == 7) __builtin_amdgcn_sched_barrier(0);
;       }
; }
; DI void phase_gemm_in(const Params& P, int layer, char* smem) {
;     ...
;     epi_foreach(acc, [&](int row, int col, float v) __attribute__((always_inline)) {
;       const int c = n0 + col;
;       Cs[row * 136 + col] = (c >= C_QI && c < C_CQ) ? f2h(v) : f2bf(v);
;     });
	global_load_lds_dwordx4 v[64:65], off
	v_lshl_add_u64 v[64:65], v[66:67], 0, s[66:67]
	s_mov_b32 m0, s21
	v_mfma_f32_32x32x16_bf16 v[16:31], v[88:91], v[92:95], v[16:31]
	global_load_lds_dwordx4 v[64:65], off
	v_lshl_add_u64 v[64:65], v[68:69], 0, s[66:67]
	s_mov_b32 m0, s22
	s_nop 0
	global_load_lds_dwordx4 v[64:65], off
	v_lshl_add_u64 v[64:65], v[70:71], 0, s[66:67]
	s_mov_b32 m0, s1
	v_mfma_f32_32x32x16_bf16 v[0:15], v[88:91], v[96:99], v[0:15]
	global_load_lds_dwordx4 v[64:65], off
	v_lshl_add_u64 v[64:65], v[72:73], 0, s[66:67]
	s_mov_b32 m0, s16
	v_mov_b32_e32 v96, v161
	global_load_lds_dwordx4 v[64:65], off
	v_lshl_add_u64 v[64:65], v[74:75], 0, s[66:67]
	s_mov_b32 m0, s17
	v_mov_b32_e32 v97, v161
	global_load_lds_dwordx4 v[64:65], off
	v_lshl_add_u64 v[64:65], v[76:77], 0, s[66:67]
	s_mov_b32 m0, s18
	s_add_i32 s1, s10, 0xfffffa00
	global_load_lds_dwordx4 v[64:65], off
	v_lshl_add_u64 v[64:65], v[78:79], 0, s[66:67]
	s_mov_b32 m0, s19
	s_nop 0
	global_load_lds_dwordx4 v[64:65], off
	ds_read_b128 v[64:67], v80
	ds_read_b128 v[68:71], v82 offset:16384
	ds_read_b128 v[72:75], v82 offset:20480
	s_waitcnt lgkmcnt(0)
	v_mfma_f32_32x32x16_bf16 v[48:63], v[64:67], v[68:71], v[48:63]
	v_mfma_f32_32x32x16_bf16 v[32:47], v[64:67], v[72:75], v[32:47]
	ds_read_b128 v[64:67], v80 offset:4096
	s_waitcnt lgkmcnt(0)
	v_mfma_f32_32x32x16_bf16 v[16:31], v[64:67], v[68:71], v[16:31]
	v_mfma_f32_32x32x16_bf16 v[0:15], v[64:67], v[72:75], v[0:15]
	ds_read_b128 v[64:67], v81
	ds_read_b128 v[68:71], v83 offset:16384
	ds_read_b128 v[72:75], v83 offset:20480
	s_waitcnt lgkmcnt(0)
	v_mfma_f32_32x32x16_bf16 v[48:63], v[64:67], v[68:71], v[48:63]
	v_mfma_f32_32x32x16_bf16 v[32:47], v[64:67], v[72:75], v[32:47]
	ds_read_b128 v[64:67], v81 offset:4096
	s_waitcnt lgkmcnt(0)
	v_mfma_f32_32x32x16_bf16 v[16:31], v[64:67], v[68:71], v[16:31]
	v_mfma_f32_32x32x16_bf16 v[0:15], v[64:67], v[72:75], v[0:15]
	ds_read_b128 v[124:127], v84
	ds_read_b128 v[132:135], v85 offset:16384
	ds_read_b128 v[140:143], v85 offset:20480
	ds_read_b128 v[128:131], v84 offset:4096
	ds_read_b128 v[64:67], v86
	ds_read_b128 v[68:71], v87 offset:16384
	ds_read_b128 v[72:75], v87 offset:20480
	ds_read_b128 v[120:123], v86 offset:4096
	s_waitcnt vmcnt(0)
	s_waitcnt vmcnt(0) lgkmcnt(0)
	s_barrier
	v_mfma_f32_32x32x16_bf16 v[48:63], v[124:127], v[132:135], v[48:63]
	v_mfma_f32_32x32x16_bf16 v[32:47], v[124:127], v[140:143], v[32:47]
	v_mfma_f32_32x32x16_bf16 v[16:31], v[128:131], v[132:135], v[16:31]
	v_mfma_f32_32x32x16_bf16 v[0:15], v[128:131], v[140:143], v[0:15]
	v_mfma_f32_32x32x16_bf16 v[48:63], v[64:67], v[68:71], v[48:63]
	v_mfma_f32_32x32x16_bf16 v[32:47], v[64:67], v[72:75], v[32:47]
	v_mfma_f32_32x32x16_bf16 v[16:31], v[120:123], v[68:71], v[16:31]
	v_mfma_f32_32x32x16_bf16 v[0:15], v[120:123], v[72:75], v[0:15]
	ds_read_b128 v[64:67], v80 offset:32768
	ds_read_b128 v[68:71], v82 offset:49152
	ds_read_b128 v[72:75], v82 offset:53248
	s_waitcnt lgkmcnt(1)
	v_mfma_f32_32x32x16_bf16 v[48:63], v[64:67], v[68:71], v[48:63]
	s_waitcnt lgkmcnt(0)
	v_mfma_f32_32x32x16_bf16 v[32:47], v[64:67], v[72:75], v[32:47]
	ds_read_b128 v[64:67], v80 offset:36864
	s_waitcnt lgkmcnt(0)
	v_mfma_f32_32x32x16_bf16 v[16:31], v[64:67], v[68:71], v[16:31]
	v_mfma_f32_32x32x16_bf16 v[0:15], v[64:67], v[72:75], v[0:15]
	ds_read_b128 v[64:67], v81 offset:32768
	ds_read_b128 v[68:71], v83 offset:49152
	ds_read_b128 v[72:75], v83 offset:53248
	s_waitcnt lgkmcnt(1)
	v_mfma_f32_32x32x16_bf16 v[48:63], v[64:67], v[68:71], v[48:63]
	s_waitcnt lgkmcnt(0)
	v_mfma_f32_32x32x16_bf16 v[32:47], v[64:67], v[72:75], v[32:47]
	ds_read_b128 v[64:67], v81 offset:36864
	s_waitcnt lgkmcnt(0)
	v_mfma_f32_32x32x16_bf16 v[16:31], v[64:67], v[68:71], v[16:31]
	ds_read_b128 v[68:71], v84 offset:32768
	ds_read_b128 v[76:79], v84 offset:36864
	v_mfma_f32_32x32x16_bf16 v[0:15], v[64:67], v[72:75], v[0:15]
	ds_read_b128 v[64:67], v85 offset:49152
	ds_read_b128 v[72:75], v85 offset:53248
	ds_read_b128 v[80:83], v86 offset:32768
	ds_read_b128 v[88:91], v86 offset:36864
	ds_read_b128 v[92:95], v87 offset:49152
	ds_read_b128 v[84:87], v87 offset:53248
	s_waitcnt vmcnt(0)
	s_waitcnt lgkmcnt(0)
	s_barrier
	v_mfma_f32_32x32x16_bf16 v[48:63], v[68:71], v[64:67], v[48:63]
	v_mfma_f32_32x32x16_bf16 v[48:63], v[80:83], v[92:95], v[48:63]
	v_mfma_f32_32x32x16_bf16 v[32:47], v[68:71], v[72:75], v[32:47]
	v_lshrrev_b32_e32 v69, 3, v96
	v_lshrrev_b32_e32 v68, 1, v97
	v_and_b32_e32 v69, 4, v69
	v_and_b32_e32 v70, 31, v96
	v_and_or_b32 v68, v68, s7, v69
	s_nop 5
	v_cvt_f16_f32_e32 v69, v48
	v_and_or_b32 v70, v97, 64, v70
	v_or_b32_e32 v71, s1, v70
	v_cmp_gt_u32_e64 s[40:41], s45, v71
	v_cvt_pk_bf16_f32 v48, v48, s0
	v_mfma_f32_32x32x16_bf16 v[16:31], v[76:79], v[64:67], v[16:31]
	v_cndmask_b32_e64 v69, v48, v69, s[40:41]
	v_mul_lo_u32 v48, v68, s97
	v_cvt_f16_f32_e32 v68, v49
	v_cvt_pk_bf16_f32 v49, v49, s0
	v_lshl_add_u32 v48, v70, 1, v48
	v_cvt_f16_f32_e32 v64, v51
	v_cndmask_b32_e64 v49, v49, v68, s[40:41]
	ds_write_b16 v48, v49 offset:272
	v_cvt_f16_f32_e32 v49, v50
	v_cvt_pk_bf16_f32 v50, v50, s0
	v_mfma_f32_32x32x16_bf16 v[0:15], v[76:79], v[72:75], v[0:15]
	ds_write_b16 v48, v69
	v_cndmask_b32_e64 v49, v50, v49, s[40:41]
	ds_write_b16 v48, v49 offset:544
	v_cvt_pk_bf16_f32 v49, v51, s0
	v_cndmask_b32_e64 v49, v49, v64, s[40:41]
	ds_write_b16 v48, v49 offset:816
	v_cvt_f16_f32_e32 v49, v52
	v_cvt_f16_f32_e32 v51, v53
	v_cvt_pk_bf16_f32 v50, v52, s0
	v_mfma_f32_32x32x16_bf16 v[32:47], v[80:83], v[84:87], v[32:47]
	v_cndmask_b32_e64 v49, v50, v49, s[40:41]
	v_cvt_f16_f32_e32 v50, v54
	ds_write_b16 v48, v49 offset:2176
	v_cvt_pk_bf16_f32 v49, v53, s0
; DI int ltid() { int t = threadIdx.x; asm volatile("" : "+v"(t)); return t; }
; template <class F>
; DI void epi_foreach(const f32x16 (&acc)[2][2], F f) {
;   const int lane = ltid() & 63, w = ltid() >> 6;
;   const int wm = w >> 1, wn = w & 1;
; #pragma unroll
;   for (int mb = 0; mb < 2; ++mb)
; #pragma unroll
;     for (int nb = 0; nb < 2; ++nb)
; #pragma unroll
;       for (int r = 0; r < 16; ++r) {
;         const int row = wm * 64 + mb * 32 + (r & 3) + 8 * (r >> 2) + 4 * (lane >> 5);
;         const int col = wn * 64 + nb * 32 + (lane & 31);
;         f(row, col, acc[mb][nb][r]);
;         if ((r & 7) == 7) __builtin_amdgcn_sched_barrier(0);
;       }
; }
; DI void phase_gemm_in(const Params& P, int layer, char* smem) {
;     ...
;     epi_foreach(acc, [&](int row, int col, float v) __attribute__((always_inline)) {
;       const int c = n0 + col;
;       Cs[row * 136 + col] = (c >= C_QI && c < C_CQ) ? f2h(v) : f2bf(v);
;     });
	v_cndmask_b32_e64 v49, v49, v51, s[40:41]
	v_cvt_f16_f32_e32 v51, v55
	ds_write_b16 v48, v49 offset:2448
	v_cvt_pk_bf16_f32 v49, v54, s0
	v_cndmask_b32_e64 v49, v49, v50, s[40:41]
	ds_write_b16 v48, v49 offset:2720
	v_cvt_pk_bf16_f32 v49, v55, s0
	v_cndmask_b32_e64 v49, v49, v51, s[40:41]
	v_mfma_f32_32x32x16_bf16 v[16:31], v[88:91], v[92:95], v[16:31]
	ds_write_b16 v48, v49 offset:2992
	v_mfma_f32_32x32x16_bf16 v[0:15], v[88:91], v[84:87], v[0:15]
	v_cvt_f16_f32_e32 v49, v56
	v_cvt_pk_bf16_f32 v50, v56, s0
	v_cndmask_b32_e64 v49, v50, v49, s[40:41]
	ds_write_b16 v48, v49 offset:4352
	v_cvt_f16_f32_e32 v49, v57
	v_cvt_pk_bf16_f32 v50, v57, s0
	v_cndmask_b32_e64 v49, v50, v49, s[40:41]
	ds_write_b16 v48, v49 offset:4624
	v_cvt_f16_f32_e32 v49, v58
	v_cvt_pk_bf16_f32 v50, v58, s0
	v_cndmask_b32_e64 v49, v50, v49, s[40:41]
	ds_write_b16 v48, v49 offset:4896
	v_cvt_f16_f32_e32 v49, v59
	v_cvt_pk_bf16_f32 v50, v59, s0
	v_cndmask_b32_e64 v49, v50, v49, s[40:41]
	ds_write_b16 v48, v49 offset:5168
	v_cvt_f16_f32_e32 v49, v60
	v_cvt_pk_bf16_f32 v50, v60, s0
	v_cndmask_b32_e64 v49, v50, v49, s[40:41]
	ds_write_b16 v48, v49 offset:6528
	v_cvt_f16_f32_e32 v49, v61
	v_cvt_pk_bf16_f32 v50, v61, s0
	v_cndmask_b32_e64 v49, v50, v49, s[40:41]
	ds_write_b16 v48, v49 offset:6800
	v_cvt_f16_f32_e32 v49, v62
	v_cvt_pk_bf16_f32 v50, v62, s0
	v_cndmask_b32_e64 v49, v50, v49, s[40:41]
	ds_write_b16 v48, v49 offset:7072
	v_cvt_f16_f32_e32 v49, v63
	v_cvt_pk_bf16_f32 v50, v63, s0
	v_cndmask_b32_e64 v49, v50, v49, s[40:41]
	ds_write_b16 v48, v49 offset:7344
	s_add_i32 s1, s10, 0xfffffa20
	v_or_b32_e32 v49, s1, v70
	v_cmp_gt_u32_e32 vcc, s45, v49
	v_cvt_f16_f32_e32 v49, v32
	v_cvt_pk_bf16_f32 v32, v32, s0
	v_cndmask_b32_e32 v32, v32, v49, vcc
	ds_write_b16 v48, v32 offset:64
	v_cvt_f16_f32_e32 v32, v33
	v_cvt_pk_bf16_f32 v33, v33, s0
	v_cndmask_b32_e32 v32, v33, v32, vcc
	ds_write_b16 v48, v32 offset:336
	v_cvt_f16_f32_e32 v32, v34
	v_cvt_pk_bf16_f32 v33, v34, s0
	v_cndmask_b32_e32 v32, v33, v32, vcc
	ds_write_b16 v48, v32 offset:608
	v_cvt_f16_f32_e32 v32, v35
	v_cvt_pk_bf16_f32 v33, v35, s0
	v_cndmask_b32_e32 v32, v33, v32, vcc
	ds_write_b16 v48, v32 offset:880
	v_cvt_f16_f32_e32 v32, v36
	v_cvt_pk_bf16_f32 v33, v36, s0
	v_cndmask_b32_e32 v32, v33, v32, vcc
	ds_write_b16 v48, v32 offset:2240
	v_cvt_f16_f32_e32 v32, v37
	v_cvt_pk_bf16_f32 v33, v37, s0
	v_cndmask_b32_e32 v32, v33, v32, vcc
	ds_write_b16 v48, v32 offset:2512
	v_cvt_f16_f32_e32 v32, v38
	v_cvt_pk_bf16_f32 v33, v38, s0
	v_cndmask_b32_e32 v32, v33, v32, vcc
	ds_write_b16 v48, v32 offset:2784
	v_cvt_f16_f32_e32 v32, v39
	v_cvt_pk_bf16_f32 v33, v39, s0
	v_cndmask_b32_e32 v32, v33, v32, vcc
	ds_write_b16 v48, v32 offset:3056
	v_cvt_f16_f32_e32 v32, v40
	v_cvt_pk_bf16_f32 v33, v40, s0
	v_cndmask_b32_e32 v32, v33, v32, vcc
	ds_write_b16 v48, v32 offset:4416
	v_cvt_f16_f32_e32 v32, v41
	v_cvt_pk_bf16_f32 v33, v41, s0
	v_cndmask_b32_e32 v32, v33, v32, vcc
	ds_write_b16 v48, v32 offset:4688
	v_cvt_f16_f32_e32 v32, v42
	v_cvt_pk_bf16_f32 v33, v42, s0
	v_cndmask_b32_e32 v32, v33, v32, vcc
	ds_write_b16 v48, v32 offset:4960
	v_cvt_f16_f32_e32 v32, v43
	v_cvt_pk_bf16_f32 v33, v43, s0
	v_cndmask_b32_e32 v32, v33, v32, vcc
	ds_write_b16 v48, v32 offset:5232
	v_cvt_f16_f32_e32 v32, v44
	v_cvt_pk_bf16_f32 v33, v44, s0
	v_cndmask_b32_e32 v32, v33, v32, vcc
	ds_write_b16 v48, v32 offset:6592
	v_cvt_f16_f32_e32 v32, v45
	v_cvt_pk_bf16_f32 v33, v45, s0
	v_cndmask_b32_e32 v32, v33, v32, vcc
	ds_write_b16 v48, v32 offset:6864
	v_cvt_f16_f32_e32 v32, v46
	v_cvt_pk_bf16_f32 v33, v46, s0
	v_cndmask_b32_e32 v32, v33, v32, vcc
	ds_write_b16 v48, v32 offset:7136
	v_cvt_f16_f32_e32 v32, v47
	v_cvt_pk_bf16_f32 v33, v47, s0
	v_cndmask_b32_e32 v32, v33, v32, vcc
	ds_write_b16 v48, v32 offset:7408
	v_cvt_f16_f32_e32 v32, v16
	v_cvt_pk_bf16_f32 v16, v16, s0
	v_cndmask_b32_e64 v16, v16, v32, s[40:41]
	ds_write_b16 v48, v16 offset:8704
	v_cvt_f16_f32_e32 v16, v17
	v_cvt_pk_bf16_f32 v17, v17, s0
	v_cndmask_b32_e64 v16, v17, v16, s[40:41]
	ds_write_b16 v48, v16 offset:8976
	v_cvt_f16_f32_e32 v16, v18
	v_cvt_pk_bf16_f32 v17, v18, s0
	v_cndmask_b32_e64 v16, v17, v16, s[40:41]
	ds_write_b16 v48, v16 offset:9248
	v_cvt_f16_f32_e32 v16, v19
	v_cvt_pk_bf16_f32 v17, v19, s0
	v_cndmask_b32_e64 v16, v17, v16, s[40:41]
	ds_write_b16 v48, v16 offset:9520
	v_cvt_f16_f32_e32 v16, v20
	v_cvt_pk_bf16_f32 v17, v20, s0
	v_cndmask_b32_e64 v16, v17, v16, s[40:41]
	ds_write_b16 v48, v16 offset:10880
	v_cvt_f16_f32_e32 v16, v21
	v_cvt_pk_bf16_f32 v17, v21, s0
	v_cndmask_b32_e64 v16, v17, v16, s[40:41]
	ds_write_b16 v48, v16 offset:11152
	v_cvt_f16_f32_e32 v16, v22
	v_cvt_pk_bf16_f32 v17, v22, s0
	v_cndmask_b32_e64 v16, v17, v16, s[40:41]
	ds_write_b16 v48, v16 offset:11424
	v_cvt_f16_f32_e32 v16, v23
	v_cvt_pk_bf16_f32 v17, v23, s0
	v_cndmask_b32_e64 v16, v17, v16, s[40:41]
	ds_write_b16 v48, v16 offset:11696
	v_cvt_f16_f32_e32 v16, v24
	v_cvt_pk_bf16_f32 v17, v24, s0
	v_cndmask_b32_e64 v16, v17, v16, s[40:41]
	ds_write_b16 v48, v16 offset:13056
	v_cvt_f16_f32_e32 v16, v25
	v_cvt_pk_bf16_f32 v17, v25, s0
	v_cndmask_b32_e64 v16, v17, v16, s[40:41]
	ds_write_b16 v48, v16 offset:13328
	v_cvt_f16_f32_e32 v16, v26
	v_cvt_pk_bf16_f32 v17, v26, s0
; DI int ltid() { int t = threadIdx.x; asm volatile("" : "+v"(t)); return t; }
; DI void store_tile16(const unsigned short* Cs, unsigned short* dst, int ldd) {
;   const int tid = ltid();
; #pragma unroll
;   for (int i = 0; i < 8; ++i) {
;     const int idx = tid + 256 * i;
;     const int row = idx >> 4, c8 = (idx & 15) * 8;
;     *(u32x4*)(dst + (size_t)row * ldd + c8) = *(const u32x4*)(Cs + row * 136 + c8);
;   }
; }
; DI void phase_gemm_in(const Params& P, int layer, char* smem) {
;     ...
;   for (int t0 = blockIdx.x; t0 < NT * MT; t0 += gridDim.x) {
;     const int tl = xcd_tile(t0, NT * MT) - (t0 & 7) * ((NT * MT) >> 3);
;     const int m0 = ((t0 & 3) * 64 + tl / 11) * 128, n0 = (((t0 & 7) >> 2) * 11 + tl % 11) * 128;
;     f32x16 acc[2][2];
;     gemm_tile(smem, 16, hn, 1024, m0, wt, 1024, n0, acc);
;     unsigned short* Cs = (unsigned short*)smem;
;     epi_foreach(acc, [&](int row, int col, float v) __attribute__((always_inline)) {
;       const int c = n0 + col;
;       Cs[row * 136 + col] = (c >= C_QI && c < C_CQ) ? f2h(v) : f2bf(v);
;     });
;     __syncthreads();
;     store_tile16(Cs, Z + (size_t)m0 * ZLD + n0, ZLD);
;     __syncthreads();
	v_cndmask_b32_e64 v16, v17, v16, s[40:41]
	ds_write_b16 v48, v16 offset:13600
	v_cvt_f16_f32_e32 v16, v27
	v_cvt_pk_bf16_f32 v17, v27, s0
	v_cndmask_b32_e64 v16, v17, v16, s[40:41]
	ds_write_b16 v48, v16 offset:13872
	v_cvt_f16_f32_e32 v16, v28
	v_cvt_pk_bf16_f32 v17, v28, s0
	v_cndmask_b32_e64 v16, v17, v16, s[40:41]
	ds_write_b16 v48, v16 offset:15232
	v_cvt_f16_f32_e32 v16, v29
	v_cvt_pk_bf16_f32 v17, v29, s0
	v_cndmask_b32_e64 v16, v17, v16, s[40:41]
	ds_write_b16 v48, v16 offset:15504
	v_cvt_f16_f32_e32 v16, v30
	v_cvt_pk_bf16_f32 v17, v30, s0
	v_cndmask_b32_e64 v16, v17, v16, s[40:41]
	ds_write_b16 v48, v16 offset:15776
	v_cvt_f16_f32_e32 v16, v31
	v_cvt_pk_bf16_f32 v17, v31, s0
	v_cndmask_b32_e64 v16, v17, v16, s[40:41]
	ds_write_b16 v48, v16 offset:16048
	v_cvt_f16_f32_e32 v16, v0
	v_cvt_pk_bf16_f32 v0, v0, s0
	v_cndmask_b32_e32 v0, v0, v16, vcc
	ds_write_b16 v48, v0 offset:8768
	v_cvt_f16_f32_e32 v0, v1
	v_cvt_pk_bf16_f32 v1, v1, s0
	v_cndmask_b32_e32 v0, v1, v0, vcc
	ds_write_b16 v48, v0 offset:9040
	v_cvt_f16_f32_e32 v0, v2
	v_cvt_pk_bf16_f32 v1, v2, s0
	v_cndmask_b32_e32 v0, v1, v0, vcc
	ds_write_b16 v48, v0 offset:9312
	v_cvt_f16_f32_e32 v0, v3
	v_cvt_pk_bf16_f32 v1, v3, s0
	v_cndmask_b32_e32 v0, v1, v0, vcc
	ds_write_b16 v48, v0 offset:9584
	v_cvt_f16_f32_e32 v0, v4
	v_cvt_pk_bf16_f32 v1, v4, s0
	v_cndmask_b32_e32 v0, v1, v0, vcc
	ds_write_b16 v48, v0 offset:10944
	v_cvt_f16_f32_e32 v0, v5
	v_cvt_pk_bf16_f32 v1, v5, s0
	v_cndmask_b32_e32 v0, v1, v0, vcc
	ds_write_b16 v48, v0 offset:11216
	v_cvt_f16_f32_e32 v0, v6
	v_cvt_pk_bf16_f32 v1, v6, s0
	v_cndmask_b32_e32 v0, v1, v0, vcc
	ds_write_b16 v48, v0 offset:11488
	v_cvt_f16_f32_e32 v0, v7
	v_cvt_pk_bf16_f32 v1, v7, s0
	v_cndmask_b32_e32 v0, v1, v0, vcc
	ds_write_b16 v48, v0 offset:11760
	v_cvt_f16_f32_e32 v0, v8
	v_cvt_pk_bf16_f32 v1, v8, s0
	v_cndmask_b32_e32 v0, v1, v0, vcc
	ds_write_b16 v48, v0 offset:13120
	v_cvt_f16_f32_e32 v0, v9
	v_cvt_pk_bf16_f32 v1, v9, s0
	v_cndmask_b32_e32 v0, v1, v0, vcc
	ds_write_b16 v48, v0 offset:13392
	v_cvt_f16_f32_e32 v0, v10
	v_cvt_pk_bf16_f32 v1, v10, s0
	v_cndmask_b32_e32 v0, v1, v0, vcc
	ds_write_b16 v48, v0 offset:13664
	v_cvt_f16_f32_e32 v0, v11
	v_cvt_pk_bf16_f32 v1, v11, s0
	v_cndmask_b32_e32 v0, v1, v0, vcc
	ds_write_b16 v48, v0 offset:13936
	v_cvt_f16_f32_e32 v0, v12
	v_cvt_pk_bf16_f32 v1, v12, s0
	v_cndmask_b32_e32 v0, v1, v0, vcc
	ds_write_b16 v48, v0 offset:15296
	v_cvt_f16_f32_e32 v0, v13
	v_cvt_pk_bf16_f32 v1, v13, s0
	v_cndmask_b32_e32 v0, v1, v0, vcc
	ds_write_b16 v48, v0 offset:15568
	v_cvt_f16_f32_e32 v0, v14
	v_cvt_pk_bf16_f32 v1, v14, s0
	v_cndmask_b32_e32 v0, v1, v0, vcc
	ds_write_b16 v48, v0 offset:15840
	v_cvt_f16_f32_e32 v0, v15
	v_cvt_pk_bf16_f32 v1, v15, s0
	v_cndmask_b32_e32 v0, v1, v0, vcc
	ds_write_b16 v48, v0 offset:16112
	s_mul_i32 s15, s15, 0xb0000
	s_mul_hi_i32 s0, s0, 0x1600
	s_add_u32 s15, s86, s15
	s_addc_u32 s16, s87, s0
	s_lshl_b64 s[0:1], s[10:11], 1
	v_mov_b32_e32 v8, v161
	s_waitcnt lgkmcnt(0)
	s_barrier
	s_add_u32 s0, s15, s0
	s_addc_u32 s1, s16, s1
	v_lshlrev_b32_e32 v0, 4, v8
	v_and_b32_e32 v136, 0xf0, v0
	v_ashrrev_i32_e32 v6, 4, v8
	v_lshl_add_u64 v[4:5], s[0:1], 0, v[136:137]
	v_mad_u64_u32 v[0:1], s[0:1], v6, s97, v[136:137]
	ds_read_b128 v[0:3], v0
	v_mad_i64_i32 v[6:7], s[0:1], v6, s33, v[4:5]
	s_add_i32 s14, s14, s70
	s_add_i32 s13, s13, s3
	s_waitcnt lgkmcnt(0)
	global_store_dwordx4 v[6:7], v[0:3], off
	s_cmpk_gt_i32 s14, 0x15ff
	s_nop 0
	v_add_u32_e32 v0, 0x100, v8
	v_ashrrev_i32_e32 v6, 4, v0
	v_mad_u64_u32 v[0:1], s[0:1], v6, s97, v[136:137]
	ds_read_b128 v[0:3], v0
	v_mad_i64_i32 v[6:7], s[0:1], v6, s33, v[4:5]
	s_waitcnt lgkmcnt(0)
	global_store_dwordx4 v[6:7], v[0:3], off
	s_nop 1
	v_add_u32_e32 v0, 0x200, v8
	v_ashrrev_i32_e32 v6, 4, v0
	v_mad_u64_u32 v[0:1], s[0:1], v6, s97, v[136:137]
	ds_read_b128 v[0:3], v0
	v_mad_i64_i32 v[6:7], s[0:1], v6, s33, v[4:5]
	s_waitcnt lgkmcnt(0)
	global_store_dwordx4 v[6:7], v[0:3], off
	s_nop 1
	v_add_u32_e32 v0, 0x300, v8
	v_ashrrev_i32_e32 v6, 4, v0
	v_mad_u64_u32 v[0:1], s[0:1], v6, s97, v[136:137]
	ds_read_b128 v[0:3], v0
	v_mad_i64_i32 v[6:7], s[0:1], v6, s33, v[4:5]
	s_waitcnt lgkmcnt(0)
	global_store_dwordx4 v[6:7], v[0:3], off
	s_nop 1
	v_add_u32_e32 v0, 0x400, v8
	v_ashrrev_i32_e32 v6, 4, v0
	v_mad_u64_u32 v[0:1], s[0:1], v6, s97, v[136:137]
	ds_read_b128 v[0:3], v0
	v_mad_i64_i32 v[6:7], s[0:1], v6, s33, v[4:5]
	s_waitcnt lgkmcnt(0)
	global_store_dwordx4 v[6:7], v[0:3], off
	s_nop 1
	v_add_u32_e32 v0, 0x500, v8
	v_ashrrev_i32_e32 v6, 4, v0
	v_mad_u64_u32 v[0:1], s[0:1], v6, s97, v[136:137]
	ds_read_b128 v[0:3], v0
	v_mad_i64_i32 v[6:7], s[0:1], v6, s33, v[4:5]
	s_waitcnt lgkmcnt(0)
	global_store_dwordx4 v[6:7], v[0:3], off
	s_nop 1
	v_add_u32_e32 v0, 0x600, v8
	v_ashrrev_i32_e32 v6, 4, v0
	v_mad_u64_u32 v[0:1], s[0:1], v6, s97, v[136:137]
	ds_read_b128 v[0:3], v0
	v_mad_i64_i32 v[6:7], s[0:1], v6, s33, v[4:5]
	s_waitcnt lgkmcnt(0)
	global_store_dwordx4 v[6:7], v[0:3], off
	s_nop 1
	v_add_u32_e32 v0, 0x700, v8
	v_ashrrev_i32_e32 v6, 4, v0
	v_mad_u64_u32 v[0:1], s[0:1], v6, s97, v[136:137]
	ds_read_b128 v[0:3], v0
	v_mad_i64_i32 v[4:5], s[0:1], v6, s33, v[4:5]
	s_waitcnt lgkmcnt(0)
	global_store_dwordx4 v[4:5], v[0:3], off
	s_barrier
	s_cbranch_scc0 .LBB0_436
